# GEMM K-loops: priority raise issued before the segment barrier instead of after, redundant post-barrier lgkmcnt wait dropped, priority drop moved behind the closing barrier (3 issue slots off the MFMA
# speedup vs baseline: 1.0110x; 1.0110x over previous
;     __device__ __forceinline__ size_t a_extra(const Unit& u) const { return (size_t)(u.pn >> 1) * ((size_t)T * 512 * 2); }
;     __device__ __forceinline__ size_t a_extra(const Unit& u) const { return (size_t)(u.pn >> 1) * 512 * 2; }
;     __device__ __forceinline__ size_t b_extra(const Unit& u) const { return (size_t)(u.pn >> 1) * 512 * 2 - (size_t)(u.pn & ~1) * ((size_t)256 * D * 2); }
; #define PG8_STAGE(bufoff, gbase, voff) do { _Pragma("unroll") for (int _i = 0; _i < 2; ++_i) \
;         __builtin_amdgcn_global_load_lds((const unsigned*)((const char*)(gbase) + (voff)[_i]), (PG8_LAS unsigned*)(lds + (bufoff) + ldsw + _i * 8192), 16, 0, 0); } while (0)
; #define PG8_LDA(dst, b, h) do { _Pragma("unroll") for (int m = 0; m < 4; ++m) _Pragma("unroll") for (int k = 0; k < 2; ++k) dst[m][k] = *(const PG8_LAS bf16x8*)(lds + PG8_SA(b, h) + aoff + m * 2048 + k * 1024); } while (0)
; #define PG8_WAIT_V(n) asm volatile("s_waitcnt vmcnt(" #n ")" ::: "memory")
; #define PG8_WAIT_L(n) asm volatile("s_waitcnt lgkmcnt(" #n ")" ::: "memory")
; template <class Epi, class Sched, bool ALIGN_EPI = true, bool SP2 = true, bool GS = false>
; __device__ __forceinline__ void gemm_phase(PG8_LAS unsigned char* lds, const Gemm g, const Sched& S, const Epi& E, const float* gs_ss = nullptr) {
;     ...
;         const char* nA = has_next ? (const char*)g.A + S.a_extra(nxt) + (size_t)nxt.pm * tstep : cA; const char* nB = has_next ? (const char*)g.Bt + S.b_extra(nxt) + (size_t)nxt.pn * tstep : cB;
;         for (int t = 0; t < nt; t += 2) {
;             const bool last = (t == nt - 2);
;             const char* a1 = cA + (size_t)(t + 1) * kstep;
;             const char* a2 = last ? nA : cA + (size_t)(t + 2) * kstep; const char* b2 = last ? nB : cB + (size_t)(t + 2) * kstep;
;             const char* a3 = a2 + kstep; const char* b3 = b2 + kstep;
;             if constexpr (SP2) {
;             PG8_LDB(B0, 0, 0); PG8_LDB(B1, 0, 1); PG8_SCHED; PG8_LDA(At, 0, 0); PG8_STAGE(PG8_SA(1, 1), a1 + hstep, voffA);
;             PG8_WAIT_V(8); PG8_WAIT_L(0); PG8_BAR; PG8_MMA(0, 0, At, B0); PG8_MMA(0, 1, At, B1); PG8_BAR; PG8_SCHED;
;             PG8_LDA(At, 0, 1); PG8_STAGE(PG8_SB(0, 0), b2, voffB); PG8_STAGE(PG8_SB(0, 1), b2 + hstep, voffB); PG8_STAGE(PG8_SA(0, 0), a2, voffA);
;             PG8_WAIT_V(8); PG8_WAIT_L(0); PG8_BAR; PG8_MMA(1, 0, At, B0); PG8_MMA(1, 1, At, B1); PG8_BAR; PG8_SCHED;
.LBB0_151:
	s_add_u32 s2, s40, 0xfff80080
	s_addc_u32 s3, s41, -1
	s_add_i32 s67, 0, 0x10000
	s_cmp_eq_u32 s65, 28
	s_cselect_b32 s21, s13, s3
	s_cselect_b32 s20, s53, s2
	v_add_u32_e32 v0, s67, v167
	s_cselect_b32 s3, s51, s43
	s_cselect_b32 s2, s64, s42
	s_add_i32 s69, 0, 0x14000
	ds_read_b128 v[146:149], v0
	ds_read_b128 v[150:153], v0 offset:1024
	ds_read_b128 v[154:157], v0 offset:2048
	ds_read_b128 v[158:161], v0 offset:3072
	v_add_u32_e32 v0, s69, v167
	ds_read_b128 v[162:165], v0
	ds_read_b128 v[172:175], v0 offset:1024
	ds_read_b128 v[180:183], v0 offset:2048
	ds_read_b128 v[184:187], v0 offset:3072
	v_lshl_add_u64 v[176:177], s[40:41], 0, v[142:143]
	s_add_i32 m0, s24, 0xc000
	ds_read_b128 v[188:191], v171
	ds_read_b128 v[192:195], v171 offset:1024
	ds_read_b128 v[196:199], v171 offset:2048
	ds_read_b128 v[200:203], v171 offset:3072
	ds_read_b128 v[204:207], v171 offset:4096
	ds_read_b128 v[208:211], v171 offset:5120
	ds_read_b128 v[212:215], v171 offset:6144
	ds_read_b128 v[216:219], v171 offset:7168
	global_load_lds_dwordx4 v[176:177], off
	v_lshl_add_u64 v[176:177], s[40:41], 0, v[144:145]
	s_add_i32 m0, s24, 0xe000
	s_nop 0
	global_load_lds_dwordx4 v[176:177], off
	s_waitcnt vmcnt(8)
	s_waitcnt lgkmcnt(0)
	s_setprio 1
	s_barrier
	v_mfma_f32_16x16x32_bf16 v[126:129], v[146:149], v[188:191], v[126:129]
	v_mfma_f32_16x16x32_bf16 v[122:125], v[154:157], v[188:191], v[122:125]
	v_mfma_f32_16x16x32_bf16 v[110:113], v[146:149], v[196:199], v[110:113]
	v_mfma_f32_16x16x32_bf16 v[106:109], v[154:157], v[196:199], v[106:109]
	v_mfma_f32_16x16x32_bf16 v[94:97], v[146:149], v[204:207], v[94:97]
	v_mfma_f32_16x16x32_bf16 v[90:93], v[154:157], v[204:207], v[90:93]
	v_mfma_f32_16x16x32_bf16 v[78:81], v[146:149], v[212:215], v[78:81]
	v_mfma_f32_16x16x32_bf16 v[74:77], v[154:157], v[212:215], v[74:77]
	v_mfma_f32_16x16x32_bf16 v[126:129], v[150:153], v[192:195], v[126:129]
	v_mfma_f32_16x16x32_bf16 v[122:125], v[158:161], v[192:195], v[122:125]
	v_mfma_f32_16x16x32_bf16 v[110:113], v[150:153], v[200:203], v[110:113]
	v_mfma_f32_16x16x32_bf16 v[106:109], v[158:161], v[200:203], v[106:109]
	v_mfma_f32_16x16x32_bf16 v[94:97], v[150:153], v[208:211], v[94:97]
	v_mfma_f32_16x16x32_bf16 v[90:93], v[158:161], v[208:211], v[90:93]
	v_mfma_f32_16x16x32_bf16 v[78:81], v[150:153], v[216:219], v[78:81]
	v_mfma_f32_16x16x32_bf16 v[74:77], v[158:161], v[216:219], v[74:77]
	s_setprio 0
	s_setprio 1
	v_mfma_f32_16x16x32_bf16 v[118:121], v[162:165], v[188:191], v[118:121]
	v_mfma_f32_16x16x32_bf16 v[114:117], v[180:183], v[188:191], v[114:117]
	v_mfma_f32_16x16x32_bf16 v[102:105], v[162:165], v[196:199], v[102:105]
	v_mfma_f32_16x16x32_bf16 v[98:101], v[180:183], v[196:199], v[98:101]
	v_mfma_f32_16x16x32_bf16 v[86:89], v[162:165], v[204:207], v[86:89]
	v_mfma_f32_16x16x32_bf16 v[82:85], v[180:183], v[204:207], v[82:85]
	v_mfma_f32_16x16x32_bf16 v[70:73], v[162:165], v[212:215], v[70:73]
	v_mfma_f32_16x16x32_bf16 v[66:69], v[180:183], v[212:215], v[66:69]
	v_mfma_f32_16x16x32_bf16 v[118:121], v[172:175], v[192:195], v[118:121]
	v_mfma_f32_16x16x32_bf16 v[114:117], v[184:187], v[192:195], v[114:117]
	v_mfma_f32_16x16x32_bf16 v[102:105], v[172:175], v[200:203], v[102:105]
	v_mfma_f32_16x16x32_bf16 v[98:101], v[184:187], v[200:203], v[98:101]
	v_mfma_f32_16x16x32_bf16 v[86:89], v[172:175], v[208:211], v[86:89]
	v_mfma_f32_16x16x32_bf16 v[82:85], v[184:187], v[208:211], v[82:85]
	v_mfma_f32_16x16x32_bf16 v[70:73], v[172:175], v[216:219], v[70:73]
	v_mfma_f32_16x16x32_bf16 v[66:69], v[184:187], v[216:219], v[66:69]
	s_barrier
	s_setprio 0
	s_add_i32 s67, s67, s23
	v_lshl_add_u64 v[176:177], s[2:3], 0, v[132:133]
	s_mov_b32 m0, s67
	ds_read_b128 v[188:191], v171 offset:16384
	ds_read_b128 v[192:195], v171 offset:17408
	ds_read_b128 v[196:199], v171 offset:18432
	ds_read_b128 v[200:203], v171 offset:19456
	ds_read_b128 v[204:207], v171 offset:20480
	ds_read_b128 v[208:211], v171 offset:21504
	ds_read_b128 v[212:215], v171 offset:22528
	ds_read_b128 v[216:219], v171 offset:23552
	global_load_lds_dwordx4 v[176:177], off
	s_add_i32 m0, s67, 0x2000
	s_add_u32 s70, s2, 0x80000
	v_lshl_add_u64 v[220:221], s[2:3], 0, v[136:137]
	s_addc_u32 s71, s3, 0
	s_add_i32 s67, s69, s23
	global_load_lds_dwordx4 v[220:221], off
	v_lshl_add_u64 v[236:237], s[70:71], 0, v[132:133]
	s_mov_b32 m0, s67
	v_lshl_add_u64 v[238:239], s[20:21], 0, v[134:135]
	global_load_lds_dwordx4 v[236:237], off
	v_lshl_add_u64 v[236:237], s[70:71], 0, v[136:137]
	s_add_i32 m0, s67, 0x2000
	s_nop 0
	global_load_lds_dwordx4 v[236:237], off
	v_lshl_add_u64 v[236:237], s[20:21], 0, v[130:131]
	s_mov_b32 m0, s24
	s_nop 0
	global_load_lds_dwordx4 v[236:237], off
	s_mov_b32 m0, s25
	s_nop 0
	global_load_lds_dwordx4 v[238:239], off
	s_waitcnt vmcnt(8)
	s_waitcnt lgkmcnt(0)
	s_setprio 1
	s_barrier
; #define PG8_STAGE(bufoff, gbase, voff) do { _Pragma("unroll") for (int _i = 0; _i < 2; ++_i) \
;         __builtin_amdgcn_global_load_lds((const unsigned*)((const char*)(gbase) + (voff)[_i]), (PG8_LAS unsigned*)(lds + (bufoff) + ldsw + _i * 8192), 16, 0, 0); } while (0)
; #define PG8_LDA(dst, b, h) do { _Pragma("unroll") for (int m = 0; m < 4; ++m) _Pragma("unroll") for (int k = 0; k < 2; ++k) dst[m][k] = *(const PG8_LAS bf16x8*)(lds + PG8_SA(b, h) + aoff + m * 2048 + k * 1024); } while (0)
; #define PG8_LDB(dst, b, h) do { _Pragma("unroll") for (int n = 0; n < 2; ++n) _Pragma("unroll") for (int k = 0; k < 2; ++k) dst[n][k] = *(const PG8_LAS bf16x8*)(lds + PG8_SB(b, h) + boff + n * 2048 + k * 1024); } while (0)
; #define PG8_MMA(ai, bj, At, Bt) do { __builtin_amdgcn_s_setprio(1); _Pragma("unroll") for (int m = 0; m < 4; ++m) _Pragma("unroll") for (int n = 0; n < 2; ++n) _Pragma("unroll") for (int k = 0; k < 2; ++k) \
;         acc[ai][bj][m][n] = __builtin_amdgcn_mfma_f32_16x16x32_bf16(Bt[n][k], At[m][k], acc[ai][bj][m][n], 0, 0, 0); __builtin_amdgcn_s_setprio(0); } while (0)
; #define PG8_WAIT_V(n) asm volatile("s_waitcnt vmcnt(" #n ")" ::: "memory")
; #define PG8_WAIT_L(n) asm volatile("s_waitcnt lgkmcnt(" #n ")" ::: "memory")
; #define PG8_BAR __builtin_amdgcn_s_barrier()
; #define PG8_SCHED __builtin_amdgcn_sched_barrier(0)
; template <class Epi, class Sched, bool ALIGN_EPI = true, bool SP2 = true, bool GS = false>
; __device__ __forceinline__ void gemm_phase(PG8_LAS unsigned char* lds, const Gemm g, const Sched& S, const Epi& E, const float* gs_ss = nullptr) {
;     ...
;             PG8_WAIT_V(8); PG8_WAIT_L(0); PG8_BAR; PG8_MMA(1, 0, At, B0); PG8_MMA(1, 1, At, B1); PG8_BAR; PG8_SCHED;
;             PG8_LDB(B0, 1, 0); PG8_LDB(B1, 1, 1); PG8_SCHED; PG8_LDA(At, 1, 0); PG8_STAGE(PG8_SA(0, 1), a2 + hstep, voffA);
;             PG8_WAIT_V(8); PG8_WAIT_L(0); PG8_BAR; PG8_MMA(0, 0, At, B0); PG8_MMA(0, 1, At, B1); PG8_BAR; PG8_SCHED;
	v_mfma_f32_16x16x32_bf16 v[62:65], v[146:149], v[188:191], v[62:65]
	v_mfma_f32_16x16x32_bf16 v[58:61], v[154:157], v[188:191], v[58:61]
	v_mfma_f32_16x16x32_bf16 v[46:49], v[146:149], v[196:199], v[46:49]
	v_mfma_f32_16x16x32_bf16 v[42:45], v[154:157], v[196:199], v[42:45]
	v_mfma_f32_16x16x32_bf16 v[30:33], v[146:149], v[204:207], v[30:33]
	v_mfma_f32_16x16x32_bf16 v[26:29], v[154:157], v[204:207], v[26:29]
	v_mfma_f32_16x16x32_bf16 v[14:17], v[146:149], v[212:215], v[14:17]
	v_mfma_f32_16x16x32_bf16 v[10:13], v[154:157], v[212:215], v[10:13]
	v_mfma_f32_16x16x32_bf16 v[62:65], v[150:153], v[192:195], v[62:65]
	v_mfma_f32_16x16x32_bf16 v[58:61], v[158:161], v[192:195], v[58:61]
	v_mfma_f32_16x16x32_bf16 v[46:49], v[150:153], v[200:203], v[46:49]
	v_mfma_f32_16x16x32_bf16 v[42:45], v[158:161], v[200:203], v[42:45]
	v_mfma_f32_16x16x32_bf16 v[30:33], v[150:153], v[208:211], v[30:33]
	v_mfma_f32_16x16x32_bf16 v[26:29], v[158:161], v[208:211], v[26:29]
	v_mfma_f32_16x16x32_bf16 v[14:17], v[150:153], v[216:219], v[14:17]
	v_mfma_f32_16x16x32_bf16 v[10:13], v[158:161], v[216:219], v[10:13]
	s_setprio 0
	s_setprio 1
	v_mfma_f32_16x16x32_bf16 v[54:57], v[162:165], v[188:191], v[54:57]
	v_mfma_f32_16x16x32_bf16 v[50:53], v[180:183], v[188:191], v[50:53]
	v_mfma_f32_16x16x32_bf16 v[38:41], v[162:165], v[196:199], v[38:41]
	v_mfma_f32_16x16x32_bf16 v[34:37], v[180:183], v[196:199], v[34:37]
	v_mfma_f32_16x16x32_bf16 v[22:25], v[162:165], v[204:207], v[22:25]
	v_mfma_f32_16x16x32_bf16 v[18:21], v[180:183], v[204:207], v[18:21]
	v_mfma_f32_16x16x32_bf16 v[6:9], v[162:165], v[212:215], v[6:9]
	v_mfma_f32_16x16x32_bf16 v[2:5], v[180:183], v[212:215], v[2:5]
	v_mfma_f32_16x16x32_bf16 v[54:57], v[172:175], v[192:195], v[54:57]
	v_mfma_f32_16x16x32_bf16 v[50:53], v[184:187], v[192:195], v[50:53]
	v_mfma_f32_16x16x32_bf16 v[38:41], v[172:175], v[200:203], v[38:41]
	v_mfma_f32_16x16x32_bf16 v[34:37], v[184:187], v[200:203], v[34:37]
	v_mfma_f32_16x16x32_bf16 v[22:25], v[172:175], v[208:211], v[22:25]
	v_mfma_f32_16x16x32_bf16 v[18:21], v[184:187], v[208:211], v[18:21]
	v_mfma_f32_16x16x32_bf16 v[6:9], v[172:175], v[216:219], v[6:9]
	v_mfma_f32_16x16x32_bf16 v[2:5], v[184:187], v[216:219], v[2:5]
	s_barrier
	s_setprio 0
	s_add_i32 s67, 0, 0x18000
	v_add_u32_e32 v0, s67, v167
	s_add_i32 s69, 0, 0x1c000
	ds_read_b128 v[146:149], v0
	ds_read_b128 v[150:153], v0 offset:1024
	ds_read_b128 v[154:157], v0 offset:2048
	ds_read_b128 v[158:161], v0 offset:3072
	v_add_u32_e32 v0, s69, v167
	ds_read_b128 v[162:165], v0
	ds_read_b128 v[172:175], v0 offset:1024
	ds_read_b128 v[180:183], v0 offset:2048
	ds_read_b128 v[184:187], v0 offset:3072
	s_add_u32 s20, s20, 0x80000
	s_addc_u32 s21, s21, 0
	s_mov_b32 m0, s30
	v_lshl_add_u64 v[240:241], s[20:21], 0, v[130:131]
	ds_read_b128 v[188:191], v171 offset:32768
	ds_read_b128 v[192:195], v171 offset:33792
	ds_read_b128 v[196:199], v171 offset:34816
	ds_read_b128 v[200:203], v171 offset:35840
	ds_read_b128 v[204:207], v171 offset:36864
	ds_read_b128 v[208:211], v171 offset:37888
	ds_read_b128 v[212:215], v171 offset:38912
	ds_read_b128 v[216:219], v171 offset:39936
	global_load_lds_dwordx4 v[240:241], off
	v_lshl_add_u64 v[240:241], s[20:21], 0, v[134:135]
	s_mov_b32 m0, s35
	s_nop 0
	global_load_lds_dwordx4 v[240:241], off
	s_waitcnt vmcnt(8)
	s_waitcnt lgkmcnt(0)
	s_setprio 1
	s_barrier
	v_mfma_f32_16x16x32_bf16 v[126:129], v[146:149], v[188:191], v[126:129]
	v_mfma_f32_16x16x32_bf16 v[122:125], v[154:157], v[188:191], v[122:125]
	v_mfma_f32_16x16x32_bf16 v[110:113], v[146:149], v[196:199], v[110:113]
	v_mfma_f32_16x16x32_bf16 v[106:109], v[154:157], v[196:199], v[106:109]
	v_mfma_f32_16x16x32_bf16 v[94:97], v[146:149], v[204:207], v[94:97]
	v_mfma_f32_16x16x32_bf16 v[90:93], v[154:157], v[204:207], v[90:93]
	v_mfma_f32_16x16x32_bf16 v[78:81], v[146:149], v[212:215], v[78:81]
	v_mfma_f32_16x16x32_bf16 v[74:77], v[154:157], v[212:215], v[74:77]
	v_mfma_f32_16x16x32_bf16 v[126:129], v[150:153], v[192:195], v[126:129]
	v_mfma_f32_16x16x32_bf16 v[122:125], v[158:161], v[192:195], v[122:125]
	v_mfma_f32_16x16x32_bf16 v[110:113], v[150:153], v[200:203], v[110:113]
	v_mfma_f32_16x16x32_bf16 v[106:109], v[158:161], v[200:203], v[106:109]
	v_mfma_f32_16x16x32_bf16 v[94:97], v[150:153], v[208:211], v[94:97]
	v_mfma_f32_16x16x32_bf16 v[90:93], v[158:161], v[208:211], v[90:93]
	v_mfma_f32_16x16x32_bf16 v[78:81], v[150:153], v[216:219], v[78:81]
	v_mfma_f32_16x16x32_bf16 v[74:77], v[158:161], v[216:219], v[74:77]
	s_setprio 0
	s_setprio 1
	v_mfma_f32_16x16x32_bf16 v[118:121], v[162:165], v[188:191], v[118:121]
	v_mfma_f32_16x16x32_bf16 v[114:117], v[180:183], v[188:191], v[114:117]
	v_mfma_f32_16x16x32_bf16 v[102:105], v[162:165], v[196:199], v[102:105]
	v_mfma_f32_16x16x32_bf16 v[98:101], v[180:183], v[196:199], v[98:101]
	v_mfma_f32_16x16x32_bf16 v[86:89], v[162:165], v[204:207], v[86:89]
	v_mfma_f32_16x16x32_bf16 v[82:85], v[180:183], v[204:207], v[82:85]
	v_mfma_f32_16x16x32_bf16 v[70:73], v[162:165], v[212:215], v[70:73]
	v_mfma_f32_16x16x32_bf16 v[66:69], v[180:183], v[212:215], v[66:69]
	v_mfma_f32_16x16x32_bf16 v[118:121], v[172:175], v[192:195], v[118:121]
	v_mfma_f32_16x16x32_bf16 v[114:117], v[184:187], v[192:195], v[114:117]
	v_mfma_f32_16x16x32_bf16 v[102:105], v[172:175], v[200:203], v[102:105]
	v_mfma_f32_16x16x32_bf16 v[98:101], v[184:187], v[200:203], v[98:101]
	v_mfma_f32_16x16x32_bf16 v[86:89], v[172:175], v[208:211], v[86:89]
	v_mfma_f32_16x16x32_bf16 v[82:85], v[184:187], v[208:211], v[82:85]
	v_mfma_f32_16x16x32_bf16 v[70:73], v[172:175], v[216:219], v[70:73]
	v_mfma_f32_16x16x32_bf16 v[66:69], v[184:187], v[216:219], v[66:69]
	s_barrier
; #define PG8_STAGE(bufoff, gbase, voff) do { _Pragma("unroll") for (int _i = 0; _i < 2; ++_i) \
;         __builtin_amdgcn_global_load_lds((const unsigned*)((const char*)(gbase) + (voff)[_i]), (PG8_LAS unsigned*)(lds + (bufoff) + ldsw + _i * 8192), 16, 0, 0); } while (0)
; #define PG8_LDA(dst, b, h) do { _Pragma("unroll") for (int m = 0; m < 4; ++m) _Pragma("unroll") for (int k = 0; k < 2; ++k) dst[m][k] = *(const PG8_LAS bf16x8*)(lds + PG8_SA(b, h) + aoff + m * 2048 + k * 1024); } while (0)
; #define PG8_MMA(ai, bj, At, Bt) do { __builtin_amdgcn_s_setprio(1); _Pragma("unroll") for (int m = 0; m < 4; ++m) _Pragma("unroll") for (int n = 0; n < 2; ++n) _Pragma("unroll") for (int k = 0; k < 2; ++k) \
;         acc[ai][bj][m][n] = __builtin_amdgcn_mfma_f32_16x16x32_bf16(Bt[n][k], At[m][k], acc[ai][bj][m][n], 0, 0, 0); __builtin_amdgcn_s_setprio(0); } while (0)
; #define PG8_WAIT_V(n) asm volatile("s_waitcnt vmcnt(" #n ")" ::: "memory")
; #define PG8_WAIT_L(n) asm volatile("s_waitcnt lgkmcnt(" #n ")" ::: "memory")
; #define PG8_BAR __builtin_amdgcn_s_barrier()
; #define PG8_SCHED __builtin_amdgcn_sched_barrier(0)
; template <class Epi, class Sched, bool ALIGN_EPI = true, bool SP2 = true, bool GS = false>
; __device__ __forceinline__ void gemm_phase(PG8_LAS unsigned char* lds, const Gemm g, const Sched& S, const Epi& E, const float* gs_ss = nullptr) {
;     ...
;         for (int t = 0; t < nt; t += 2) {
;             const bool last = (t == nt - 2);
;             const char* a1 = cA + (size_t)(t + 1) * kstep;
;     ...
;             PG8_LDA(At, 1, 1); PG8_STAGE(PG8_SB(1, 0), b3, voffB); PG8_STAGE(PG8_SB(1, 1), b3 + hstep, voffB); PG8_STAGE(PG8_SA(1, 0), a3, voffA);
;             PG8_WAIT_V(8); PG8_WAIT_L(0); PG8_BAR; PG8_MMA(1, 0, At, B0); PG8_MMA(1, 1, At, B1); PG8_BAR; PG8_SCHED;
	s_setprio 0
	s_add_i32 s20, s67, s23
	v_lshl_add_u64 v[176:177], v[176:177], 0, s[26:27]
	s_mov_b32 m0, s20
	ds_read_b128 v[188:191], v171 offset:49152
	ds_read_b128 v[192:195], v171 offset:50176
	ds_read_b128 v[196:199], v171 offset:51200
	ds_read_b128 v[200:203], v171 offset:52224
	ds_read_b128 v[204:207], v171 offset:53248
	ds_read_b128 v[208:211], v171 offset:54272
	ds_read_b128 v[212:215], v171 offset:55296
	ds_read_b128 v[216:219], v171 offset:56320
	global_load_lds_dwordx4 v[176:177], off
	s_add_i32 m0, s20, 0x2000
	s_add_u32 s2, s2, 0x80080
	v_lshl_add_u64 v[176:177], v[220:221], 0, s[26:27]
	s_addc_u32 s3, s3, 0
	s_add_i32 s20, s69, s23
	global_load_lds_dwordx4 v[176:177], off
	v_lshl_add_u64 v[176:177], s[2:3], 0, v[132:133]
	s_mov_b32 m0, s20
	s_nop 0
	global_load_lds_dwordx4 v[176:177], off
	v_lshl_add_u64 v[176:177], s[2:3], 0, v[136:137]
	s_add_i32 m0, s20, 0x2000
	s_nop 0
	global_load_lds_dwordx4 v[176:177], off
	v_lshl_add_u64 v[176:177], v[236:237], 0, s[26:27]
	s_mov_b32 m0, s59
	s_nop 0
	global_load_lds_dwordx4 v[176:177], off
	v_lshl_add_u64 v[176:177], v[238:239], 0, s[26:27]
	s_mov_b32 m0, s60
	s_nop 0
	global_load_lds_dwordx4 v[176:177], off
	s_waitcnt vmcnt(8)
	s_waitcnt lgkmcnt(0)
	s_setprio 1
	s_barrier
	v_mfma_f32_16x16x32_bf16 v[62:65], v[146:149], v[188:191], v[62:65]
	v_mfma_f32_16x16x32_bf16 v[58:61], v[154:157], v[188:191], v[58:61]
	v_mfma_f32_16x16x32_bf16 v[46:49], v[146:149], v[196:199], v[46:49]
	v_mfma_f32_16x16x32_bf16 v[42:45], v[154:157], v[196:199], v[42:45]
	v_mfma_f32_16x16x32_bf16 v[30:33], v[146:149], v[204:207], v[30:33]
	v_mfma_f32_16x16x32_bf16 v[26:29], v[154:157], v[204:207], v[26:29]
	v_mfma_f32_16x16x32_bf16 v[14:17], v[146:149], v[212:215], v[14:17]
	v_mfma_f32_16x16x32_bf16 v[10:13], v[154:157], v[212:215], v[10:13]
	v_mfma_f32_16x16x32_bf16 v[62:65], v[150:153], v[192:195], v[62:65]
	v_mfma_f32_16x16x32_bf16 v[58:61], v[158:161], v[192:195], v[58:61]
	v_mfma_f32_16x16x32_bf16 v[46:49], v[150:153], v[200:203], v[46:49]
	v_mfma_f32_16x16x32_bf16 v[42:45], v[158:161], v[200:203], v[42:45]
	v_mfma_f32_16x16x32_bf16 v[30:33], v[150:153], v[208:211], v[30:33]
	v_mfma_f32_16x16x32_bf16 v[26:29], v[158:161], v[208:211], v[26:29]
	v_mfma_f32_16x16x32_bf16 v[14:17], v[150:153], v[216:219], v[14:17]
	v_mfma_f32_16x16x32_bf16 v[10:13], v[158:161], v[216:219], v[10:13]
	s_setprio 0
	s_setprio 1
	v_mfma_f32_16x16x32_bf16 v[54:57], v[162:165], v[188:191], v[54:57]
	v_mfma_f32_16x16x32_bf16 v[50:53], v[180:183], v[188:191], v[50:53]
	v_mfma_f32_16x16x32_bf16 v[38:41], v[162:165], v[196:199], v[38:41]
	v_mfma_f32_16x16x32_bf16 v[34:37], v[180:183], v[196:199], v[34:37]
	v_mfma_f32_16x16x32_bf16 v[22:25], v[162:165], v[204:207], v[22:25]
	v_mfma_f32_16x16x32_bf16 v[18:21], v[180:183], v[204:207], v[18:21]
	v_mfma_f32_16x16x32_bf16 v[6:9], v[162:165], v[212:215], v[6:9]
	v_mfma_f32_16x16x32_bf16 v[2:5], v[180:183], v[212:215], v[2:5]
	v_mfma_f32_16x16x32_bf16 v[54:57], v[172:175], v[192:195], v[54:57]
	v_mfma_f32_16x16x32_bf16 v[50:53], v[184:187], v[192:195], v[50:53]
	v_mfma_f32_16x16x32_bf16 v[38:41], v[172:175], v[200:203], v[38:41]
	v_mfma_f32_16x16x32_bf16 v[34:37], v[184:187], v[200:203], v[34:37]
	v_mfma_f32_16x16x32_bf16 v[22:25], v[172:175], v[208:211], v[22:25]
	v_mfma_f32_16x16x32_bf16 v[18:21], v[184:187], v[208:211], v[18:21]
	v_mfma_f32_16x16x32_bf16 v[6:9], v[172:175], v[216:219], v[6:9]
	v_mfma_f32_16x16x32_bf16 v[2:5], v[184:187], v[216:219], v[2:5]
	s_barrier
	s_setprio 0
	s_add_i32 s65, s65, 2
	s_add_u32 s40, s40, 0x100
	s_addc_u32 s41, s41, 0
	s_add_u32 s42, s42, 0x100
	s_addc_u32 s43, s43, 0
	s_cmp_gt_u32 s65, 29
	s_cbranch_scc0 .LBB0_151
	s_and_b64 vcc, exec, s[46:47]
	s_cbranch_vccz .LBB0_154
	s_barrier

;     __device__ __forceinline__ size_t a_extra(const Unit& u) const { return (size_t)(u.pn >> 1) * ((size_t)T * 512 * 2); }
;     __device__ __forceinline__ size_t a_extra(const Unit& u) const { return (size_t)(u.pn >> 1) * 512 * 2; }
;     __device__ __forceinline__ size_t b_extra(const Unit& u) const { return (size_t)(u.pn >> 1) * 512 * 2 - (size_t)(u.pn & ~1) * ((size_t)256 * D * 2); }
; #define PG8_STAGE(bufoff, gbase, voff) do { _Pragma("unroll") for (int _i = 0; _i < 2; ++_i) \
;         __builtin_amdgcn_global_load_lds((const unsigned*)((const char*)(gbase) + (voff)[_i]), (PG8_LAS unsigned*)(lds + (bufoff) + ldsw + _i * 8192), 16, 0, 0); } while (0)
; #define PG8_LDA(dst, b, h) do { _Pragma("unroll") for (int m = 0; m < 4; ++m) _Pragma("unroll") for (int k = 0; k < 2; ++k) dst[m][k] = *(const PG8_LAS bf16x8*)(lds + PG8_SA(b, h) + aoff + m * 2048 + k * 1024); } while (0)
; #define PG8_WAIT_V(n) asm volatile("s_waitcnt vmcnt(" #n ")" ::: "memory")
; #define PG8_WAIT_L(n) asm volatile("s_waitcnt lgkmcnt(" #n ")" ::: "memory")
; template <class Epi, class Sched, bool ALIGN_EPI = true, bool SP2 = true, bool GS = false>
; __device__ __forceinline__ void gemm_phase(PG8_LAS unsigned char* lds, const Gemm g, const Sched& S, const Epi& E, const float* gs_ss = nullptr) {
;     ...
;         const char* nA = has_next ? (const char*)g.A + S.a_extra(nxt) + (size_t)nxt.pm * tstep : cA; const char* nB = has_next ? (const char*)g.Bt + S.b_extra(nxt) + (size_t)nxt.pn * tstep : cB;
;         for (int t = 0; t < nt; t += 2) {
;             const bool last = (t == nt - 2);
;             const char* a1 = cA + (size_t)(t + 1) * kstep;
;             const char* a2 = last ? nA : cA + (size_t)(t + 2) * kstep; const char* b2 = last ? nB : cB + (size_t)(t + 2) * kstep;
;             const char* a3 = a2 + kstep; const char* b3 = b2 + kstep;
;             if constexpr (SP2) {
;             PG8_LDB(B0, 0, 0); PG8_LDB(B1, 0, 1); PG8_SCHED; PG8_LDA(At, 0, 0); PG8_STAGE(PG8_SA(1, 1), a1 + hstep, voffA);
;             PG8_WAIT_V(8); PG8_WAIT_L(0); PG8_BAR; PG8_MMA(0, 0, At, B0); PG8_MMA(0, 1, At, B1); PG8_BAR; PG8_SCHED;
;             PG8_LDA(At, 0, 1); PG8_STAGE(PG8_SB(0, 0), b2, voffB); PG8_STAGE(PG8_SB(0, 1), b2 + hstep, voffB); PG8_STAGE(PG8_SA(0, 0), a2, voffA);
;             PG8_WAIT_V(8); PG8_WAIT_L(0); PG8_BAR; PG8_MMA(1, 0, At, B0); PG8_MMA(1, 1, At, B1); PG8_BAR; PG8_SCHED;
.LBB0_314:
	s_add_u32 s2, s38, 0xfff80080
	s_addc_u32 s3, s39, -1
	s_add_i32 s64, 0, 0x10000
	s_cmp_eq_u32 s51, 28
	s_cselect_b32 s21, s13, s3
	s_cselect_b32 s20, s16, s2
	v_add_u32_e32 v0, s64, v173
	s_cselect_b32 s3, s17, s41
	s_cselect_b32 s2, s49, s40
	s_add_i32 s67, 0, 0x14000
	ds_read_b128 v[130:133], v0
	ds_read_b128 v[150:153], v0 offset:1024
	ds_read_b128 v[154:157], v0 offset:2048
	ds_read_b128 v[158:161], v0 offset:3072
	v_add_u32_e32 v0, s67, v173
	ds_read_b128 v[162:165], v0
	ds_read_b128 v[166:169], v0 offset:1024
	ds_read_b128 v[188:191], v0 offset:2048
	ds_read_b128 v[192:195], v0 offset:3072
	v_lshl_add_u64 v[170:171], s[38:39], 0, v[146:147]
	s_add_i32 m0, s24, 0xc000
	ds_read_b128 v[196:199], v177
	ds_read_b128 v[200:203], v177 offset:1024
	ds_read_b128 v[204:207], v177 offset:2048
	ds_read_b128 v[208:211], v177 offset:3072
	ds_read_b128 v[212:215], v177 offset:4096
	ds_read_b128 v[216:219], v177 offset:5120
	ds_read_b128 v[236:239], v177 offset:6144
	ds_read_b128 v[240:243], v177 offset:7168
	global_load_lds_dwordx4 v[170:171], off
	v_lshl_add_u64 v[170:171], s[38:39], 0, v[148:149]
	s_add_i32 m0, s24, 0xe000
	s_nop 0
	global_load_lds_dwordx4 v[170:171], off
	s_waitcnt vmcnt(8)
	s_waitcnt lgkmcnt(0)
	s_setprio 1
	s_barrier
	v_mfma_f32_16x16x32_bf16 v[126:129], v[130:133], v[196:199], v[126:129]
	v_mfma_f32_16x16x32_bf16 v[122:125], v[154:157], v[196:199], v[122:125]
	v_mfma_f32_16x16x32_bf16 v[118:121], v[130:133], v[204:207], v[118:121]
	v_mfma_f32_16x16x32_bf16 v[110:113], v[154:157], v[204:207], v[110:113]
	v_mfma_f32_16x16x32_bf16 v[102:105], v[130:133], v[212:215], v[102:105]
	v_mfma_f32_16x16x32_bf16 v[94:97], v[154:157], v[212:215], v[94:97]
	v_mfma_f32_16x16x32_bf16 v[86:89], v[130:133], v[236:239], v[86:89]
	v_mfma_f32_16x16x32_bf16 v[78:81], v[154:157], v[236:239], v[78:81]
	v_mfma_f32_16x16x32_bf16 v[126:129], v[150:153], v[200:203], v[126:129]
	v_mfma_f32_16x16x32_bf16 v[122:125], v[158:161], v[200:203], v[122:125]
	v_mfma_f32_16x16x32_bf16 v[118:121], v[150:153], v[208:211], v[118:121]
	v_mfma_f32_16x16x32_bf16 v[110:113], v[158:161], v[208:211], v[110:113]
	v_mfma_f32_16x16x32_bf16 v[102:105], v[150:153], v[216:219], v[102:105]
	v_mfma_f32_16x16x32_bf16 v[94:97], v[158:161], v[216:219], v[94:97]
	v_mfma_f32_16x16x32_bf16 v[86:89], v[150:153], v[240:243], v[86:89]
	v_mfma_f32_16x16x32_bf16 v[78:81], v[158:161], v[240:243], v[78:81]
	s_setprio 0
	s_setprio 1
	v_mfma_f32_16x16x32_bf16 v[114:117], v[162:165], v[196:199], v[114:117]
	v_mfma_f32_16x16x32_bf16 v[106:109], v[188:191], v[196:199], v[106:109]
	v_mfma_f32_16x16x32_bf16 v[98:101], v[162:165], v[204:207], v[98:101]
	v_mfma_f32_16x16x32_bf16 v[90:93], v[188:191], v[204:207], v[90:93]
	v_mfma_f32_16x16x32_bf16 v[82:85], v[162:165], v[212:215], v[82:85]
	v_mfma_f32_16x16x32_bf16 v[74:77], v[188:191], v[212:215], v[74:77]
	v_mfma_f32_16x16x32_bf16 v[70:73], v[162:165], v[236:239], v[70:73]
	v_mfma_f32_16x16x32_bf16 v[66:69], v[188:191], v[236:239], v[66:69]
	v_mfma_f32_16x16x32_bf16 v[114:117], v[166:169], v[200:203], v[114:117]
	v_mfma_f32_16x16x32_bf16 v[106:109], v[192:195], v[200:203], v[106:109]
	v_mfma_f32_16x16x32_bf16 v[98:101], v[166:169], v[208:211], v[98:101]
	v_mfma_f32_16x16x32_bf16 v[90:93], v[192:195], v[208:211], v[90:93]
	v_mfma_f32_16x16x32_bf16 v[82:85], v[166:169], v[216:219], v[82:85]
	v_mfma_f32_16x16x32_bf16 v[74:77], v[192:195], v[216:219], v[74:77]
	v_mfma_f32_16x16x32_bf16 v[70:73], v[166:169], v[240:243], v[70:73]
	v_mfma_f32_16x16x32_bf16 v[66:69], v[192:195], v[240:243], v[66:69]
	s_barrier
	s_setprio 0
	s_add_i32 s64, s64, s23
	v_lshl_add_u64 v[170:171], s[2:3], 0, v[136:137]
	s_mov_b32 m0, s64
	ds_read_b128 v[196:199], v177 offset:16384
	ds_read_b128 v[200:203], v177 offset:17408
	ds_read_b128 v[204:207], v177 offset:18432
	ds_read_b128 v[208:211], v177 offset:19456
	ds_read_b128 v[212:215], v177 offset:20480
	ds_read_b128 v[216:219], v177 offset:21504
	ds_read_b128 v[236:239], v177 offset:22528
	ds_read_b128 v[240:243], v177 offset:23552
	global_load_lds_dwordx4 v[170:171], off
	s_add_i32 m0, s64, 0x2000
	s_add_u32 s64, s2, 0x80000
	v_lshl_add_u64 v[180:181], s[2:3], 0, v[140:141]
	s_addc_u32 s65, s3, 0
	s_add_i32 s67, s67, s23
	global_load_lds_dwordx4 v[180:181], off
	v_lshl_add_u64 v[182:183], s[64:65], 0, v[136:137]
	s_mov_b32 m0, s67
	v_lshl_add_u64 v[184:185], s[20:21], 0, v[138:139]
	global_load_lds_dwordx4 v[182:183], off
	v_lshl_add_u64 v[182:183], s[64:65], 0, v[140:141]
	s_add_i32 m0, s67, 0x2000
	s_nop 0
	global_load_lds_dwordx4 v[182:183], off
	v_lshl_add_u64 v[182:183], s[20:21], 0, v[134:135]
	s_mov_b32 m0, s24
	s_nop 0
	global_load_lds_dwordx4 v[182:183], off
	s_mov_b32 m0, s25
	s_nop 0
	global_load_lds_dwordx4 v[184:185], off
	s_waitcnt vmcnt(8)
	s_waitcnt lgkmcnt(0)
	s_setprio 1
	s_barrier
; #define PG8_STAGE(bufoff, gbase, voff) do { _Pragma("unroll") for (int _i = 0; _i < 2; ++_i) \
;         __builtin_amdgcn_global_load_lds((const unsigned*)((const char*)(gbase) + (voff)[_i]), (PG8_LAS unsigned*)(lds + (bufoff) + ldsw + _i * 8192), 16, 0, 0); } while (0)
; #define PG8_LDA(dst, b, h) do { _Pragma("unroll") for (int m = 0; m < 4; ++m) _Pragma("unroll") for (int k = 0; k < 2; ++k) dst[m][k] = *(const PG8_LAS bf16x8*)(lds + PG8_SA(b, h) + aoff + m * 2048 + k * 1024); } while (0)
; #define PG8_LDB(dst, b, h) do { _Pragma("unroll") for (int n = 0; n < 2; ++n) _Pragma("unroll") for (int k = 0; k < 2; ++k) dst[n][k] = *(const PG8_LAS bf16x8*)(lds + PG8_SB(b, h) + boff + n * 2048 + k * 1024); } while (0)
; #define PG8_MMA(ai, bj, At, Bt) do { __builtin_amdgcn_s_setprio(1); _Pragma("unroll") for (int m = 0; m < 4; ++m) _Pragma("unroll") for (int n = 0; n < 2; ++n) _Pragma("unroll") for (int k = 0; k < 2; ++k) \
;         acc[ai][bj][m][n] = __builtin_amdgcn_mfma_f32_16x16x32_bf16(Bt[n][k], At[m][k], acc[ai][bj][m][n], 0, 0, 0); __builtin_amdgcn_s_setprio(0); } while (0)
; #define PG8_WAIT_V(n) asm volatile("s_waitcnt vmcnt(" #n ")" ::: "memory")
; #define PG8_WAIT_L(n) asm volatile("s_waitcnt lgkmcnt(" #n ")" ::: "memory")
; #define PG8_BAR __builtin_amdgcn_s_barrier()
; #define PG8_SCHED __builtin_amdgcn_sched_barrier(0)
; template <class Epi, class Sched, bool ALIGN_EPI = true, bool SP2 = true, bool GS = false>
; __device__ __forceinline__ void gemm_phase(PG8_LAS unsigned char* lds, const Gemm g, const Sched& S, const Epi& E, const float* gs_ss = nullptr) {
;     ...
;             PG8_WAIT_V(8); PG8_WAIT_L(0); PG8_BAR; PG8_MMA(1, 0, At, B0); PG8_MMA(1, 1, At, B1); PG8_BAR; PG8_SCHED;
;             PG8_LDB(B0, 1, 0); PG8_LDB(B1, 1, 1); PG8_SCHED; PG8_LDA(At, 1, 0); PG8_STAGE(PG8_SA(0, 1), a2 + hstep, voffA);
;             PG8_WAIT_V(8); PG8_WAIT_L(0); PG8_BAR; PG8_MMA(0, 0, At, B0); PG8_MMA(0, 1, At, B1); PG8_BAR; PG8_SCHED;
	v_mfma_f32_16x16x32_bf16 v[62:65], v[130:133], v[196:199], v[62:65]
	v_mfma_f32_16x16x32_bf16 v[58:61], v[154:157], v[196:199], v[58:61]
	v_mfma_f32_16x16x32_bf16 v[54:57], v[130:133], v[204:207], v[54:57]
	v_mfma_f32_16x16x32_bf16 v[46:49], v[154:157], v[204:207], v[46:49]
	v_mfma_f32_16x16x32_bf16 v[38:41], v[130:133], v[212:215], v[38:41]
	v_mfma_f32_16x16x32_bf16 v[30:33], v[154:157], v[212:215], v[30:33]
	v_mfma_f32_16x16x32_bf16 v[22:25], v[130:133], v[236:239], v[22:25]
	v_mfma_f32_16x16x32_bf16 v[14:17], v[154:157], v[236:239], v[14:17]
	v_mfma_f32_16x16x32_bf16 v[62:65], v[150:153], v[200:203], v[62:65]
	v_mfma_f32_16x16x32_bf16 v[58:61], v[158:161], v[200:203], v[58:61]
	v_mfma_f32_16x16x32_bf16 v[54:57], v[150:153], v[208:211], v[54:57]
	v_mfma_f32_16x16x32_bf16 v[46:49], v[158:161], v[208:211], v[46:49]
	v_mfma_f32_16x16x32_bf16 v[38:41], v[150:153], v[216:219], v[38:41]
	v_mfma_f32_16x16x32_bf16 v[30:33], v[158:161], v[216:219], v[30:33]
	v_mfma_f32_16x16x32_bf16 v[22:25], v[150:153], v[240:243], v[22:25]
	v_mfma_f32_16x16x32_bf16 v[14:17], v[158:161], v[240:243], v[14:17]
	s_setprio 0
	s_setprio 1
	v_mfma_f32_16x16x32_bf16 v[50:53], v[162:165], v[196:199], v[50:53]
	v_mfma_f32_16x16x32_bf16 v[42:45], v[188:191], v[196:199], v[42:45]
	v_mfma_f32_16x16x32_bf16 v[34:37], v[162:165], v[204:207], v[34:37]
	v_mfma_f32_16x16x32_bf16 v[26:29], v[188:191], v[204:207], v[26:29]
	v_mfma_f32_16x16x32_bf16 v[18:21], v[162:165], v[212:215], v[18:21]
	v_mfma_f32_16x16x32_bf16 v[10:13], v[188:191], v[212:215], v[10:13]
	v_mfma_f32_16x16x32_bf16 v[6:9], v[162:165], v[236:239], v[6:9]
	v_mfma_f32_16x16x32_bf16 v[2:5], v[188:191], v[236:239], v[2:5]
	v_mfma_f32_16x16x32_bf16 v[50:53], v[166:169], v[200:203], v[50:53]
	v_mfma_f32_16x16x32_bf16 v[42:45], v[192:195], v[200:203], v[42:45]
	v_mfma_f32_16x16x32_bf16 v[34:37], v[166:169], v[208:211], v[34:37]
	v_mfma_f32_16x16x32_bf16 v[26:29], v[192:195], v[208:211], v[26:29]
	v_mfma_f32_16x16x32_bf16 v[18:21], v[166:169], v[216:219], v[18:21]
	v_mfma_f32_16x16x32_bf16 v[10:13], v[192:195], v[216:219], v[10:13]
	v_mfma_f32_16x16x32_bf16 v[6:9], v[166:169], v[240:243], v[6:9]
	v_mfma_f32_16x16x32_bf16 v[2:5], v[192:195], v[240:243], v[2:5]
	s_barrier
	s_setprio 0
	s_add_i32 s64, 0, 0x18000
	v_add_u32_e32 v0, s64, v173
	s_add_i32 s65, 0, 0x1c000
	ds_read_b128 v[130:133], v0
	ds_read_b128 v[150:153], v0 offset:1024
	ds_read_b128 v[154:157], v0 offset:2048
	ds_read_b128 v[158:161], v0 offset:3072
	v_add_u32_e32 v0, s65, v173
	ds_read_b128 v[162:165], v0
	ds_read_b128 v[166:169], v0 offset:1024
	ds_read_b128 v[188:191], v0 offset:2048
	ds_read_b128 v[192:195], v0 offset:3072
	s_add_u32 s20, s20, 0x80000
	s_addc_u32 s21, s21, 0
	s_mov_b32 m0, s30
	v_lshl_add_u64 v[186:187], s[20:21], 0, v[134:135]
	ds_read_b128 v[196:199], v177 offset:32768
	ds_read_b128 v[200:203], v177 offset:33792
	ds_read_b128 v[204:207], v177 offset:34816
	ds_read_b128 v[208:211], v177 offset:35840
	ds_read_b128 v[212:215], v177 offset:36864
	ds_read_b128 v[216:219], v177 offset:37888
	ds_read_b128 v[236:239], v177 offset:38912
	ds_read_b128 v[240:243], v177 offset:39936
	global_load_lds_dwordx4 v[186:187], off
	v_lshl_add_u64 v[186:187], s[20:21], 0, v[138:139]
	s_mov_b32 m0, s36
	s_nop 0
	global_load_lds_dwordx4 v[186:187], off
	s_waitcnt vmcnt(8)
	s_waitcnt lgkmcnt(0)
	s_setprio 1
	s_barrier
	v_mfma_f32_16x16x32_bf16 v[126:129], v[130:133], v[196:199], v[126:129]
	v_mfma_f32_16x16x32_bf16 v[122:125], v[154:157], v[196:199], v[122:125]
	v_mfma_f32_16x16x32_bf16 v[118:121], v[130:133], v[204:207], v[118:121]
	v_mfma_f32_16x16x32_bf16 v[110:113], v[154:157], v[204:207], v[110:113]
	v_mfma_f32_16x16x32_bf16 v[102:105], v[130:133], v[212:215], v[102:105]
	v_mfma_f32_16x16x32_bf16 v[94:97], v[154:157], v[212:215], v[94:97]
	v_mfma_f32_16x16x32_bf16 v[86:89], v[130:133], v[236:239], v[86:89]
	v_mfma_f32_16x16x32_bf16 v[78:81], v[154:157], v[236:239], v[78:81]
	v_mfma_f32_16x16x32_bf16 v[126:129], v[150:153], v[200:203], v[126:129]
	v_mfma_f32_16x16x32_bf16 v[122:125], v[158:161], v[200:203], v[122:125]
	v_mfma_f32_16x16x32_bf16 v[118:121], v[150:153], v[208:211], v[118:121]
	v_mfma_f32_16x16x32_bf16 v[110:113], v[158:161], v[208:211], v[110:113]
	v_mfma_f32_16x16x32_bf16 v[102:105], v[150:153], v[216:219], v[102:105]
	v_mfma_f32_16x16x32_bf16 v[94:97], v[158:161], v[216:219], v[94:97]
	v_mfma_f32_16x16x32_bf16 v[86:89], v[150:153], v[240:243], v[86:89]
	v_mfma_f32_16x16x32_bf16 v[78:81], v[158:161], v[240:243], v[78:81]
	s_setprio 0
	s_setprio 1
	v_mfma_f32_16x16x32_bf16 v[114:117], v[162:165], v[196:199], v[114:117]
	v_mfma_f32_16x16x32_bf16 v[106:109], v[188:191], v[196:199], v[106:109]
	v_mfma_f32_16x16x32_bf16 v[98:101], v[162:165], v[204:207], v[98:101]
	v_mfma_f32_16x16x32_bf16 v[90:93], v[188:191], v[204:207], v[90:93]
	v_mfma_f32_16x16x32_bf16 v[82:85], v[162:165], v[212:215], v[82:85]
	v_mfma_f32_16x16x32_bf16 v[74:77], v[188:191], v[212:215], v[74:77]
	v_mfma_f32_16x16x32_bf16 v[70:73], v[162:165], v[236:239], v[70:73]
	v_mfma_f32_16x16x32_bf16 v[66:69], v[188:191], v[236:239], v[66:69]
	v_mfma_f32_16x16x32_bf16 v[114:117], v[166:169], v[200:203], v[114:117]
	v_mfma_f32_16x16x32_bf16 v[106:109], v[192:195], v[200:203], v[106:109]
	v_mfma_f32_16x16x32_bf16 v[98:101], v[166:169], v[208:211], v[98:101]
	v_mfma_f32_16x16x32_bf16 v[90:93], v[192:195], v[208:211], v[90:93]
	v_mfma_f32_16x16x32_bf16 v[82:85], v[166:169], v[216:219], v[82:85]
	v_mfma_f32_16x16x32_bf16 v[74:77], v[192:195], v[216:219], v[74:77]
	v_mfma_f32_16x16x32_bf16 v[70:73], v[166:169], v[240:243], v[70:73]
	v_mfma_f32_16x16x32_bf16 v[66:69], v[192:195], v[240:243], v[66:69]
	s_barrier
; #define PG8_STAGE(bufoff, gbase, voff) do { _Pragma("unroll") for (int _i = 0; _i < 2; ++_i) \
;         __builtin_amdgcn_global_load_lds((const unsigned*)((const char*)(gbase) + (voff)[_i]), (PG8_LAS unsigned*)(lds + (bufoff) + ldsw + _i * 8192), 16, 0, 0); } while (0)
; #define PG8_LDA(dst, b, h) do { _Pragma("unroll") for (int m = 0; m < 4; ++m) _Pragma("unroll") for (int k = 0; k < 2; ++k) dst[m][k] = *(const PG8_LAS bf16x8*)(lds + PG8_SA(b, h) + aoff + m * 2048 + k * 1024); } while (0)
; #define PG8_MMA(ai, bj, At, Bt) do { __builtin_amdgcn_s_setprio(1); _Pragma("unroll") for (int m = 0; m < 4; ++m) _Pragma("unroll") for (int n = 0; n < 2; ++n) _Pragma("unroll") for (int k = 0; k < 2; ++k) \
;         acc[ai][bj][m][n] = __builtin_amdgcn_mfma_f32_16x16x32_bf16(Bt[n][k], At[m][k], acc[ai][bj][m][n], 0, 0, 0); __builtin_amdgcn_s_setprio(0); } while (0)
; #define PG8_WAIT_V(n) asm volatile("s_waitcnt vmcnt(" #n ")" ::: "memory")
; #define PG8_WAIT_L(n) asm volatile("s_waitcnt lgkmcnt(" #n ")" ::: "memory")
; #define PG8_BAR __builtin_amdgcn_s_barrier()
; #define PG8_SCHED __builtin_amdgcn_sched_barrier(0)
; template <class Epi, class Sched, bool ALIGN_EPI = true, bool SP2 = true, bool GS = false>
; __device__ __forceinline__ void gemm_phase(PG8_LAS unsigned char* lds, const Gemm g, const Sched& S, const Epi& E, const float* gs_ss = nullptr) {
;     ...
;             PG8_LDA(At, 1, 1); PG8_STAGE(PG8_SB(1, 0), b3, voffB); PG8_STAGE(PG8_SB(1, 1), b3 + hstep, voffB); PG8_STAGE(PG8_SA(1, 0), a3, voffA);
;             PG8_WAIT_V(8); PG8_WAIT_L(0); PG8_BAR; PG8_MMA(1, 0, At, B0); PG8_MMA(1, 1, At, B1); PG8_BAR; PG8_SCHED;
;     ...
;         if constexpr (ALIGN_EPI) { if (wr == 0) PG8_BAR; }
	s_setprio 0
	s_add_i32 s20, s64, s23
	v_lshl_add_u64 v[170:171], v[170:171], 0, s[26:27]
	s_mov_b32 m0, s20
	ds_read_b128 v[196:199], v177 offset:49152
	ds_read_b128 v[200:203], v177 offset:50176
	ds_read_b128 v[204:207], v177 offset:51200
	ds_read_b128 v[208:211], v177 offset:52224
	ds_read_b128 v[212:215], v177 offset:53248
	ds_read_b128 v[216:219], v177 offset:54272
	ds_read_b128 v[236:239], v177 offset:55296
	ds_read_b128 v[240:243], v177 offset:56320
	global_load_lds_dwordx4 v[170:171], off
	s_add_i32 m0, s20, 0x2000
	s_add_u32 s2, s2, 0x80080
	v_lshl_add_u64 v[170:171], v[180:181], 0, s[26:27]
	s_addc_u32 s3, s3, 0
	s_add_i32 s20, s65, s23
	global_load_lds_dwordx4 v[170:171], off
	v_lshl_add_u64 v[170:171], s[2:3], 0, v[136:137]
	s_mov_b32 m0, s20
	s_nop 0
	global_load_lds_dwordx4 v[170:171], off
	v_lshl_add_u64 v[170:171], s[2:3], 0, v[140:141]
	s_add_i32 m0, s20, 0x2000
	s_nop 0
	global_load_lds_dwordx4 v[170:171], off
	v_lshl_add_u64 v[170:171], v[182:183], 0, s[26:27]
	s_mov_b32 m0, s59
	s_nop 0
	global_load_lds_dwordx4 v[170:171], off
	v_lshl_add_u64 v[170:171], v[184:185], 0, s[26:27]
	s_mov_b32 m0, s60
	s_nop 0
	global_load_lds_dwordx4 v[170:171], off
	s_waitcnt vmcnt(8)
	s_waitcnt lgkmcnt(0)
	s_setprio 1
	s_barrier
	v_mfma_f32_16x16x32_bf16 v[62:65], v[130:133], v[196:199], v[62:65]
	v_mfma_f32_16x16x32_bf16 v[58:61], v[154:157], v[196:199], v[58:61]
	v_mfma_f32_16x16x32_bf16 v[54:57], v[130:133], v[204:207], v[54:57]
	v_mfma_f32_16x16x32_bf16 v[46:49], v[154:157], v[204:207], v[46:49]
	v_mfma_f32_16x16x32_bf16 v[38:41], v[130:133], v[212:215], v[38:41]
	v_mfma_f32_16x16x32_bf16 v[30:33], v[154:157], v[212:215], v[30:33]
	v_mfma_f32_16x16x32_bf16 v[22:25], v[130:133], v[236:239], v[22:25]
	v_mfma_f32_16x16x32_bf16 v[14:17], v[154:157], v[236:239], v[14:17]
	v_mfma_f32_16x16x32_bf16 v[62:65], v[150:153], v[200:203], v[62:65]
	v_mfma_f32_16x16x32_bf16 v[58:61], v[158:161], v[200:203], v[58:61]
	v_mfma_f32_16x16x32_bf16 v[54:57], v[150:153], v[208:211], v[54:57]
	v_mfma_f32_16x16x32_bf16 v[46:49], v[158:161], v[208:211], v[46:49]
	v_mfma_f32_16x16x32_bf16 v[38:41], v[150:153], v[216:219], v[38:41]
	v_mfma_f32_16x16x32_bf16 v[30:33], v[158:161], v[216:219], v[30:33]
	v_mfma_f32_16x16x32_bf16 v[22:25], v[150:153], v[240:243], v[22:25]
	v_mfma_f32_16x16x32_bf16 v[14:17], v[158:161], v[240:243], v[14:17]
	s_setprio 0
	s_setprio 1
	v_mfma_f32_16x16x32_bf16 v[50:53], v[162:165], v[196:199], v[50:53]
	v_mfma_f32_16x16x32_bf16 v[42:45], v[188:191], v[196:199], v[42:45]
	v_mfma_f32_16x16x32_bf16 v[34:37], v[162:165], v[204:207], v[34:37]
	v_mfma_f32_16x16x32_bf16 v[26:29], v[188:191], v[204:207], v[26:29]
	v_mfma_f32_16x16x32_bf16 v[18:21], v[162:165], v[212:215], v[18:21]
	v_mfma_f32_16x16x32_bf16 v[10:13], v[188:191], v[212:215], v[10:13]
	v_mfma_f32_16x16x32_bf16 v[6:9], v[162:165], v[236:239], v[6:9]
	v_mfma_f32_16x16x32_bf16 v[2:5], v[188:191], v[236:239], v[2:5]
	v_mfma_f32_16x16x32_bf16 v[50:53], v[166:169], v[200:203], v[50:53]
	v_mfma_f32_16x16x32_bf16 v[42:45], v[192:195], v[200:203], v[42:45]
	v_mfma_f32_16x16x32_bf16 v[34:37], v[166:169], v[208:211], v[34:37]
	v_mfma_f32_16x16x32_bf16 v[26:29], v[192:195], v[208:211], v[26:29]
	v_mfma_f32_16x16x32_bf16 v[18:21], v[166:169], v[216:219], v[18:21]
	v_mfma_f32_16x16x32_bf16 v[10:13], v[192:195], v[216:219], v[10:13]
	v_mfma_f32_16x16x32_bf16 v[6:9], v[166:169], v[240:243], v[6:9]
	v_mfma_f32_16x16x32_bf16 v[2:5], v[192:195], v[240:243], v[2:5]
	s_barrier
	s_setprio 0
	s_add_i32 s51, s51, 2
	s_add_u32 s38, s38, 0x100
	s_addc_u32 s39, s39, 0
	s_add_u32 s40, s40, 0x100
	s_addc_u32 s41, s41, 0
	s_cmp_gt_u32 s51, 29
	s_cbranch_scc0 .LBB0_314
	s_and_b64 vcc, exec, s[42:43]
	s_cbranch_vccz .LBB0_319
	s_barrier
	s_lshl_b32 s16, s12, 8
	s_cmp_lt_i32 s46, 14
	s_mov_b64 s[2:3], -1
	s_cbranch_scc1 .LBB0_320

;     __device__ __forceinline__ size_t a_extra(const Unit& u) const { return (size_t)(u.pn >> 1) * ((size_t)T * 512 * 2); }
;     __device__ __forceinline__ size_t a_extra(const Unit& u) const { return (size_t)(u.pn >> 1) * 512 * 2; }
;     __device__ __forceinline__ size_t b_extra(const Unit& u) const { return (size_t)(u.pn >> 1) * 512 * 2 - (size_t)(u.pn & ~1) * ((size_t)256 * D * 2); }
; #define PG8_STAGE(bufoff, gbase, voff) do { _Pragma("unroll") for (int _i = 0; _i < 2; ++_i) \
;         __builtin_amdgcn_global_load_lds((const unsigned*)((const char*)(gbase) + (voff)[_i]), (PG8_LAS unsigned*)(lds + (bufoff) + ldsw + _i * 8192), 16, 0, 0); } while (0)
; #define PG8_LDA(dst, b, h) do { _Pragma("unroll") for (int m = 0; m < 4; ++m) _Pragma("unroll") for (int k = 0; k < 2; ++k) dst[m][k] = *(const PG8_LAS bf16x8*)(lds + PG8_SA(b, h) + aoff + m * 2048 + k * 1024); } while (0)
; #define PG8_WAIT_V(n) asm volatile("s_waitcnt vmcnt(" #n ")" ::: "memory")
; #define PG8_WAIT_L(n) asm volatile("s_waitcnt lgkmcnt(" #n ")" ::: "memory")
; template <class Epi, class Sched, bool ALIGN_EPI = true, bool SP2 = true, bool GS = false>
; __device__ __forceinline__ void gemm_phase(PG8_LAS unsigned char* lds, const Gemm g, const Sched& S, const Epi& E, const float* gs_ss = nullptr) {
;     ...
;         const char* nA = has_next ? (const char*)g.A + S.a_extra(nxt) + (size_t)nxt.pm * tstep : cA; const char* nB = has_next ? (const char*)g.Bt + S.b_extra(nxt) + (size_t)nxt.pn * tstep : cB;
;         for (int t = 0; t < nt; t += 2) {
;             const bool last = (t == nt - 2);
;             const char* a1 = cA + (size_t)(t + 1) * kstep;
;             const char* a2 = last ? nA : cA + (size_t)(t + 2) * kstep; const char* b2 = last ? nB : cB + (size_t)(t + 2) * kstep;
;             const char* a3 = a2 + kstep; const char* b3 = b2 + kstep;
;             if constexpr (SP2) {
;             PG8_LDB(B0, 0, 0); PG8_LDB(B1, 0, 1); PG8_SCHED; PG8_LDA(At, 0, 0); PG8_STAGE(PG8_SA(1, 1), a1 + hstep, voffA);
;             PG8_WAIT_V(8); PG8_WAIT_L(0); PG8_BAR; PG8_MMA(0, 0, At, B0); PG8_MMA(0, 1, At, B1); PG8_BAR; PG8_SCHED;
;             PG8_LDA(At, 0, 1); PG8_STAGE(PG8_SB(0, 0), b2, voffB); PG8_STAGE(PG8_SB(0, 1), b2 + hstep, voffB); PG8_STAGE(PG8_SA(0, 0), a2, voffA);
;             PG8_WAIT_V(8); PG8_WAIT_L(0); PG8_BAR; PG8_MMA(1, 0, At, B0); PG8_MMA(1, 1, At, B1); PG8_BAR; PG8_SCHED;
.LBB0_788:
	s_add_u32 s2, s34, 0xfffe0080
	s_addc_u32 s3, s35, -1
	s_add_i32 s42, 0, 0x10000
	s_cmp_eq_u32 s41, 4
	s_cselect_b32 s21, s16, s3
	s_cselect_b32 s20, s17, s2
	v_add_u32_e32 v0, s42, v183
	s_cselect_b32 s3, s13, s40
	s_cselect_b32 s2, s18, s29
	s_add_i32 s57, 0, 0x14000
	ds_read_b128 v[18:21], v0
	ds_read_b128 v[26:29], v0 offset:1024
	ds_read_b128 v[30:33], v0 offset:2048
	ds_read_b128 v[38:41], v0 offset:3072
	v_add_u32_e32 v0, s57, v183
	ds_read_b128 v[42:45], v0
	ds_read_b128 v[46:49], v0 offset:1024
	ds_read_b128 v[58:61], v0 offset:2048
	ds_read_b128 v[70:73], v0 offset:3072
	v_lshl_add_u64 v[180:181], s[34:35], 0, v[196:197]
	s_add_i32 m0, s37, 0xc000
	ds_read_b128 v[82:85], v219
	ds_read_b128 v[94:97], v219 offset:1024
	ds_read_b128 v[106:109], v219 offset:2048
	ds_read_b128 v[118:121], v219 offset:3072
	ds_read_b128 v[184:187], v219 offset:4096
	ds_read_b128 v[200:203], v219 offset:5120
	ds_read_b128 v[204:207], v219 offset:6144
	ds_read_b128 v[208:211], v219 offset:7168
	global_load_lds_dwordx4 v[180:181], off
	v_lshl_add_u64 v[180:181], s[34:35], 0, v[198:199]
	s_add_i32 m0, s37, 0xe000
	s_nop 0
	global_load_lds_dwordx4 v[180:181], off
	s_waitcnt vmcnt(8)
	s_waitcnt lgkmcnt(0)
	s_setprio 1
	s_barrier
	v_mfma_f32_16x16x32_bf16 v[174:177], v[18:21], v[82:85], v[174:177]
	v_mfma_f32_16x16x32_bf16 v[170:173], v[30:33], v[82:85], v[170:173]
	v_mfma_f32_16x16x32_bf16 v[158:161], v[18:21], v[106:109], v[158:161]
	v_mfma_f32_16x16x32_bf16 v[154:157], v[30:33], v[106:109], v[154:157]
	v_mfma_f32_16x16x32_bf16 v[142:145], v[18:21], v[184:187], v[142:145]
	v_mfma_f32_16x16x32_bf16 v[138:141], v[30:33], v[184:187], v[138:141]
	v_mfma_f32_16x16x32_bf16 v[126:129], v[18:21], v[204:207], v[126:129]
	v_mfma_f32_16x16x32_bf16 v[122:125], v[30:33], v[204:207], v[122:125]
	v_mfma_f32_16x16x32_bf16 v[174:177], v[26:29], v[94:97], v[174:177]
	v_mfma_f32_16x16x32_bf16 v[170:173], v[38:41], v[94:97], v[170:173]
	v_mfma_f32_16x16x32_bf16 v[158:161], v[26:29], v[118:121], v[158:161]
	v_mfma_f32_16x16x32_bf16 v[154:157], v[38:41], v[118:121], v[154:157]
	v_mfma_f32_16x16x32_bf16 v[142:145], v[26:29], v[200:203], v[142:145]
	v_mfma_f32_16x16x32_bf16 v[138:141], v[38:41], v[200:203], v[138:141]
	v_mfma_f32_16x16x32_bf16 v[126:129], v[26:29], v[208:211], v[126:129]
	v_mfma_f32_16x16x32_bf16 v[122:125], v[38:41], v[208:211], v[122:125]
	s_setprio 0
	s_setprio 1
	v_mfma_f32_16x16x32_bf16 v[166:169], v[42:45], v[82:85], v[166:169]
	v_mfma_f32_16x16x32_bf16 v[82:85], v[58:61], v[82:85], v[162:165]
	v_mfma_f32_16x16x32_bf16 v[166:169], v[46:49], v[94:97], v[166:169]
	v_mfma_f32_16x16x32_bf16 v[82:85], v[70:73], v[94:97], v[82:85]
	v_mfma_f32_16x16x32_bf16 v[94:97], v[42:45], v[106:109], v[150:153]
	v_mfma_f32_16x16x32_bf16 v[106:109], v[58:61], v[106:109], v[146:149]
	v_mfma_f32_16x16x32_bf16 v[130:133], v[58:61], v[184:187], v[130:133]
	v_mfma_f32_16x16x32_bf16 v[114:117], v[42:45], v[204:207], v[114:117]
	v_mfma_f32_16x16x32_bf16 v[110:113], v[58:61], v[204:207], v[110:113]
	v_mfma_f32_16x16x32_bf16 v[94:97], v[46:49], v[118:121], v[94:97]
	v_mfma_f32_16x16x32_bf16 v[106:109], v[70:73], v[118:121], v[106:109]
	v_mfma_f32_16x16x32_bf16 v[118:121], v[42:45], v[184:187], v[134:137]
	v_mfma_f32_16x16x32_bf16 v[130:133], v[70:73], v[200:203], v[130:133]
	v_mfma_f32_16x16x32_bf16 v[114:117], v[46:49], v[208:211], v[114:117]
	v_mfma_f32_16x16x32_bf16 v[110:113], v[70:73], v[208:211], v[110:113]
	v_mfma_f32_16x16x32_bf16 v[118:121], v[46:49], v[200:203], v[118:121]
	s_barrier
	s_setprio 0
	s_add_i32 s42, s42, s25
	v_lshl_add_u64 v[180:181], s[2:3], 0, v[190:191]
	s_mov_b32 m0, s42
	ds_read_b128 v[134:137], v219 offset:16384
	ds_read_b128 v[146:149], v219 offset:17408
	ds_read_b128 v[150:153], v219 offset:18432
	ds_read_b128 v[162:165], v219 offset:19456
	ds_read_b128 v[184:187], v219 offset:20480
	ds_read_b128 v[200:203], v219 offset:21504
	ds_read_b128 v[204:207], v219 offset:22528
	ds_read_b128 v[208:211], v219 offset:23552
	global_load_lds_dwordx4 v[180:181], off
	s_add_i32 m0, s42, 0x2000
	s_add_u32 s42, s2, 0x20000
	v_lshl_add_u64 v[216:217], s[2:3], 0, v[194:195]
	s_addc_u32 s43, s3, 0
	s_add_i32 s57, s57, s25
	global_load_lds_dwordx4 v[216:217], off
	v_lshl_add_u64 v[212:213], s[42:43], 0, v[190:191]
	s_mov_b32 m0, s57
	v_lshl_add_u64 v[220:221], s[20:21], 0, v[188:189]
	global_load_lds_dwordx4 v[212:213], off
	v_lshl_add_u64 v[212:213], s[42:43], 0, v[194:195]
	s_add_i32 m0, s57, 0x2000
	v_lshl_add_u64 v[244:245], s[20:21], 0, v[192:193]
	global_load_lds_dwordx4 v[212:213], off
	s_mov_b32 m0, s37
	s_nop 0
	global_load_lds_dwordx4 v[220:221], off
	s_mov_b32 m0, s59
	s_nop 0
	global_load_lds_dwordx4 v[244:245], off
	s_waitcnt vmcnt(8)
	s_waitcnt lgkmcnt(0)
	s_setprio 1
	s_barrier
; #define PG8_STAGE(bufoff, gbase, voff) do { _Pragma("unroll") for (int _i = 0; _i < 2; ++_i) \
;         __builtin_amdgcn_global_load_lds((const unsigned*)((const char*)(gbase) + (voff)[_i]), (PG8_LAS unsigned*)(lds + (bufoff) + ldsw + _i * 8192), 16, 0, 0); } while (0)
; #define PG8_LDA(dst, b, h) do { _Pragma("unroll") for (int m = 0; m < 4; ++m) _Pragma("unroll") for (int k = 0; k < 2; ++k) dst[m][k] = *(const PG8_LAS bf16x8*)(lds + PG8_SA(b, h) + aoff + m * 2048 + k * 1024); } while (0)
; #define PG8_LDB(dst, b, h) do { _Pragma("unroll") for (int n = 0; n < 2; ++n) _Pragma("unroll") for (int k = 0; k < 2; ++k) dst[n][k] = *(const PG8_LAS bf16x8*)(lds + PG8_SB(b, h) + boff + n * 2048 + k * 1024); } while (0)
; #define PG8_MMA(ai, bj, At, Bt) do { __builtin_amdgcn_s_setprio(1); _Pragma("unroll") for (int m = 0; m < 4; ++m) _Pragma("unroll") for (int n = 0; n < 2; ++n) _Pragma("unroll") for (int k = 0; k < 2; ++k) \
;         acc[ai][bj][m][n] = __builtin_amdgcn_mfma_f32_16x16x32_bf16(Bt[n][k], At[m][k], acc[ai][bj][m][n], 0, 0, 0); __builtin_amdgcn_s_setprio(0); } while (0)
; #define PG8_WAIT_V(n) asm volatile("s_waitcnt vmcnt(" #n ")" ::: "memory")
; #define PG8_WAIT_L(n) asm volatile("s_waitcnt lgkmcnt(" #n ")" ::: "memory")
; #define PG8_BAR __builtin_amdgcn_s_barrier()
; #define PG8_SCHED __builtin_amdgcn_sched_barrier(0)
; template <class Epi, class Sched, bool ALIGN_EPI = true, bool SP2 = true, bool GS = false>
; __device__ __forceinline__ void gemm_phase(PG8_LAS unsigned char* lds, const Gemm g, const Sched& S, const Epi& E, const float* gs_ss = nullptr) {
;     ...
;             PG8_WAIT_V(8); PG8_WAIT_L(0); PG8_BAR; PG8_MMA(1, 0, At, B0); PG8_MMA(1, 1, At, B1); PG8_BAR; PG8_SCHED;
;             PG8_LDB(B0, 1, 0); PG8_LDB(B1, 1, 1); PG8_SCHED; PG8_LDA(At, 1, 0); PG8_STAGE(PG8_SA(0, 1), a2 + hstep, voffA);
;             PG8_WAIT_V(8); PG8_WAIT_L(0); PG8_BAR; PG8_MMA(0, 0, At, B0); PG8_MMA(0, 1, At, B1); PG8_BAR; PG8_SCHED;
	v_mfma_f32_16x16x32_bf16 v[102:105], v[18:21], v[134:137], v[102:105]
	v_mfma_f32_16x16x32_bf16 v[98:101], v[30:33], v[134:137], v[98:101]
	v_mfma_f32_16x16x32_bf16 v[78:81], v[18:21], v[150:153], v[78:81]
	v_mfma_f32_16x16x32_bf16 v[74:77], v[30:33], v[150:153], v[74:77]
	v_mfma_f32_16x16x32_bf16 v[54:57], v[18:21], v[184:187], v[54:57]
	v_mfma_f32_16x16x32_bf16 v[50:53], v[30:33], v[184:187], v[50:53]
	v_mfma_f32_16x16x32_bf16 v[14:17], v[18:21], v[204:207], v[14:17]
	v_mfma_f32_16x16x32_bf16 v[10:13], v[30:33], v[204:207], v[10:13]
	v_mfma_f32_16x16x32_bf16 v[102:105], v[26:29], v[146:149], v[102:105]
	v_mfma_f32_16x16x32_bf16 v[98:101], v[38:41], v[146:149], v[98:101]
	v_mfma_f32_16x16x32_bf16 v[78:81], v[26:29], v[162:165], v[78:81]
	v_mfma_f32_16x16x32_bf16 v[74:77], v[38:41], v[162:165], v[74:77]
	v_mfma_f32_16x16x32_bf16 v[54:57], v[26:29], v[200:203], v[54:57]
	v_mfma_f32_16x16x32_bf16 v[50:53], v[38:41], v[200:203], v[50:53]
	v_mfma_f32_16x16x32_bf16 v[14:17], v[26:29], v[208:211], v[14:17]
	v_mfma_f32_16x16x32_bf16 v[10:13], v[38:41], v[208:211], v[10:13]
	s_setprio 0
	s_setprio 1
	v_mfma_f32_16x16x32_bf16 v[34:37], v[42:45], v[184:187], v[34:37]
	v_mfma_f32_16x16x32_bf16 v[22:25], v[58:61], v[184:187], v[22:25]
	v_mfma_f32_16x16x32_bf16 v[6:9], v[42:45], v[204:207], v[6:9]
	v_mfma_f32_16x16x32_bf16 v[2:5], v[58:61], v[204:207], v[2:5]
	v_mfma_f32_16x16x32_bf16 v[18:21], v[42:45], v[134:137], v[90:93]
	v_mfma_f32_16x16x32_bf16 v[26:29], v[58:61], v[134:137], v[86:89]
	v_mfma_f32_16x16x32_bf16 v[30:33], v[42:45], v[150:153], v[66:69]
	v_mfma_f32_16x16x32_bf16 v[38:41], v[58:61], v[150:153], v[62:65]
	v_mfma_f32_16x16x32_bf16 v[34:37], v[46:49], v[200:203], v[34:37]
	v_mfma_f32_16x16x32_bf16 v[22:25], v[70:73], v[200:203], v[22:25]
	v_mfma_f32_16x16x32_bf16 v[6:9], v[46:49], v[208:211], v[6:9]
	v_mfma_f32_16x16x32_bf16 v[2:5], v[70:73], v[208:211], v[2:5]
	v_mfma_f32_16x16x32_bf16 v[18:21], v[46:49], v[146:149], v[18:21]
	v_mfma_f32_16x16x32_bf16 v[26:29], v[70:73], v[146:149], v[26:29]
	v_mfma_f32_16x16x32_bf16 v[30:33], v[46:49], v[162:165], v[30:33]
	v_mfma_f32_16x16x32_bf16 v[38:41], v[70:73], v[162:165], v[38:41]
	s_barrier
	s_setprio 0
	s_add_i32 s42, 0, 0x18000
	v_add_u32_e32 v0, s42, v183
	s_add_i32 s43, 0, 0x1c000
	ds_read_b128 v[42:45], v0
	ds_read_b128 v[46:49], v0 offset:1024
	ds_read_b128 v[58:61], v0 offset:2048
	ds_read_b128 v[62:65], v0 offset:3072
	v_add_u32_e32 v0, s43, v183
	ds_read_b128 v[70:73], v0
	ds_read_b128 v[184:187], v0 offset:1024
	ds_read_b128 v[200:203], v0 offset:2048
	ds_read_b128 v[204:207], v0 offset:3072
	s_add_u32 s20, s20, 0x20000
	s_addc_u32 s21, s21, 0
	s_mov_b32 m0, s69
	v_lshl_add_u64 v[146:147], s[20:21], 0, v[188:189]
	ds_read_b128 v[66:69], v219 offset:32768
	ds_read_b128 v[86:89], v219 offset:33792
	ds_read_b128 v[90:93], v219 offset:34816
	ds_read_b128 v[134:137], v219 offset:35840
	ds_read_b128 v[208:211], v219 offset:36864
	ds_read_b128 v[212:215], v219 offset:37888
	ds_read_b128 v[236:239], v219 offset:38912
	ds_read_b128 v[240:243], v219 offset:39936
	global_load_lds_dwordx4 v[146:147], off
	v_lshl_add_u64 v[146:147], s[20:21], 0, v[192:193]
	s_mov_b32 m0, s64
	s_nop 0
	global_load_lds_dwordx4 v[146:147], off
	s_waitcnt vmcnt(8)
	s_waitcnt lgkmcnt(0)
	s_setprio 1
	s_barrier
	v_mfma_f32_16x16x32_bf16 v[146:149], v[42:45], v[66:69], v[174:177]
	v_mfma_f32_16x16x32_bf16 v[174:177], v[46:49], v[86:89], v[146:149]
	v_mfma_f32_16x16x32_bf16 v[146:149], v[58:61], v[66:69], v[170:173]
	v_mfma_f32_16x16x32_bf16 v[170:173], v[62:65], v[86:89], v[146:149]
	v_mfma_f32_16x16x32_bf16 v[146:149], v[42:45], v[90:93], v[158:161]
	v_mfma_f32_16x16x32_bf16 v[158:161], v[46:49], v[134:137], v[146:149]
	v_mfma_f32_16x16x32_bf16 v[146:149], v[58:61], v[90:93], v[154:157]
	v_mfma_f32_16x16x32_bf16 v[142:145], v[42:45], v[208:211], v[142:145]
	v_mfma_f32_16x16x32_bf16 v[138:141], v[58:61], v[208:211], v[138:141]
	v_mfma_f32_16x16x32_bf16 v[126:129], v[42:45], v[236:239], v[126:129]
	v_mfma_f32_16x16x32_bf16 v[122:125], v[58:61], v[236:239], v[122:125]
	v_mfma_f32_16x16x32_bf16 v[154:157], v[62:65], v[134:137], v[146:149]
	v_mfma_f32_16x16x32_bf16 v[142:145], v[46:49], v[212:215], v[142:145]
	v_mfma_f32_16x16x32_bf16 v[138:141], v[62:65], v[212:215], v[138:141]
	v_mfma_f32_16x16x32_bf16 v[126:129], v[46:49], v[240:243], v[126:129]
	v_mfma_f32_16x16x32_bf16 v[122:125], v[62:65], v[240:243], v[122:125]
	s_setprio 0
	s_setprio 1
	v_mfma_f32_16x16x32_bf16 v[146:149], v[70:73], v[66:69], v[166:169]
	v_mfma_f32_16x16x32_bf16 v[66:69], v[200:203], v[66:69], v[82:85]
	v_mfma_f32_16x16x32_bf16 v[162:165], v[204:207], v[86:89], v[66:69]
	v_mfma_f32_16x16x32_bf16 v[66:69], v[70:73], v[90:93], v[94:97]
	v_mfma_f32_16x16x32_bf16 v[150:153], v[184:187], v[134:137], v[66:69]
	v_mfma_f32_16x16x32_bf16 v[66:69], v[200:203], v[90:93], v[106:109]
	v_mfma_f32_16x16x32_bf16 v[166:169], v[184:187], v[86:89], v[146:149]
	v_mfma_f32_16x16x32_bf16 v[146:149], v[204:207], v[134:137], v[66:69]
	v_mfma_f32_16x16x32_bf16 v[66:69], v[70:73], v[208:211], v[118:121]
	v_mfma_f32_16x16x32_bf16 v[134:137], v[184:187], v[212:215], v[66:69]
	v_mfma_f32_16x16x32_bf16 v[66:69], v[200:203], v[208:211], v[130:133]
	v_mfma_f32_16x16x32_bf16 v[130:133], v[204:207], v[212:215], v[66:69]
	v_mfma_f32_16x16x32_bf16 v[66:69], v[70:73], v[236:239], v[114:117]
	v_mfma_f32_16x16x32_bf16 v[114:117], v[184:187], v[240:243], v[66:69]
	v_mfma_f32_16x16x32_bf16 v[66:69], v[200:203], v[236:239], v[110:113]
	v_mfma_f32_16x16x32_bf16 v[110:113], v[204:207], v[240:243], v[66:69]
	s_barrier
; #define PG8_STAGE(bufoff, gbase, voff) do { _Pragma("unroll") for (int _i = 0; _i < 2; ++_i) \
;         __builtin_amdgcn_global_load_lds((const unsigned*)((const char*)(gbase) + (voff)[_i]), (PG8_LAS unsigned*)(lds + (bufoff) + ldsw + _i * 8192), 16, 0, 0); } while (0)
; #define PG8_LDA(dst, b, h) do { _Pragma("unroll") for (int m = 0; m < 4; ++m) _Pragma("unroll") for (int k = 0; k < 2; ++k) dst[m][k] = *(const PG8_LAS bf16x8*)(lds + PG8_SA(b, h) + aoff + m * 2048 + k * 1024); } while (0)
; #define PG8_MMA(ai, bj, At, Bt) do { __builtin_amdgcn_s_setprio(1); _Pragma("unroll") for (int m = 0; m < 4; ++m) _Pragma("unroll") for (int n = 0; n < 2; ++n) _Pragma("unroll") for (int k = 0; k < 2; ++k) \
;         acc[ai][bj][m][n] = __builtin_amdgcn_mfma_f32_16x16x32_bf16(Bt[n][k], At[m][k], acc[ai][bj][m][n], 0, 0, 0); __builtin_amdgcn_s_setprio(0); } while (0)
; #define PG8_WAIT_V(n) asm volatile("s_waitcnt vmcnt(" #n ")" ::: "memory")
; #define PG8_WAIT_L(n) asm volatile("s_waitcnt lgkmcnt(" #n ")" ::: "memory")
; #define PG8_BAR __builtin_amdgcn_s_barrier()
; #define PG8_SCHED __builtin_amdgcn_sched_barrier(0)
; template <class Epi, class Sched, bool ALIGN_EPI = true, bool SP2 = true, bool GS = false>
; __device__ __forceinline__ void gemm_phase(PG8_LAS unsigned char* lds, const Gemm g, const Sched& S, const Epi& E, const float* gs_ss = nullptr) {
;     ...
;         for (int t = 0; t < nt; t += 2) {
;             const bool last = (t == nt - 2);
;             const char* a1 = cA + (size_t)(t + 1) * kstep;
;     ...
;             PG8_LDA(At, 1, 1); PG8_STAGE(PG8_SB(1, 0), b3, voffB); PG8_STAGE(PG8_SB(1, 1), b3 + hstep, voffB); PG8_STAGE(PG8_SA(1, 0), a3, voffA);
;             PG8_WAIT_V(8); PG8_WAIT_L(0); PG8_BAR; PG8_MMA(1, 0, At, B0); PG8_MMA(1, 1, At, B1); PG8_BAR; PG8_SCHED;
	s_setprio 0
	s_add_i32 s20, s42, s25
	v_lshl_add_u64 v[86:87], v[180:181], 0, s[26:27]
	s_mov_b32 m0, s20
	s_nop 1
	ds_read_b128 v[66:69], v219 offset:49152
	ds_read_b128 v[82:85], v219 offset:50176
	ds_read_b128 v[94:97], v219 offset:51200
	ds_read_b128 v[106:109], v219 offset:52224
	ds_read_b128 v[118:121], v219 offset:53248
	ds_read_b128 v[208:211], v219 offset:54272
	ds_read_b128 v[212:215], v219 offset:55296
	ds_read_b128 v[236:239], v219 offset:56320
	global_load_lds_dwordx4 v[86:87], off
	s_add_i32 m0, s20, 0x2000
	s_add_u32 s2, s2, 0x20080
	v_lshl_add_u64 v[86:87], v[216:217], 0, s[26:27]
	s_addc_u32 s3, s3, 0
	s_add_i32 s20, s43, s25
	global_load_lds_dwordx4 v[86:87], off
	v_lshl_add_u64 v[86:87], s[2:3], 0, v[190:191]
	s_mov_b32 m0, s20
	s_nop 0
	global_load_lds_dwordx4 v[86:87], off
	v_lshl_add_u64 v[86:87], s[2:3], 0, v[194:195]
	s_add_i32 m0, s20, 0x2000
	s_nop 0
	global_load_lds_dwordx4 v[86:87], off
	v_lshl_add_u64 v[86:87], v[220:221], 0, s[26:27]
	s_mov_b32 m0, s30
	s_nop 0
	global_load_lds_dwordx4 v[86:87], off
	v_lshl_add_u64 v[86:87], v[244:245], 0, s[26:27]
	s_mov_b32 m0, s14
	s_nop 0
	global_load_lds_dwordx4 v[86:87], off
	s_waitcnt vmcnt(8)
	s_waitcnt lgkmcnt(0)
	s_setprio 1
	s_barrier
	v_mfma_f32_16x16x32_bf16 v[86:89], v[42:45], v[66:69], v[102:105]
	v_mfma_f32_16x16x32_bf16 v[102:105], v[46:49], v[82:85], v[86:89]
	v_mfma_f32_16x16x32_bf16 v[86:89], v[58:61], v[66:69], v[98:101]
	v_mfma_f32_16x16x32_bf16 v[78:81], v[42:45], v[94:97], v[78:81]
	v_mfma_f32_16x16x32_bf16 v[74:77], v[58:61], v[94:97], v[74:77]
	v_mfma_f32_16x16x32_bf16 v[54:57], v[42:45], v[118:121], v[54:57]
	v_mfma_f32_16x16x32_bf16 v[50:53], v[58:61], v[118:121], v[50:53]
	v_mfma_f32_16x16x32_bf16 v[14:17], v[42:45], v[212:215], v[14:17]
	v_mfma_f32_16x16x32_bf16 v[10:13], v[58:61], v[212:215], v[10:13]
	v_mfma_f32_16x16x32_bf16 v[98:101], v[62:65], v[82:85], v[86:89]
	v_mfma_f32_16x16x32_bf16 v[78:81], v[46:49], v[106:109], v[78:81]
	v_mfma_f32_16x16x32_bf16 v[74:77], v[62:65], v[106:109], v[74:77]
	v_mfma_f32_16x16x32_bf16 v[54:57], v[46:49], v[208:211], v[54:57]
	v_mfma_f32_16x16x32_bf16 v[50:53], v[62:65], v[208:211], v[50:53]
	v_mfma_f32_16x16x32_bf16 v[14:17], v[46:49], v[236:239], v[14:17]
	v_mfma_f32_16x16x32_bf16 v[10:13], v[62:65], v[236:239], v[10:13]
	s_setprio 0
	s_setprio 1
	v_mfma_f32_16x16x32_bf16 v[18:21], v[70:73], v[66:69], v[18:21]
	v_mfma_f32_16x16x32_bf16 v[90:93], v[184:187], v[82:85], v[18:21]
	v_mfma_f32_16x16x32_bf16 v[18:21], v[200:203], v[66:69], v[26:29]
	v_mfma_f32_16x16x32_bf16 v[86:89], v[204:207], v[82:85], v[18:21]
	v_mfma_f32_16x16x32_bf16 v[18:21], v[70:73], v[94:97], v[30:33]
	v_mfma_f32_16x16x32_bf16 v[66:69], v[184:187], v[106:109], v[18:21]
	v_mfma_f32_16x16x32_bf16 v[18:21], v[200:203], v[94:97], v[38:41]
	v_mfma_f32_16x16x32_bf16 v[62:65], v[204:207], v[106:109], v[18:21]
	v_mfma_f32_16x16x32_bf16 v[18:21], v[70:73], v[118:121], v[34:37]
	v_mfma_f32_16x16x32_bf16 v[34:37], v[184:187], v[208:211], v[18:21]
	v_mfma_f32_16x16x32_bf16 v[18:21], v[200:203], v[118:121], v[22:25]
	v_mfma_f32_16x16x32_bf16 v[6:9], v[70:73], v[212:215], v[6:9]
	v_mfma_f32_16x16x32_bf16 v[2:5], v[200:203], v[212:215], v[2:5]
	v_mfma_f32_16x16x32_bf16 v[22:25], v[204:207], v[208:211], v[18:21]
	v_mfma_f32_16x16x32_bf16 v[6:9], v[184:187], v[236:239], v[6:9]
	v_mfma_f32_16x16x32_bf16 v[2:5], v[204:207], v[236:239], v[2:5]
	s_barrier
	s_setprio 0
	s_add_i32 s41, s41, 2
	s_add_u32 s34, s34, 0x100
	s_addc_u32 s35, s35, 0
	s_add_u32 s29, s29, 0x100
	s_addc_u32 s40, s40, 0
	s_cmp_gt_u32 s41, 5
	s_cbranch_scc0 .LBB0_788
	s_and_b64 vcc, exec, s[54:55]
	s_cbranch_vccz .LBB0_791
	s_barrier

;     __device__ __forceinline__ size_t a_extra(const Unit& u) const { return (size_t)(u.pn >> 1) * ((size_t)T * 512 * 2); }
;     __device__ __forceinline__ size_t a_extra(const Unit& u) const { return (size_t)(u.pn >> 1) * 512 * 2; }
;     __device__ __forceinline__ size_t b_extra(const Unit& u) const { return (size_t)(u.pn >> 1) * 512 * 2 - (size_t)(u.pn & ~1) * ((size_t)256 * D * 2); }
; #define PG8_STAGE(bufoff, gbase, voff) do { _Pragma("unroll") for (int _i = 0; _i < 2; ++_i) \
;         __builtin_amdgcn_global_load_lds((const unsigned*)((const char*)(gbase) + (voff)[_i]), (PG8_LAS unsigned*)(lds + (bufoff) + ldsw + _i * 8192), 16, 0, 0); } while (0)
; #define PG8_LDA(dst, b, h) do { _Pragma("unroll") for (int m = 0; m < 4; ++m) _Pragma("unroll") for (int k = 0; k < 2; ++k) dst[m][k] = *(const PG8_LAS bf16x8*)(lds + PG8_SA(b, h) + aoff + m * 2048 + k * 1024); } while (0)
; #define PG8_WAIT_V(n) asm volatile("s_waitcnt vmcnt(" #n ")" ::: "memory")
; #define PG8_WAIT_L(n) asm volatile("s_waitcnt lgkmcnt(" #n ")" ::: "memory")
; template <class Epi, class Sched, bool ALIGN_EPI = true, bool SP2 = true, bool GS = false>
; __device__ __forceinline__ void gemm_phase(PG8_LAS unsigned char* lds, const Gemm g, const Sched& S, const Epi& E, const float* gs_ss = nullptr) {
;     ...
;         const char* nA = has_next ? (const char*)g.A + S.a_extra(nxt) + (size_t)nxt.pm * tstep : cA; const char* nB = has_next ? (const char*)g.Bt + S.b_extra(nxt) + (size_t)nxt.pn * tstep : cB;
;         for (int t = 0; t < nt; t += 2) {
;             const bool last = (t == nt - 2);
;             const char* a1 = cA + (size_t)(t + 1) * kstep;
;             const char* a2 = last ? nA : cA + (size_t)(t + 2) * kstep; const char* b2 = last ? nB : cB + (size_t)(t + 2) * kstep;
;             const char* a3 = a2 + kstep; const char* b3 = b2 + kstep;
;             if constexpr (SP2) {
;             PG8_LDB(B0, 0, 0); PG8_LDB(B1, 0, 1); PG8_SCHED; PG8_LDA(At, 0, 0); PG8_STAGE(PG8_SA(1, 1), a1 + hstep, voffA);
;             PG8_WAIT_V(8); PG8_WAIT_L(0); PG8_BAR; PG8_MMA(0, 0, At, B0); PG8_MMA(0, 1, At, B1); PG8_BAR; PG8_SCHED;
;             PG8_LDA(At, 0, 1); PG8_STAGE(PG8_SB(0, 0), b2, voffB); PG8_STAGE(PG8_SB(0, 1), b2 + hstep, voffB); PG8_STAGE(PG8_SA(0, 0), a2, voffA);
;             PG8_WAIT_V(8); PG8_WAIT_L(0); PG8_BAR; PG8_MMA(1, 0, At, B0); PG8_MMA(1, 1, At, B1); PG8_BAR; PG8_SCHED;
.LBB0_990:
	s_add_i32 s73, s73, 2
	s_add_u32 s2, s60, s62
	s_addc_u32 s3, s61, s63
	s_add_u32 s20, s2, 0x100
	s_addc_u32 s21, s3, 0
	s_add_u32 s74, s71, s62
	s_addc_u32 s75, s72, s63
	s_add_i32 s76, 0, 0x10000
	s_cmpk_eq_i32 s62, 0xf00
	s_cselect_b64 vcc, -1, 0
	s_and_b64 s[2:3], vcc, exec
	s_cselect_b32 s21, s53, s21
	s_cselect_b32 s20, s67, s20
	v_add_u32_e32 v0, s76, v195
	s_cselect_b32 s3, s51, s75
	s_cselect_b32 s2, s70, s74
	s_add_i32 s77, 0, 0x14000
	ds_read_b128 v[154:157], v0
	ds_read_b128 v[158:161], v0 offset:1024
	ds_read_b128 v[162:165], v0 offset:2048
	ds_read_b128 v[166:169], v0 offset:3072
	v_add_u32_e32 v0, s77, v195
	ds_read_b128 v[170:173], v0
	ds_read_b128 v[174:177], v0 offset:1024
	ds_read_b128 v[184:187], v0 offset:2048
	ds_read_b128 v[188:191], v0 offset:3072
	v_lshl_add_u64 v[2:3], v[132:133], 0, s[62:63]
	s_add_i32 m0, s13, 0xc000
	ds_read_b128 v[198:201], v197
	ds_read_b128 v[202:205], v197 offset:1024
	ds_read_b128 v[206:209], v197 offset:2048
	ds_read_b128 v[210:213], v197 offset:3072
	ds_read_b128 v[214:217], v197 offset:4096
	ds_read_b128 v[218:221], v197 offset:5120
	ds_read_b128 v[236:239], v197 offset:6144
	ds_read_b128 v[240:243], v197 offset:7168
	global_load_lds_dwordx4 v[2:3], off
	v_lshl_add_u64 v[2:3], v[134:135], 0, s[62:63]
	s_add_i32 m0, s13, 0xe000
	s_nop 0
	global_load_lds_dwordx4 v[2:3], off
	s_waitcnt vmcnt(8)
	s_waitcnt lgkmcnt(0)
	s_setprio 1
	s_barrier
	v_mfma_f32_16x16x32_bf16 v[128:131], v[154:157], v[198:201], v[128:131]
	v_mfma_f32_16x16x32_bf16 v[124:127], v[162:165], v[198:201], v[124:127]
	v_mfma_f32_16x16x32_bf16 v[112:115], v[154:157], v[206:209], v[112:115]
	v_mfma_f32_16x16x32_bf16 v[108:111], v[162:165], v[206:209], v[108:111]
	v_mfma_f32_16x16x32_bf16 v[96:99], v[154:157], v[214:217], v[96:99]
	v_mfma_f32_16x16x32_bf16 v[92:95], v[162:165], v[214:217], v[92:95]
	v_mfma_f32_16x16x32_bf16 v[80:83], v[154:157], v[236:239], v[80:83]
	v_mfma_f32_16x16x32_bf16 v[76:79], v[162:165], v[236:239], v[76:79]
	v_mfma_f32_16x16x32_bf16 v[128:131], v[158:161], v[202:205], v[128:131]
	v_mfma_f32_16x16x32_bf16 v[124:127], v[166:169], v[202:205], v[124:127]
	v_mfma_f32_16x16x32_bf16 v[112:115], v[158:161], v[210:213], v[112:115]
	v_mfma_f32_16x16x32_bf16 v[108:111], v[166:169], v[210:213], v[108:111]
	v_mfma_f32_16x16x32_bf16 v[96:99], v[158:161], v[218:221], v[96:99]
	v_mfma_f32_16x16x32_bf16 v[92:95], v[166:169], v[218:221], v[92:95]
	v_mfma_f32_16x16x32_bf16 v[80:83], v[158:161], v[240:243], v[80:83]
	v_mfma_f32_16x16x32_bf16 v[76:79], v[166:169], v[240:243], v[76:79]
	s_setprio 0
	s_setprio 1
	v_mfma_f32_16x16x32_bf16 v[120:123], v[170:173], v[198:201], v[120:123]
	v_mfma_f32_16x16x32_bf16 v[116:119], v[184:187], v[198:201], v[116:119]
	v_mfma_f32_16x16x32_bf16 v[104:107], v[170:173], v[206:209], v[104:107]
	v_mfma_f32_16x16x32_bf16 v[100:103], v[184:187], v[206:209], v[100:103]
	v_mfma_f32_16x16x32_bf16 v[88:91], v[170:173], v[214:217], v[88:91]
	v_mfma_f32_16x16x32_bf16 v[84:87], v[184:187], v[214:217], v[84:87]
	v_mfma_f32_16x16x32_bf16 v[72:75], v[170:173], v[236:239], v[72:75]
	v_mfma_f32_16x16x32_bf16 v[68:71], v[184:187], v[236:239], v[68:71]
	v_mfma_f32_16x16x32_bf16 v[120:123], v[174:177], v[202:205], v[120:123]
	v_mfma_f32_16x16x32_bf16 v[116:119], v[188:191], v[202:205], v[116:119]
	v_mfma_f32_16x16x32_bf16 v[104:107], v[174:177], v[210:213], v[104:107]
	v_mfma_f32_16x16x32_bf16 v[100:103], v[188:191], v[210:213], v[100:103]
	v_mfma_f32_16x16x32_bf16 v[88:91], v[174:177], v[218:221], v[88:91]
	v_mfma_f32_16x16x32_bf16 v[84:87], v[188:191], v[218:221], v[84:87]
	v_mfma_f32_16x16x32_bf16 v[72:75], v[174:177], v[240:243], v[72:75]
	v_mfma_f32_16x16x32_bf16 v[68:71], v[188:191], v[240:243], v[68:71]
	s_barrier
	s_setprio 0
	s_add_i32 s74, s76, s14
	v_lshl_add_u64 v[138:139], s[2:3], 0, v[142:143]
	s_mov_b32 m0, s74
	ds_read_b128 v[198:201], v197 offset:16384
	ds_read_b128 v[202:205], v197 offset:17408
	ds_read_b128 v[206:209], v197 offset:18432
	ds_read_b128 v[210:213], v197 offset:19456
	ds_read_b128 v[214:217], v197 offset:20480
	ds_read_b128 v[218:221], v197 offset:21504
	ds_read_b128 v[236:239], v197 offset:22528
	ds_read_b128 v[240:243], v197 offset:23552
	global_load_lds_dwordx4 v[138:139], off
	s_add_i32 m0, s74, 0x2000
	s_add_u32 s74, s2, 0x80000
	v_lshl_add_u64 v[180:181], s[2:3], 0, v[146:147]
	s_addc_u32 s75, s3, 0
	s_add_i32 s76, s77, s14
	global_load_lds_dwordx4 v[180:181], off
	v_lshl_add_u64 v[2:3], s[74:75], 0, v[142:143]
	s_mov_b32 m0, s76
	v_lshl_add_u64 v[244:245], s[20:21], 0, v[140:141]
	global_load_lds_dwordx4 v[2:3], off
	v_lshl_add_u64 v[2:3], s[74:75], 0, v[146:147]
	s_add_i32 m0, s76, 0x2000
	v_lshl_add_u64 v[246:247], s[20:21], 0, v[144:145]
	global_load_lds_dwordx4 v[2:3], off
	s_mov_b32 m0, s13
	s_nop 0
	global_load_lds_dwordx4 v[244:245], off
	s_mov_b32 m0, s25
	s_nop 0
	global_load_lds_dwordx4 v[246:247], off
	s_waitcnt vmcnt(8)
	s_waitcnt lgkmcnt(0)
	s_setprio 1
	s_barrier
; #define PG8_STAGE(bufoff, gbase, voff) do { _Pragma("unroll") for (int _i = 0; _i < 2; ++_i) \
;         __builtin_amdgcn_global_load_lds((const unsigned*)((const char*)(gbase) + (voff)[_i]), (PG8_LAS unsigned*)(lds + (bufoff) + ldsw + _i * 8192), 16, 0, 0); } while (0)
; #define PG8_LDA(dst, b, h) do { _Pragma("unroll") for (int m = 0; m < 4; ++m) _Pragma("unroll") for (int k = 0; k < 2; ++k) dst[m][k] = *(const PG8_LAS bf16x8*)(lds + PG8_SA(b, h) + aoff + m * 2048 + k * 1024); } while (0)
; #define PG8_LDB(dst, b, h) do { _Pragma("unroll") for (int n = 0; n < 2; ++n) _Pragma("unroll") for (int k = 0; k < 2; ++k) dst[n][k] = *(const PG8_LAS bf16x8*)(lds + PG8_SB(b, h) + boff + n * 2048 + k * 1024); } while (0)
; #define PG8_MMA(ai, bj, At, Bt) do { __builtin_amdgcn_s_setprio(1); _Pragma("unroll") for (int m = 0; m < 4; ++m) _Pragma("unroll") for (int n = 0; n < 2; ++n) _Pragma("unroll") for (int k = 0; k < 2; ++k) \
;         acc[ai][bj][m][n] = __builtin_amdgcn_mfma_f32_16x16x32_bf16(Bt[n][k], At[m][k], acc[ai][bj][m][n], 0, 0, 0); __builtin_amdgcn_s_setprio(0); } while (0)
; #define PG8_WAIT_V(n) asm volatile("s_waitcnt vmcnt(" #n ")" ::: "memory")
; #define PG8_WAIT_L(n) asm volatile("s_waitcnt lgkmcnt(" #n ")" ::: "memory")
; #define PG8_BAR __builtin_amdgcn_s_barrier()
; #define PG8_SCHED __builtin_amdgcn_sched_barrier(0)
; template <class Epi, class Sched, bool ALIGN_EPI = true, bool SP2 = true, bool GS = false>
; __device__ __forceinline__ void gemm_phase(PG8_LAS unsigned char* lds, const Gemm g, const Sched& S, const Epi& E, const float* gs_ss = nullptr) {
;     ...
;             PG8_WAIT_V(8); PG8_WAIT_L(0); PG8_BAR; PG8_MMA(1, 0, At, B0); PG8_MMA(1, 1, At, B1); PG8_BAR; PG8_SCHED;
;             PG8_LDB(B0, 1, 0); PG8_LDB(B1, 1, 1); PG8_SCHED; PG8_LDA(At, 1, 0); PG8_STAGE(PG8_SA(0, 1), a2 + hstep, voffA);
;             PG8_WAIT_V(8); PG8_WAIT_L(0); PG8_BAR; PG8_MMA(0, 0, At, B0); PG8_MMA(0, 1, At, B1); PG8_BAR; PG8_SCHED;
	v_mfma_f32_16x16x32_bf16 v[64:67], v[154:157], v[198:201], v[64:67]
	v_mfma_f32_16x16x32_bf16 v[60:63], v[162:165], v[198:201], v[60:63]
	v_mfma_f32_16x16x32_bf16 v[48:51], v[154:157], v[206:209], v[48:51]
	v_mfma_f32_16x16x32_bf16 v[44:47], v[162:165], v[206:209], v[44:47]
	v_mfma_f32_16x16x32_bf16 v[32:35], v[154:157], v[214:217], v[32:35]
	v_mfma_f32_16x16x32_bf16 v[28:31], v[162:165], v[214:217], v[28:31]
	v_mfma_f32_16x16x32_bf16 v[16:19], v[154:157], v[236:239], v[16:19]
	v_mfma_f32_16x16x32_bf16 v[12:15], v[162:165], v[236:239], v[12:15]
	v_mfma_f32_16x16x32_bf16 v[64:67], v[158:161], v[202:205], v[64:67]
	v_mfma_f32_16x16x32_bf16 v[60:63], v[166:169], v[202:205], v[60:63]
	v_mfma_f32_16x16x32_bf16 v[48:51], v[158:161], v[210:213], v[48:51]
	v_mfma_f32_16x16x32_bf16 v[44:47], v[166:169], v[210:213], v[44:47]
	v_mfma_f32_16x16x32_bf16 v[32:35], v[158:161], v[218:221], v[32:35]
	v_mfma_f32_16x16x32_bf16 v[28:31], v[166:169], v[218:221], v[28:31]
	v_mfma_f32_16x16x32_bf16 v[16:19], v[158:161], v[240:243], v[16:19]
	v_mfma_f32_16x16x32_bf16 v[12:15], v[166:169], v[240:243], v[12:15]
	s_setprio 0
	s_setprio 1
	v_mfma_f32_16x16x32_bf16 v[56:59], v[170:173], v[198:201], v[56:59]
	v_mfma_f32_16x16x32_bf16 v[52:55], v[184:187], v[198:201], v[52:55]
	v_mfma_f32_16x16x32_bf16 v[40:43], v[170:173], v[206:209], v[40:43]
	v_mfma_f32_16x16x32_bf16 v[36:39], v[184:187], v[206:209], v[36:39]
	v_mfma_f32_16x16x32_bf16 v[24:27], v[170:173], v[214:217], v[24:27]
	v_mfma_f32_16x16x32_bf16 v[20:23], v[184:187], v[214:217], v[20:23]
	v_mfma_f32_16x16x32_bf16 v[8:11], v[170:173], v[236:239], v[8:11]
	v_mfma_f32_16x16x32_bf16 v[2:5], v[184:187], v[236:239], v[4:7]
	v_mfma_f32_16x16x32_bf16 v[56:59], v[174:177], v[202:205], v[56:59]
	v_mfma_f32_16x16x32_bf16 v[52:55], v[188:191], v[202:205], v[52:55]
	v_mfma_f32_16x16x32_bf16 v[40:43], v[174:177], v[210:213], v[40:43]
	v_mfma_f32_16x16x32_bf16 v[36:39], v[188:191], v[210:213], v[36:39]
	v_mfma_f32_16x16x32_bf16 v[24:27], v[174:177], v[218:221], v[24:27]
	v_mfma_f32_16x16x32_bf16 v[20:23], v[188:191], v[218:221], v[20:23]
	v_mfma_f32_16x16x32_bf16 v[8:11], v[174:177], v[240:243], v[8:11]
	v_mfma_f32_16x16x32_bf16 v[2:5], v[188:191], v[240:243], v[2:5]
	s_barrier
	s_setprio 0
	s_add_i32 s74, 0, 0x18000
	v_add_u32_e32 v0, s74, v195
	s_add_i32 s75, 0, 0x1c000
	ds_read_b128 v[154:157], v0
	ds_read_b128 v[158:161], v0 offset:1024
	ds_read_b128 v[162:165], v0 offset:2048
	ds_read_b128 v[166:169], v0 offset:3072
	v_add_u32_e32 v0, s75, v195
	ds_read_b128 v[170:173], v0
	ds_read_b128 v[174:177], v0 offset:1024
	ds_read_b128 v[184:187], v0 offset:2048
	ds_read_b128 v[188:191], v0 offset:3072
	s_add_u32 s20, s20, 0x80000
	s_addc_u32 s21, s21, 0
	s_mov_b32 m0, s30
	v_lshl_add_u64 v[6:7], s[20:21], 0, v[140:141]
	ds_read_b128 v[198:201], v197 offset:32768
	ds_read_b128 v[202:205], v197 offset:33792
	ds_read_b128 v[206:209], v197 offset:34816
	ds_read_b128 v[210:213], v197 offset:35840
	ds_read_b128 v[214:217], v197 offset:36864
	ds_read_b128 v[218:221], v197 offset:37888
	ds_read_b128 v[236:239], v197 offset:38912
	ds_read_b128 v[240:243], v197 offset:39936
	global_load_lds_dwordx4 v[6:7], off
	v_lshl_add_u64 v[6:7], s[20:21], 0, v[144:145]
	s_mov_b32 m0, s36
	s_nop 0
	global_load_lds_dwordx4 v[6:7], off
	s_waitcnt vmcnt(8)
	s_waitcnt lgkmcnt(0)
	s_setprio 1
	s_barrier
	v_mfma_f32_16x16x32_bf16 v[128:131], v[154:157], v[198:201], v[128:131]
	v_mfma_f32_16x16x32_bf16 v[124:127], v[162:165], v[198:201], v[124:127]
	v_mfma_f32_16x16x32_bf16 v[112:115], v[154:157], v[206:209], v[112:115]
	v_mfma_f32_16x16x32_bf16 v[108:111], v[162:165], v[206:209], v[108:111]
	v_mfma_f32_16x16x32_bf16 v[96:99], v[154:157], v[214:217], v[96:99]
	v_mfma_f32_16x16x32_bf16 v[92:95], v[162:165], v[214:217], v[92:95]
	v_mfma_f32_16x16x32_bf16 v[80:83], v[154:157], v[236:239], v[80:83]
	v_mfma_f32_16x16x32_bf16 v[76:79], v[162:165], v[236:239], v[76:79]
	v_mfma_f32_16x16x32_bf16 v[128:131], v[158:161], v[202:205], v[128:131]
	v_mfma_f32_16x16x32_bf16 v[124:127], v[166:169], v[202:205], v[124:127]
	v_mfma_f32_16x16x32_bf16 v[112:115], v[158:161], v[210:213], v[112:115]
	v_mfma_f32_16x16x32_bf16 v[108:111], v[166:169], v[210:213], v[108:111]
	v_mfma_f32_16x16x32_bf16 v[96:99], v[158:161], v[218:221], v[96:99]
	v_mfma_f32_16x16x32_bf16 v[92:95], v[166:169], v[218:221], v[92:95]
	v_mfma_f32_16x16x32_bf16 v[80:83], v[158:161], v[240:243], v[80:83]
	v_mfma_f32_16x16x32_bf16 v[76:79], v[166:169], v[240:243], v[76:79]
	s_setprio 0
	s_setprio 1
	v_mfma_f32_16x16x32_bf16 v[120:123], v[170:173], v[198:201], v[120:123]
	v_mfma_f32_16x16x32_bf16 v[116:119], v[184:187], v[198:201], v[116:119]
	v_mfma_f32_16x16x32_bf16 v[104:107], v[170:173], v[206:209], v[104:107]
	v_mfma_f32_16x16x32_bf16 v[100:103], v[184:187], v[206:209], v[100:103]
	v_mfma_f32_16x16x32_bf16 v[88:91], v[170:173], v[214:217], v[88:91]
	v_mfma_f32_16x16x32_bf16 v[84:87], v[184:187], v[214:217], v[84:87]
	v_mfma_f32_16x16x32_bf16 v[72:75], v[170:173], v[236:239], v[72:75]
	v_mfma_f32_16x16x32_bf16 v[68:71], v[184:187], v[236:239], v[68:71]
	v_mfma_f32_16x16x32_bf16 v[120:123], v[174:177], v[202:205], v[120:123]
	v_mfma_f32_16x16x32_bf16 v[116:119], v[188:191], v[202:205], v[116:119]
	v_mfma_f32_16x16x32_bf16 v[104:107], v[174:177], v[210:213], v[104:107]
	v_mfma_f32_16x16x32_bf16 v[100:103], v[188:191], v[210:213], v[100:103]
	v_mfma_f32_16x16x32_bf16 v[88:91], v[174:177], v[218:221], v[88:91]
	v_mfma_f32_16x16x32_bf16 v[84:87], v[188:191], v[218:221], v[84:87]
	v_mfma_f32_16x16x32_bf16 v[72:75], v[174:177], v[240:243], v[72:75]
	v_mfma_f32_16x16x32_bf16 v[68:71], v[188:191], v[240:243], v[68:71]
	s_barrier
; #define PG8_STAGE(bufoff, gbase, voff) do { _Pragma("unroll") for (int _i = 0; _i < 2; ++_i) \
;         __builtin_amdgcn_global_load_lds((const unsigned*)((const char*)(gbase) + (voff)[_i]), (PG8_LAS unsigned*)(lds + (bufoff) + ldsw + _i * 8192), 16, 0, 0); } while (0)
; #define PG8_LDA(dst, b, h) do { _Pragma("unroll") for (int m = 0; m < 4; ++m) _Pragma("unroll") for (int k = 0; k < 2; ++k) dst[m][k] = *(const PG8_LAS bf16x8*)(lds + PG8_SA(b, h) + aoff + m * 2048 + k * 1024); } while (0)
; #define PG8_MMA(ai, bj, At, Bt) do { __builtin_amdgcn_s_setprio(1); _Pragma("unroll") for (int m = 0; m < 4; ++m) _Pragma("unroll") for (int n = 0; n < 2; ++n) _Pragma("unroll") for (int k = 0; k < 2; ++k) \
;         acc[ai][bj][m][n] = __builtin_amdgcn_mfma_f32_16x16x32_bf16(Bt[n][k], At[m][k], acc[ai][bj][m][n], 0, 0, 0); __builtin_amdgcn_s_setprio(0); } while (0)
; #define PG8_WAIT_V(n) asm volatile("s_waitcnt vmcnt(" #n ")" ::: "memory")
; #define PG8_WAIT_L(n) asm volatile("s_waitcnt lgkmcnt(" #n ")" ::: "memory")
; #define PG8_BAR __builtin_amdgcn_s_barrier()
; #define PG8_SCHED __builtin_amdgcn_sched_barrier(0)
; template <class Epi, class Sched, bool ALIGN_EPI = true, bool SP2 = true, bool GS = false>
; __device__ __forceinline__ void gemm_phase(PG8_LAS unsigned char* lds, const Gemm g, const Sched& S, const Epi& E, const float* gs_ss = nullptr) {
;     ...
;             PG8_LDA(At, 1, 1); PG8_STAGE(PG8_SB(1, 0), b3, voffB); PG8_STAGE(PG8_SB(1, 1), b3 + hstep, voffB); PG8_STAGE(PG8_SA(1, 0), a3, voffA);
;             PG8_WAIT_V(8); PG8_WAIT_L(0); PG8_BAR; PG8_MMA(1, 0, At, B0); PG8_MMA(1, 1, At, B1); PG8_BAR; PG8_SCHED;
	s_setprio 0
	s_add_i32 s20, s74, s14
	v_lshl_add_u64 v[6:7], v[138:139], 0, s[26:27]
	s_mov_b32 m0, s20
	ds_read_b128 v[198:201], v197 offset:49152
	ds_read_b128 v[202:205], v197 offset:50176
	ds_read_b128 v[206:209], v197 offset:51200
	ds_read_b128 v[210:213], v197 offset:52224
	ds_read_b128 v[214:217], v197 offset:53248
	ds_read_b128 v[218:221], v197 offset:54272
	ds_read_b128 v[236:239], v197 offset:55296
	ds_read_b128 v[240:243], v197 offset:56320
	global_load_lds_dwordx4 v[6:7], off
	s_add_i32 m0, s20, 0x2000
	s_add_u32 s2, s2, 0x80080
	v_lshl_add_u64 v[6:7], v[180:181], 0, s[26:27]
	s_addc_u32 s3, s3, 0
	s_add_i32 s20, s75, s14
	global_load_lds_dwordx4 v[6:7], off
	v_lshl_add_u64 v[6:7], s[2:3], 0, v[142:143]
	s_mov_b32 m0, s20
	s_nop 0
	global_load_lds_dwordx4 v[6:7], off
	v_lshl_add_u64 v[6:7], s[2:3], 0, v[146:147]
	s_add_i32 m0, s20, 0x2000
	s_nop 0
	global_load_lds_dwordx4 v[6:7], off
	v_lshl_add_u64 v[6:7], v[244:245], 0, s[26:27]
	s_mov_b32 m0, s59
	s_nop 0
	global_load_lds_dwordx4 v[6:7], off
	v_lshl_add_u64 v[6:7], v[246:247], 0, s[26:27]
	s_mov_b32 m0, s64
	s_nop 0
	global_load_lds_dwordx4 v[6:7], off
	s_waitcnt vmcnt(8)
	s_waitcnt lgkmcnt(0)
	s_setprio 1
	s_barrier
	v_mfma_f32_16x16x32_bf16 v[64:67], v[154:157], v[198:201], v[64:67]
	v_mfma_f32_16x16x32_bf16 v[60:63], v[162:165], v[198:201], v[60:63]
	v_mfma_f32_16x16x32_bf16 v[48:51], v[154:157], v[206:209], v[48:51]
	v_mfma_f32_16x16x32_bf16 v[44:47], v[162:165], v[206:209], v[44:47]
	v_mfma_f32_16x16x32_bf16 v[32:35], v[154:157], v[214:217], v[32:35]
	v_mfma_f32_16x16x32_bf16 v[28:31], v[162:165], v[214:217], v[28:31]
	v_mfma_f32_16x16x32_bf16 v[16:19], v[154:157], v[236:239], v[16:19]
	v_mfma_f32_16x16x32_bf16 v[12:15], v[162:165], v[236:239], v[12:15]
	v_mfma_f32_16x16x32_bf16 v[64:67], v[158:161], v[202:205], v[64:67]
	v_mfma_f32_16x16x32_bf16 v[60:63], v[166:169], v[202:205], v[60:63]
	v_mfma_f32_16x16x32_bf16 v[48:51], v[158:161], v[210:213], v[48:51]
	v_mfma_f32_16x16x32_bf16 v[44:47], v[166:169], v[210:213], v[44:47]
	v_mfma_f32_16x16x32_bf16 v[32:35], v[158:161], v[218:221], v[32:35]
	v_mfma_f32_16x16x32_bf16 v[28:31], v[166:169], v[218:221], v[28:31]
	v_mfma_f32_16x16x32_bf16 v[16:19], v[158:161], v[240:243], v[16:19]
	v_mfma_f32_16x16x32_bf16 v[12:15], v[166:169], v[240:243], v[12:15]
	s_setprio 0
	s_setprio 1
	v_mfma_f32_16x16x32_bf16 v[56:59], v[170:173], v[198:201], v[56:59]
	v_mfma_f32_16x16x32_bf16 v[52:55], v[184:187], v[198:201], v[52:55]
	v_mfma_f32_16x16x32_bf16 v[40:43], v[170:173], v[206:209], v[40:43]
	v_mfma_f32_16x16x32_bf16 v[36:39], v[184:187], v[206:209], v[36:39]
	v_mfma_f32_16x16x32_bf16 v[24:27], v[170:173], v[214:217], v[24:27]
	v_mfma_f32_16x16x32_bf16 v[20:23], v[184:187], v[214:217], v[20:23]
	v_mfma_f32_16x16x32_bf16 v[6:9], v[170:173], v[236:239], v[8:11]
	v_mfma_f32_16x16x32_bf16 v[2:5], v[184:187], v[236:239], v[2:5]
	v_mfma_f32_16x16x32_bf16 v[56:59], v[174:177], v[202:205], v[56:59]
	v_mfma_f32_16x16x32_bf16 v[52:55], v[188:191], v[202:205], v[52:55]
	v_mfma_f32_16x16x32_bf16 v[40:43], v[174:177], v[210:213], v[40:43]
	v_mfma_f32_16x16x32_bf16 v[36:39], v[188:191], v[210:213], v[36:39]
	v_mfma_f32_16x16x32_bf16 v[24:27], v[174:177], v[218:221], v[24:27]
	v_mfma_f32_16x16x32_bf16 v[20:23], v[188:191], v[218:221], v[20:23]
	v_mfma_f32_16x16x32_bf16 v[8:11], v[174:177], v[240:243], v[6:9]
	v_mfma_f32_16x16x32_bf16 v[4:7], v[188:191], v[240:243], v[2:5]
	s_barrier
	s_setprio 0
	s_and_b32 s2, s73, 6
	s_cmp_lg_u32 s2, 6
	s_cselect_b64 s[2:3], -1, 0
	s_or_b64 s[2:3], vcc, s[2:3]
	s_and_b64 vcc, exec, s[2:3]
	s_cbranch_vccnz .LBB0_989
	s_and_b32 s2, s62, 0xc00
	v_add_u32_e32 v137, s2, v136
	v_add_u32_e32 v154, 0x400, v137
	ds_read2_b32 v[2:3], v137 offset1:16
	ds_read2_b32 v[138:139], v154 offset1:16
	s_waitcnt lgkmcnt(0)
	v_div_scale_f32 v0, s[2:3], v138, v138, v2
	v_rcp_f32_e32 v155, v0
	v_div_scale_f32 v156, vcc, v2, v138, v2
	v_fma_f32 v157, -v0, v155, 1.0
	v_fmac_f32_e32 v155, v157, v155
	v_mul_f32_e32 v157, v156, v155
	v_fma_f32 v158, -v0, v157, v156
	v_fmac_f32_e32 v157, v158, v155
	v_fma_f32 v0, -v0, v157, v156
	v_div_fmas_f32 v0, v0, v155, v157
	v_div_fixup_f32 v0, v0, v138, v2
	v_div_scale_f32 v2, s[2:3], v139, v139, v3
	v_rcp_f32_e32 v138, v2
	v_pk_mul_f32 v[130:131], v[130:131], v[0:1] op_sel_hi:[1,0]
	v_pk_mul_f32 v[128:129], v[128:129], v[0:1] op_sel_hi:[1,0]
	v_pk_mul_f32 v[126:127], v[126:127], v[0:1] op_sel_hi:[1,0]
	v_pk_mul_f32 v[124:125], v[124:125], v[0:1] op_sel_hi:[1,0]
	v_pk_mul_f32 v[122:123], v[122:123], v[0:1] op_sel_hi:[1,0]
	v_pk_mul_f32 v[120:121], v[120:121], v[0:1] op_sel_hi:[1,0]
	v_pk_mul_f32 v[118:119], v[118:119], v[0:1] op_sel_hi:[1,0]
	v_pk_mul_f32 v[116:117], v[116:117], v[0:1] op_sel_hi:[1,0]
	v_fma_f32 v0, -v2, v138, 1.0
	v_fmac_f32_e32 v138, v0, v138
	v_div_scale_f32 v0, vcc, v3, v139, v3
	v_mul_f32_e32 v155, v0, v138
	v_fma_f32 v156, -v2, v155, v0
	v_fmac_f32_e32 v155, v156, v138
	v_fma_f32 v0, -v2, v155, v0
	v_div_fmas_f32 v0, v0, v138, v155
	v_div_fixup_f32 v0, v0, v139, v3
	ds_read2_b32 v[2:3], v137 offset0:32 offset1:48
	ds_read2_b32 v[138:139], v154 offset0:32 offset1:48
	v_pk_mul_f32 v[114:115], v[114:115], v[0:1] op_sel_hi:[1,0]
	v_pk_mul_f32 v[112:113], v[112:113], v[0:1] op_sel_hi:[1,0]
	v_pk_mul_f32 v[110:111], v[110:111], v[0:1] op_sel_hi:[1,0]
	v_pk_mul_f32 v[108:109], v[108:109], v[0:1] op_sel_hi:[1,0]
	s_waitcnt lgkmcnt(0)
	v_div_scale_f32 v155, s[2:3], v138, v138, v2
	v_rcp_f32_e32 v156, v155
	v_pk_mul_f32 v[106:107], v[106:107], v[0:1] op_sel_hi:[1,0]
	v_pk_mul_f32 v[104:105], v[104:105], v[0:1] op_sel_hi:[1,0]
	v_pk_mul_f32 v[102:103], v[102:103], v[0:1] op_sel_hi:[1,0]
	v_pk_mul_f32 v[100:101], v[100:101], v[0:1] op_sel_hi:[1,0]
	v_fma_f32 v0, -v155, v156, 1.0
	v_fmac_f32_e32 v156, v0, v156
	v_div_scale_f32 v0, vcc, v2, v138, v2
	v_mul_f32_e32 v157, v0, v156
	v_fma_f32 v158, -v155, v157, v0
	v_fmac_f32_e32 v157, v158, v156
	v_fma_f32 v0, -v155, v157, v0
	v_div_fmas_f32 v0, v0, v156, v157
	v_div_fixup_f32 v0, v0, v138, v2
	v_div_scale_f32 v2, s[2:3], v139, v139, v3
	v_rcp_f32_e32 v138, v2
	v_pk_mul_f32 v[98:99], v[98:99], v[0:1] op_sel_hi:[1,0]
	v_pk_mul_f32 v[96:97], v[96:97], v[0:1] op_sel_hi:[1,0]
	v_pk_mul_f32 v[94:95], v[94:95], v[0:1] op_sel_hi:[1,0]
	v_pk_mul_f32 v[92:93], v[92:93], v[0:1] op_sel_hi:[1,0]
	v_pk_mul_f32 v[90:91], v[90:91], v[0:1] op_sel_hi:[1,0]
	v_pk_mul_f32 v[88:89], v[88:89], v[0:1] op_sel_hi:[1,0]
	v_pk_mul_f32 v[86:87], v[86:87], v[0:1] op_sel_hi:[1,0]
	v_pk_mul_f32 v[84:85], v[84:85], v[0:1] op_sel_hi:[1,0]
	v_fma_f32 v0, -v2, v138, 1.0
	v_fmac_f32_e32 v138, v0, v138
	v_div_scale_f32 v0, vcc, v3, v139, v3
	v_mul_f32_e32 v155, v0, v138
	v_fma_f32 v156, -v2, v155, v0
	v_fmac_f32_e32 v155, v156, v138
	v_fma_f32 v0, -v2, v155, v0
	v_div_fmas_f32 v0, v0, v138, v155
	v_div_fixup_f32 v0, v0, v139, v3
	ds_read2_b32 v[2:3], v137 offset0:128 offset1:144
	ds_read2_b32 v[138:139], v154 offset0:128 offset1:144
	v_pk_mul_f32 v[82:83], v[82:83], v[0:1] op_sel_hi:[1,0]
	v_pk_mul_f32 v[80:81], v[80:81], v[0:1] op_sel_hi:[1,0]
	v_pk_mul_f32 v[78:79], v[78:79], v[0:1] op_sel_hi:[1,0]
	v_pk_mul_f32 v[76:77], v[76:77], v[0:1] op_sel_hi:[1,0]
	s_waitcnt lgkmcnt(0)
	v_div_scale_f32 v155, s[2:3], v138, v138, v2
	v_rcp_f32_e32 v156, v155
	v_pk_mul_f32 v[74:75], v[74:75], v[0:1] op_sel_hi:[1,0]
	v_pk_mul_f32 v[72:73], v[72:73], v[0:1] op_sel_hi:[1,0]
	v_pk_mul_f32 v[70:71], v[70:71], v[0:1] op_sel_hi:[1,0]
	v_pk_mul_f32 v[68:69], v[68:69], v[0:1] op_sel_hi:[1,0]
	v_fma_f32 v0, -v155, v156, 1.0
	v_fmac_f32_e32 v156, v0, v156
	v_div_scale_f32 v0, vcc, v2, v138, v2
	v_mul_f32_e32 v157, v0, v156
	v_fma_f32 v158, -v155, v157, v0
	v_fmac_f32_e32 v157, v158, v156
	v_fma_f32 v0, -v155, v157, v0
	v_div_fmas_f32 v0, v0, v156, v157
	v_div_fixup_f32 v0, v0, v138, v2
	v_div_scale_f32 v2, s[2:3], v139, v139, v3
	v_rcp_f32_e32 v138, v2
	v_pk_mul_f32 v[66:67], v[66:67], v[0:1] op_sel_hi:[1,0]
	v_pk_mul_f32 v[64:65], v[64:65], v[0:1] op_sel_hi:[1,0]
	v_pk_mul_f32 v[62:63], v[62:63], v[0:1] op_sel_hi:[1,0]
	v_pk_mul_f32 v[60:61], v[60:61], v[0:1] op_sel_hi:[1,0]
	v_pk_mul_f32 v[58:59], v[58:59], v[0:1] op_sel_hi:[1,0]
	v_pk_mul_f32 v[56:57], v[56:57], v[0:1] op_sel_hi:[1,0]
	v_pk_mul_f32 v[54:55], v[54:55], v[0:1] op_sel_hi:[1,0]
	v_pk_mul_f32 v[52:53], v[52:53], v[0:1] op_sel_hi:[1,0]
	v_fma_f32 v0, -v2, v138, 1.0
	v_fmac_f32_e32 v138, v0, v138
	v_div_scale_f32 v0, vcc, v3, v139, v3
	v_mul_f32_e32 v155, v0, v138
	v_fma_f32 v156, -v2, v155, v0
	v_fmac_f32_e32 v155, v156, v138
	v_fma_f32 v0, -v2, v155, v0
	v_div_fmas_f32 v0, v0, v138, v155
	v_div_fixup_f32 v0, v0, v139, v3
	ds_read2_b32 v[2:3], v137 offset0:160 offset1:176
	ds_read2_b32 v[138:139], v154 offset0:160 offset1:176
	v_pk_mul_f32 v[50:51], v[50:51], v[0:1] op_sel_hi:[1,0]
	v_pk_mul_f32 v[48:49], v[48:49], v[0:1] op_sel_hi:[1,0]
	v_pk_mul_f32 v[46:47], v[46:47], v[0:1] op_sel_hi:[1,0]
	v_pk_mul_f32 v[44:45], v[44:45], v[0:1] op_sel_hi:[1,0]
	s_waitcnt lgkmcnt(0)
	v_div_scale_f32 v137, s[2:3], v138, v138, v2
	v_rcp_f32_e32 v154, v137
	v_pk_mul_f32 v[42:43], v[42:43], v[0:1] op_sel_hi:[1,0]
	v_pk_mul_f32 v[40:41], v[40:41], v[0:1] op_sel_hi:[1,0]
	v_pk_mul_f32 v[38:39], v[38:39], v[0:1] op_sel_hi:[1,0]
	v_pk_mul_f32 v[36:37], v[36:37], v[0:1] op_sel_hi:[1,0]
	v_fma_f32 v0, -v137, v154, 1.0
	v_fmac_f32_e32 v154, v0, v154
	v_div_scale_f32 v0, vcc, v2, v138, v2
	v_mul_f32_e32 v155, v0, v154
	v_fma_f32 v156, -v137, v155, v0
	v_fmac_f32_e32 v155, v156, v154
	v_fma_f32 v0, -v137, v155, v0
	v_div_fmas_f32 v0, v0, v154, v155
	v_div_fixup_f32 v0, v0, v138, v2
	v_div_scale_f32 v2, s[2:3], v139, v139, v3
	v_rcp_f32_e32 v137, v2
	v_pk_mul_f32 v[34:35], v[34:35], v[0:1] op_sel_hi:[1,0]
	v_pk_mul_f32 v[32:33], v[32:33], v[0:1] op_sel_hi:[1,0]
	v_pk_mul_f32 v[30:31], v[30:31], v[0:1] op_sel_hi:[1,0]
	v_pk_mul_f32 v[28:29], v[28:29], v[0:1] op_sel_hi:[1,0]
	v_pk_mul_f32 v[26:27], v[26:27], v[0:1] op_sel_hi:[1,0]
	v_pk_mul_f32 v[24:25], v[24:25], v[0:1] op_sel_hi:[1,0]
	v_pk_mul_f32 v[22:23], v[22:23], v[0:1] op_sel_hi:[1,0]
	v_pk_mul_f32 v[20:21], v[20:21], v[0:1] op_sel_hi:[1,0]
	v_fma_f32 v0, -v2, v137, 1.0
	v_fmac_f32_e32 v137, v0, v137
	v_div_scale_f32 v0, vcc, v3, v139, v3
	v_mul_f32_e32 v138, v0, v137
	v_fma_f32 v154, -v2, v138, v0
	v_fmac_f32_e32 v138, v154, v137
	v_fma_f32 v0, -v2, v138, v0
	v_div_fmas_f32 v0, v0, v137, v138
	v_div_fixup_f32 v0, v0, v139, v3
	v_pk_mul_f32 v[18:19], v[18:19], v[0:1] op_sel_hi:[1,0]
	v_pk_mul_f32 v[16:17], v[16:17], v[0:1] op_sel_hi:[1,0]
	v_pk_mul_f32 v[14:15], v[14:15], v[0:1] op_sel_hi:[1,0]
	v_pk_mul_f32 v[12:13], v[12:13], v[0:1] op_sel_hi:[1,0]
	v_pk_mul_f32 v[10:11], v[10:11], v[0:1] op_sel_hi:[1,0]
	v_pk_mul_f32 v[8:9], v[8:9], v[0:1] op_sel_hi:[1,0]
	v_pk_mul_f32 v[6:7], v[6:7], v[0:1] op_sel_hi:[1,0]
	v_pk_mul_f32 v[4:5], v[4:5], v[0:1] op_sel_hi:[1,0]
	s_branch .LBB0_989

;     __device__ __forceinline__ size_t a_extra(const Unit& u) const { return (size_t)(u.pn >> 1) * ((size_t)T * 512 * 2); }
;     __device__ __forceinline__ size_t a_extra(const Unit& u) const { return (size_t)(u.pn >> 1) * 512 * 2; }
;     __device__ __forceinline__ size_t b_extra(const Unit& u) const { return (size_t)(u.pn >> 1) * 512 * 2 - (size_t)(u.pn & ~1) * ((size_t)256 * D * 2); }
; #define PG8_STAGE(bufoff, gbase, voff) do { _Pragma("unroll") for (int _i = 0; _i < 2; ++_i) \
;         __builtin_amdgcn_global_load_lds((const unsigned*)((const char*)(gbase) + (voff)[_i]), (PG8_LAS unsigned*)(lds + (bufoff) + ldsw + _i * 8192), 16, 0, 0); } while (0)
; #define PG8_LDA(dst, b, h) do { _Pragma("unroll") for (int m = 0; m < 4; ++m) _Pragma("unroll") for (int k = 0; k < 2; ++k) dst[m][k] = *(const PG8_LAS bf16x8*)(lds + PG8_SA(b, h) + aoff + m * 2048 + k * 1024); } while (0)
; #define PG8_WAIT_V(n) asm volatile("s_waitcnt vmcnt(" #n ")" ::: "memory")
; #define PG8_WAIT_L(n) asm volatile("s_waitcnt lgkmcnt(" #n ")" ::: "memory")
; template <class Epi, class Sched, bool ALIGN_EPI = true, bool SP2 = true, bool GS = false>
; __device__ __forceinline__ void gemm_phase(PG8_LAS unsigned char* lds, const Gemm g, const Sched& S, const Epi& E, const float* gs_ss = nullptr) {
;     ...
;         const char* nA = has_next ? (const char*)g.A + S.a_extra(nxt) + (size_t)nxt.pm * tstep : cA; const char* nB = has_next ? (const char*)g.Bt + S.b_extra(nxt) + (size_t)nxt.pn * tstep : cB;
;         for (int t = 0; t < nt; t += 2) {
;             const bool last = (t == nt - 2);
;             const char* a1 = cA + (size_t)(t + 1) * kstep;
;             const char* a2 = last ? nA : cA + (size_t)(t + 2) * kstep; const char* b2 = last ? nB : cB + (size_t)(t + 2) * kstep;
;             const char* a3 = a2 + kstep; const char* b3 = b2 + kstep;
;             if constexpr (SP2) {
;             PG8_LDB(B0, 0, 0); PG8_LDB(B1, 0, 1); PG8_SCHED; PG8_LDA(At, 0, 0); PG8_STAGE(PG8_SA(1, 1), a1 + hstep, voffA);
;             PG8_WAIT_V(8); PG8_WAIT_L(0); PG8_BAR; PG8_MMA(0, 0, At, B0); PG8_MMA(0, 1, At, B1); PG8_BAR; PG8_SCHED;
;             PG8_LDA(At, 0, 1); PG8_STAGE(PG8_SB(0, 0), b2, voffB); PG8_STAGE(PG8_SB(0, 1), b2 + hstep, voffB); PG8_STAGE(PG8_SA(0, 0), a2, voffA);
;             PG8_WAIT_V(8); PG8_WAIT_L(0); PG8_BAR; PG8_MMA(1, 0, At, B0); PG8_MMA(1, 1, At, B1); PG8_BAR; PG8_SCHED;
.LBB0_1036:
	s_add_i32 s75, s75, 2
	s_add_u32 s2, s58, s60
	s_addc_u32 s3, s59, s61
	s_add_u32 s20, s2, 0x100
	s_addc_u32 s21, s3, 0
	s_add_u32 vcc_lo, s73, s60
	s_addc_u32 vcc_hi, s74, s61
	s_add_i32 s76, 0, 0x10000
	s_cmpk_eq_i32 s60, 0xf00
	s_cselect_b64 s[62:63], -1, 0
	s_and_b64 s[2:3], s[62:63], exec
	s_cselect_b32 s21, s51, s21
	s_cselect_b32 s20, s71, s20
	v_add_u32_e32 v0, s76, v188
	s_cselect_b32 s3, s49, vcc_hi
	s_cselect_b32 s2, s72, vcc_lo
	s_add_i32 s77, 0, 0x14000
	ds_read_b128 v[138:141], v0
	ds_read_b128 v[142:145], v0 offset:1024
	ds_read_b128 v[162:165], v0 offset:2048
	ds_read_b128 v[166:169], v0 offset:3072
	v_add_u32_e32 v0, s77, v188
	ds_read_b128 v[170:173], v0
	ds_read_b128 v[184:187], v0 offset:1024
	ds_read_b128 v[192:195], v0 offset:2048
	ds_read_b128 v[196:199], v0 offset:3072
	v_lshl_add_u64 v[2:3], v[132:133], 0, s[60:61]
	s_add_i32 m0, s13, 0xc000
	ds_read_b128 v[200:203], v190
	ds_read_b128 v[204:207], v190 offset:1024
	ds_read_b128 v[208:211], v190 offset:2048
	ds_read_b128 v[212:215], v190 offset:3072
	ds_read_b128 v[216:219], v190 offset:4096
	ds_read_b128 v[236:239], v190 offset:5120
	ds_read_b128 v[240:243], v190 offset:6144
	ds_read_b128 v[244:247], v190 offset:7168
	global_load_lds_dwordx4 v[2:3], off
	v_lshl_add_u64 v[2:3], v[134:135], 0, s[60:61]
	s_add_i32 m0, s13, 0xe000
	s_nop 0
	global_load_lds_dwordx4 v[2:3], off
	s_waitcnt vmcnt(8)
	s_waitcnt lgkmcnt(0)
	s_setprio 1
	s_barrier
	v_mfma_f32_16x16x32_bf16 v[128:131], v[138:141], v[200:203], v[128:131]
	v_mfma_f32_16x16x32_bf16 v[124:127], v[162:165], v[200:203], v[124:127]
	v_mfma_f32_16x16x32_bf16 v[112:115], v[138:141], v[208:211], v[112:115]
	v_mfma_f32_16x16x32_bf16 v[108:111], v[162:165], v[208:211], v[108:111]
	v_mfma_f32_16x16x32_bf16 v[96:99], v[138:141], v[216:219], v[96:99]
	v_mfma_f32_16x16x32_bf16 v[92:95], v[162:165], v[216:219], v[92:95]
	v_mfma_f32_16x16x32_bf16 v[80:83], v[138:141], v[240:243], v[80:83]
	v_mfma_f32_16x16x32_bf16 v[76:79], v[162:165], v[240:243], v[76:79]
	v_mfma_f32_16x16x32_bf16 v[128:131], v[142:145], v[204:207], v[128:131]
	v_mfma_f32_16x16x32_bf16 v[124:127], v[166:169], v[204:207], v[124:127]
	v_mfma_f32_16x16x32_bf16 v[112:115], v[142:145], v[212:215], v[112:115]
	v_mfma_f32_16x16x32_bf16 v[108:111], v[166:169], v[212:215], v[108:111]
	v_mfma_f32_16x16x32_bf16 v[96:99], v[142:145], v[236:239], v[96:99]
	v_mfma_f32_16x16x32_bf16 v[92:95], v[166:169], v[236:239], v[92:95]
	v_mfma_f32_16x16x32_bf16 v[80:83], v[142:145], v[244:247], v[80:83]
	v_mfma_f32_16x16x32_bf16 v[76:79], v[166:169], v[244:247], v[76:79]
	s_setprio 0
	s_setprio 1
	v_mfma_f32_16x16x32_bf16 v[120:123], v[170:173], v[200:203], v[120:123]
	v_mfma_f32_16x16x32_bf16 v[116:119], v[192:195], v[200:203], v[116:119]
	v_mfma_f32_16x16x32_bf16 v[104:107], v[170:173], v[208:211], v[104:107]
	v_mfma_f32_16x16x32_bf16 v[100:103], v[192:195], v[208:211], v[100:103]
	v_mfma_f32_16x16x32_bf16 v[88:91], v[170:173], v[216:219], v[88:91]
	v_mfma_f32_16x16x32_bf16 v[84:87], v[192:195], v[216:219], v[84:87]
	v_mfma_f32_16x16x32_bf16 v[72:75], v[170:173], v[240:243], v[72:75]
	v_mfma_f32_16x16x32_bf16 v[68:71], v[192:195], v[240:243], v[68:71]
	v_mfma_f32_16x16x32_bf16 v[120:123], v[184:187], v[204:207], v[120:123]
	v_mfma_f32_16x16x32_bf16 v[116:119], v[196:199], v[204:207], v[116:119]
	v_mfma_f32_16x16x32_bf16 v[104:107], v[184:187], v[212:215], v[104:107]
	v_mfma_f32_16x16x32_bf16 v[100:103], v[196:199], v[212:215], v[100:103]
	v_mfma_f32_16x16x32_bf16 v[88:91], v[184:187], v[236:239], v[88:91]
	v_mfma_f32_16x16x32_bf16 v[84:87], v[196:199], v[236:239], v[84:87]
	v_mfma_f32_16x16x32_bf16 v[72:75], v[184:187], v[244:247], v[72:75]
	v_mfma_f32_16x16x32_bf16 v[68:71], v[196:199], v[244:247], v[68:71]
	s_barrier
	s_setprio 0
	s_add_i32 s76, s76, s14
	v_lshl_add_u64 v[146:147], s[2:3], 0, v[150:151]
	s_mov_b32 m0, s76
	ds_read_b128 v[200:203], v190 offset:16384
	ds_read_b128 v[204:207], v190 offset:17408
	ds_read_b128 v[208:211], v190 offset:18432
	ds_read_b128 v[212:215], v190 offset:19456
	ds_read_b128 v[216:219], v190 offset:20480
	ds_read_b128 v[236:239], v190 offset:21504
	ds_read_b128 v[240:243], v190 offset:22528
	ds_read_b128 v[244:247], v190 offset:23552
	global_load_lds_dwordx4 v[146:147], off
	s_add_i32 m0, s76, 0x2000
	s_add_u32 vcc_lo, s2, 0x80000
	v_lshl_add_u64 v[174:175], s[2:3], 0, v[154:155]
	s_addc_u32 vcc_hi, s3, 0
	s_add_i32 s76, s77, s14
	global_load_lds_dwordx4 v[174:175], off
	v_lshl_add_u64 v[2:3], vcc, 0, v[150:151]
	s_mov_b32 m0, s76
	v_lshl_add_u64 v[180:181], s[20:21], 0, v[148:149]
	global_load_lds_dwordx4 v[2:3], off
	v_lshl_add_u64 v[2:3], vcc, 0, v[154:155]
	s_add_i32 m0, s76, 0x2000
	v_lshl_add_u64 v[220:221], s[20:21], 0, v[152:153]
	global_load_lds_dwordx4 v[2:3], off
	s_mov_b32 m0, s13
	s_nop 0
	global_load_lds_dwordx4 v[180:181], off
	s_mov_b32 m0, s25
	s_nop 0
	global_load_lds_dwordx4 v[220:221], off
	s_waitcnt vmcnt(8)
	s_waitcnt lgkmcnt(0)
	s_setprio 1
	s_barrier
; #define PG8_STAGE(bufoff, gbase, voff) do { _Pragma("unroll") for (int _i = 0; _i < 2; ++_i) \
;         __builtin_amdgcn_global_load_lds((const unsigned*)((const char*)(gbase) + (voff)[_i]), (PG8_LAS unsigned*)(lds + (bufoff) + ldsw + _i * 8192), 16, 0, 0); } while (0)
; #define PG8_LDA(dst, b, h) do { _Pragma("unroll") for (int m = 0; m < 4; ++m) _Pragma("unroll") for (int k = 0; k < 2; ++k) dst[m][k] = *(const PG8_LAS bf16x8*)(lds + PG8_SA(b, h) + aoff + m * 2048 + k * 1024); } while (0)
; #define PG8_LDB(dst, b, h) do { _Pragma("unroll") for (int n = 0; n < 2; ++n) _Pragma("unroll") for (int k = 0; k < 2; ++k) dst[n][k] = *(const PG8_LAS bf16x8*)(lds + PG8_SB(b, h) + boff + n * 2048 + k * 1024); } while (0)
; #define PG8_MMA(ai, bj, At, Bt) do { __builtin_amdgcn_s_setprio(1); _Pragma("unroll") for (int m = 0; m < 4; ++m) _Pragma("unroll") for (int n = 0; n < 2; ++n) _Pragma("unroll") for (int k = 0; k < 2; ++k) \
;         acc[ai][bj][m][n] = __builtin_amdgcn_mfma_f32_16x16x32_bf16(Bt[n][k], At[m][k], acc[ai][bj][m][n], 0, 0, 0); __builtin_amdgcn_s_setprio(0); } while (0)
; #define PG8_WAIT_V(n) asm volatile("s_waitcnt vmcnt(" #n ")" ::: "memory")
; #define PG8_WAIT_L(n) asm volatile("s_waitcnt lgkmcnt(" #n ")" ::: "memory")
; #define PG8_BAR __builtin_amdgcn_s_barrier()
; #define PG8_SCHED __builtin_amdgcn_sched_barrier(0)
; template <class Epi, class Sched, bool ALIGN_EPI = true, bool SP2 = true, bool GS = false>
; __device__ __forceinline__ void gemm_phase(PG8_LAS unsigned char* lds, const Gemm g, const Sched& S, const Epi& E, const float* gs_ss = nullptr) {
;     ...
;             PG8_WAIT_V(8); PG8_WAIT_L(0); PG8_BAR; PG8_MMA(1, 0, At, B0); PG8_MMA(1, 1, At, B1); PG8_BAR; PG8_SCHED;
;             PG8_LDB(B0, 1, 0); PG8_LDB(B1, 1, 1); PG8_SCHED; PG8_LDA(At, 1, 0); PG8_STAGE(PG8_SA(0, 1), a2 + hstep, voffA);
;             PG8_WAIT_V(8); PG8_WAIT_L(0); PG8_BAR; PG8_MMA(0, 0, At, B0); PG8_MMA(0, 1, At, B1); PG8_BAR; PG8_SCHED;
	v_mfma_f32_16x16x32_bf16 v[64:67], v[138:141], v[200:203], v[64:67]
	v_mfma_f32_16x16x32_bf16 v[60:63], v[162:165], v[200:203], v[60:63]
	v_mfma_f32_16x16x32_bf16 v[48:51], v[138:141], v[208:211], v[48:51]
	v_mfma_f32_16x16x32_bf16 v[44:47], v[162:165], v[208:211], v[44:47]
	v_mfma_f32_16x16x32_bf16 v[32:35], v[138:141], v[216:219], v[32:35]
	v_mfma_f32_16x16x32_bf16 v[28:31], v[162:165], v[216:219], v[28:31]
	v_mfma_f32_16x16x32_bf16 v[16:19], v[138:141], v[240:243], v[16:19]
	v_mfma_f32_16x16x32_bf16 v[12:15], v[162:165], v[240:243], v[12:15]
	v_mfma_f32_16x16x32_bf16 v[64:67], v[142:145], v[204:207], v[64:67]
	v_mfma_f32_16x16x32_bf16 v[60:63], v[166:169], v[204:207], v[60:63]
	v_mfma_f32_16x16x32_bf16 v[48:51], v[142:145], v[212:215], v[48:51]
	v_mfma_f32_16x16x32_bf16 v[44:47], v[166:169], v[212:215], v[44:47]
	v_mfma_f32_16x16x32_bf16 v[32:35], v[142:145], v[236:239], v[32:35]
	v_mfma_f32_16x16x32_bf16 v[28:31], v[166:169], v[236:239], v[28:31]
	v_mfma_f32_16x16x32_bf16 v[16:19], v[142:145], v[244:247], v[16:19]
	v_mfma_f32_16x16x32_bf16 v[12:15], v[166:169], v[244:247], v[12:15]
	s_setprio 0
	s_setprio 1
	v_mfma_f32_16x16x32_bf16 v[56:59], v[170:173], v[200:203], v[56:59]
	v_mfma_f32_16x16x32_bf16 v[52:55], v[192:195], v[200:203], v[52:55]
	v_mfma_f32_16x16x32_bf16 v[40:43], v[170:173], v[208:211], v[40:43]
	v_mfma_f32_16x16x32_bf16 v[36:39], v[192:195], v[208:211], v[36:39]
	v_mfma_f32_16x16x32_bf16 v[24:27], v[170:173], v[216:219], v[24:27]
	v_mfma_f32_16x16x32_bf16 v[20:23], v[192:195], v[216:219], v[20:23]
	v_mfma_f32_16x16x32_bf16 v[8:11], v[170:173], v[240:243], v[8:11]
	v_mfma_f32_16x16x32_bf16 v[2:5], v[192:195], v[240:243], v[4:7]
	v_mfma_f32_16x16x32_bf16 v[56:59], v[184:187], v[204:207], v[56:59]
	v_mfma_f32_16x16x32_bf16 v[52:55], v[196:199], v[204:207], v[52:55]
	v_mfma_f32_16x16x32_bf16 v[40:43], v[184:187], v[212:215], v[40:43]
	v_mfma_f32_16x16x32_bf16 v[36:39], v[196:199], v[212:215], v[36:39]
	v_mfma_f32_16x16x32_bf16 v[24:27], v[184:187], v[236:239], v[24:27]
	v_mfma_f32_16x16x32_bf16 v[20:23], v[196:199], v[236:239], v[20:23]
	v_mfma_f32_16x16x32_bf16 v[8:11], v[184:187], v[244:247], v[8:11]
	v_mfma_f32_16x16x32_bf16 v[2:5], v[196:199], v[244:247], v[2:5]
	s_barrier
	s_setprio 0
	s_add_i32 s76, 0, 0x18000
	v_add_u32_e32 v0, s76, v188
	s_add_i32 s77, 0, 0x1c000
	ds_read_b128 v[138:141], v0
	ds_read_b128 v[142:145], v0 offset:1024
	ds_read_b128 v[162:165], v0 offset:2048
	ds_read_b128 v[166:169], v0 offset:3072
	v_add_u32_e32 v0, s77, v188
	ds_read_b128 v[170:173], v0
	ds_read_b128 v[184:187], v0 offset:1024
	ds_read_b128 v[192:195], v0 offset:2048
	ds_read_b128 v[196:199], v0 offset:3072
	s_add_u32 s20, s20, 0x80000
	s_addc_u32 s21, s21, 0
	s_mov_b32 m0, s30
	v_lshl_add_u64 v[6:7], s[20:21], 0, v[148:149]
	ds_read_b128 v[200:203], v190 offset:32768
	ds_read_b128 v[204:207], v190 offset:33792
	ds_read_b128 v[208:211], v190 offset:34816
	ds_read_b128 v[212:215], v190 offset:35840
	ds_read_b128 v[216:219], v190 offset:36864
	ds_read_b128 v[236:239], v190 offset:37888
	ds_read_b128 v[240:243], v190 offset:38912
	ds_read_b128 v[244:247], v190 offset:39936
	global_load_lds_dwordx4 v[6:7], off
	v_lshl_add_u64 v[6:7], s[20:21], 0, v[152:153]
	s_mov_b32 m0, s36
	s_nop 0
	global_load_lds_dwordx4 v[6:7], off
	s_waitcnt vmcnt(8)
	s_waitcnt lgkmcnt(0)
	s_setprio 1
	s_barrier
	v_mfma_f32_16x16x32_bf16 v[128:131], v[138:141], v[200:203], v[128:131]
	v_mfma_f32_16x16x32_bf16 v[124:127], v[162:165], v[200:203], v[124:127]
	v_mfma_f32_16x16x32_bf16 v[112:115], v[138:141], v[208:211], v[112:115]
	v_mfma_f32_16x16x32_bf16 v[108:111], v[162:165], v[208:211], v[108:111]
	v_mfma_f32_16x16x32_bf16 v[96:99], v[138:141], v[216:219], v[96:99]
	v_mfma_f32_16x16x32_bf16 v[92:95], v[162:165], v[216:219], v[92:95]
	v_mfma_f32_16x16x32_bf16 v[80:83], v[138:141], v[240:243], v[80:83]
	v_mfma_f32_16x16x32_bf16 v[76:79], v[162:165], v[240:243], v[76:79]
	v_mfma_f32_16x16x32_bf16 v[128:131], v[142:145], v[204:207], v[128:131]
	v_mfma_f32_16x16x32_bf16 v[124:127], v[166:169], v[204:207], v[124:127]
	v_mfma_f32_16x16x32_bf16 v[112:115], v[142:145], v[212:215], v[112:115]
	v_mfma_f32_16x16x32_bf16 v[108:111], v[166:169], v[212:215], v[108:111]
	v_mfma_f32_16x16x32_bf16 v[96:99], v[142:145], v[236:239], v[96:99]
	v_mfma_f32_16x16x32_bf16 v[92:95], v[166:169], v[236:239], v[92:95]
	v_mfma_f32_16x16x32_bf16 v[80:83], v[142:145], v[244:247], v[80:83]
	v_mfma_f32_16x16x32_bf16 v[76:79], v[166:169], v[244:247], v[76:79]
	s_setprio 0
	s_setprio 1
	v_mfma_f32_16x16x32_bf16 v[120:123], v[170:173], v[200:203], v[120:123]
	v_mfma_f32_16x16x32_bf16 v[116:119], v[192:195], v[200:203], v[116:119]
	v_mfma_f32_16x16x32_bf16 v[104:107], v[170:173], v[208:211], v[104:107]
	v_mfma_f32_16x16x32_bf16 v[100:103], v[192:195], v[208:211], v[100:103]
	v_mfma_f32_16x16x32_bf16 v[88:91], v[170:173], v[216:219], v[88:91]
	v_mfma_f32_16x16x32_bf16 v[84:87], v[192:195], v[216:219], v[84:87]
	v_mfma_f32_16x16x32_bf16 v[72:75], v[170:173], v[240:243], v[72:75]
	v_mfma_f32_16x16x32_bf16 v[68:71], v[192:195], v[240:243], v[68:71]
	v_mfma_f32_16x16x32_bf16 v[120:123], v[184:187], v[204:207], v[120:123]
	v_mfma_f32_16x16x32_bf16 v[116:119], v[196:199], v[204:207], v[116:119]
	v_mfma_f32_16x16x32_bf16 v[104:107], v[184:187], v[212:215], v[104:107]
	v_mfma_f32_16x16x32_bf16 v[100:103], v[196:199], v[212:215], v[100:103]
	v_mfma_f32_16x16x32_bf16 v[88:91], v[184:187], v[236:239], v[88:91]
	v_mfma_f32_16x16x32_bf16 v[84:87], v[196:199], v[236:239], v[84:87]
	v_mfma_f32_16x16x32_bf16 v[72:75], v[184:187], v[244:247], v[72:75]
	v_mfma_f32_16x16x32_bf16 v[68:71], v[196:199], v[244:247], v[68:71]
	s_barrier
; #define PG8_STAGE(bufoff, gbase, voff) do { _Pragma("unroll") for (int _i = 0; _i < 2; ++_i) \
;         __builtin_amdgcn_global_load_lds((const unsigned*)((const char*)(gbase) + (voff)[_i]), (PG8_LAS unsigned*)(lds + (bufoff) + ldsw + _i * 8192), 16, 0, 0); } while (0)
; #define PG8_LDA(dst, b, h) do { _Pragma("unroll") for (int m = 0; m < 4; ++m) _Pragma("unroll") for (int k = 0; k < 2; ++k) dst[m][k] = *(const PG8_LAS bf16x8*)(lds + PG8_SA(b, h) + aoff + m * 2048 + k * 1024); } while (0)
; #define PG8_MMA(ai, bj, At, Bt) do { __builtin_amdgcn_s_setprio(1); _Pragma("unroll") for (int m = 0; m < 4; ++m) _Pragma("unroll") for (int n = 0; n < 2; ++n) _Pragma("unroll") for (int k = 0; k < 2; ++k) \
;         acc[ai][bj][m][n] = __builtin_amdgcn_mfma_f32_16x16x32_bf16(Bt[n][k], At[m][k], acc[ai][bj][m][n], 0, 0, 0); __builtin_amdgcn_s_setprio(0); } while (0)
; #define PG8_WAIT_V(n) asm volatile("s_waitcnt vmcnt(" #n ")" ::: "memory")
; #define PG8_WAIT_L(n) asm volatile("s_waitcnt lgkmcnt(" #n ")" ::: "memory")
; #define PG8_BAR __builtin_amdgcn_s_barrier()
; #define PG8_SCHED __builtin_amdgcn_sched_barrier(0)
; template <class Epi, class Sched, bool ALIGN_EPI = true, bool SP2 = true, bool GS = false>
; __device__ __forceinline__ void gemm_phase(PG8_LAS unsigned char* lds, const Gemm g, const Sched& S, const Epi& E, const float* gs_ss = nullptr) {
;     ...
;             PG8_LDA(At, 1, 1); PG8_STAGE(PG8_SB(1, 0), b3, voffB); PG8_STAGE(PG8_SB(1, 1), b3 + hstep, voffB); PG8_STAGE(PG8_SA(1, 0), a3, voffA);
;             PG8_WAIT_V(8); PG8_WAIT_L(0); PG8_BAR; PG8_MMA(1, 0, At, B0); PG8_MMA(1, 1, At, B1); PG8_BAR; PG8_SCHED;
	s_setprio 0
	s_add_i32 s20, s76, s14
	v_lshl_add_u64 v[6:7], v[146:147], 0, s[26:27]
	s_mov_b32 m0, s20
	ds_read_b128 v[200:203], v190 offset:49152
	ds_read_b128 v[204:207], v190 offset:50176
	ds_read_b128 v[208:211], v190 offset:51200
	ds_read_b128 v[212:215], v190 offset:52224
	ds_read_b128 v[216:219], v190 offset:53248
	ds_read_b128 v[236:239], v190 offset:54272
	ds_read_b128 v[240:243], v190 offset:55296
	ds_read_b128 v[244:247], v190 offset:56320
	global_load_lds_dwordx4 v[6:7], off
	s_add_i32 m0, s20, 0x2000
	s_add_u32 s2, s2, 0x80080
	v_lshl_add_u64 v[6:7], v[174:175], 0, s[26:27]
	s_addc_u32 s3, s3, 0
	s_add_i32 s20, s77, s14
	global_load_lds_dwordx4 v[6:7], off
	v_lshl_add_u64 v[6:7], s[2:3], 0, v[150:151]
	s_mov_b32 m0, s20
	s_nop 0
	global_load_lds_dwordx4 v[6:7], off
	v_lshl_add_u64 v[6:7], s[2:3], 0, v[154:155]
	s_add_i32 m0, s20, 0x2000
	s_nop 0
	global_load_lds_dwordx4 v[6:7], off
	v_lshl_add_u64 v[6:7], v[180:181], 0, s[26:27]
	s_mov_b32 m0, s57
	s_nop 0
	global_load_lds_dwordx4 v[6:7], off
	v_lshl_add_u64 v[6:7], v[220:221], 0, s[26:27]
	s_mov_b32 m0, s64
	s_nop 0
	global_load_lds_dwordx4 v[6:7], off
	s_waitcnt vmcnt(8)
	s_waitcnt lgkmcnt(0)
	s_setprio 1
	s_barrier
	v_mfma_f32_16x16x32_bf16 v[64:67], v[138:141], v[200:203], v[64:67]
	v_mfma_f32_16x16x32_bf16 v[60:63], v[162:165], v[200:203], v[60:63]
	v_mfma_f32_16x16x32_bf16 v[48:51], v[138:141], v[208:211], v[48:51]
	v_mfma_f32_16x16x32_bf16 v[44:47], v[162:165], v[208:211], v[44:47]
	v_mfma_f32_16x16x32_bf16 v[32:35], v[138:141], v[216:219], v[32:35]
	v_mfma_f32_16x16x32_bf16 v[28:31], v[162:165], v[216:219], v[28:31]
	v_mfma_f32_16x16x32_bf16 v[16:19], v[138:141], v[240:243], v[16:19]
	v_mfma_f32_16x16x32_bf16 v[12:15], v[162:165], v[240:243], v[12:15]
	v_mfma_f32_16x16x32_bf16 v[64:67], v[142:145], v[204:207], v[64:67]
	v_mfma_f32_16x16x32_bf16 v[60:63], v[166:169], v[204:207], v[60:63]
	v_mfma_f32_16x16x32_bf16 v[48:51], v[142:145], v[212:215], v[48:51]
	v_mfma_f32_16x16x32_bf16 v[44:47], v[166:169], v[212:215], v[44:47]
	v_mfma_f32_16x16x32_bf16 v[32:35], v[142:145], v[236:239], v[32:35]
	v_mfma_f32_16x16x32_bf16 v[28:31], v[166:169], v[236:239], v[28:31]
	v_mfma_f32_16x16x32_bf16 v[16:19], v[142:145], v[244:247], v[16:19]
	v_mfma_f32_16x16x32_bf16 v[12:15], v[166:169], v[244:247], v[12:15]
	s_setprio 0
	s_setprio 1
	v_mfma_f32_16x16x32_bf16 v[56:59], v[170:173], v[200:203], v[56:59]
	v_mfma_f32_16x16x32_bf16 v[52:55], v[192:195], v[200:203], v[52:55]
	v_mfma_f32_16x16x32_bf16 v[40:43], v[170:173], v[208:211], v[40:43]
	v_mfma_f32_16x16x32_bf16 v[36:39], v[192:195], v[208:211], v[36:39]
	v_mfma_f32_16x16x32_bf16 v[24:27], v[170:173], v[216:219], v[24:27]
	v_mfma_f32_16x16x32_bf16 v[20:23], v[192:195], v[216:219], v[20:23]
	v_mfma_f32_16x16x32_bf16 v[6:9], v[170:173], v[240:243], v[8:11]
	v_mfma_f32_16x16x32_bf16 v[2:5], v[192:195], v[240:243], v[2:5]
	v_mfma_f32_16x16x32_bf16 v[56:59], v[184:187], v[204:207], v[56:59]
	v_mfma_f32_16x16x32_bf16 v[52:55], v[196:199], v[204:207], v[52:55]
	v_mfma_f32_16x16x32_bf16 v[40:43], v[184:187], v[212:215], v[40:43]
	v_mfma_f32_16x16x32_bf16 v[36:39], v[196:199], v[212:215], v[36:39]
	v_mfma_f32_16x16x32_bf16 v[24:27], v[184:187], v[236:239], v[24:27]
	v_mfma_f32_16x16x32_bf16 v[20:23], v[196:199], v[236:239], v[20:23]
	v_mfma_f32_16x16x32_bf16 v[8:11], v[184:187], v[244:247], v[6:9]
	v_mfma_f32_16x16x32_bf16 v[4:7], v[196:199], v[244:247], v[2:5]
	s_barrier
	s_setprio 0
	s_and_b32 s2, s75, 6
	s_cmp_lg_u32 s2, 6
	s_cselect_b64 s[2:3], -1, 0
	s_or_b64 s[2:3], s[62:63], s[2:3]
	s_and_b64 vcc, exec, s[2:3]
	s_cbranch_vccnz .LBB0_1035
	s_and_b32 s2, s60, 0xc00
	v_add_u32_e32 v137, s2, v136
	v_add_u32_e32 v140, 0x400, v137
	ds_read2_b32 v[2:3], v137 offset1:16
	ds_read2_b32 v[138:139], v140 offset1:16
	s_waitcnt lgkmcnt(0)
	v_div_scale_f32 v0, s[2:3], v138, v138, v2
	v_rcp_f32_e32 v141, v0
	v_div_scale_f32 v142, vcc, v2, v138, v2
	v_fma_f32 v143, -v0, v141, 1.0
	v_fmac_f32_e32 v141, v143, v141
	v_mul_f32_e32 v143, v142, v141
	v_fma_f32 v144, -v0, v143, v142
	v_fmac_f32_e32 v143, v144, v141
	v_fma_f32 v0, -v0, v143, v142
	v_div_fmas_f32 v0, v0, v141, v143
	v_div_fixup_f32 v0, v0, v138, v2
	v_div_scale_f32 v2, s[2:3], v139, v139, v3
	v_rcp_f32_e32 v138, v2
	v_pk_mul_f32 v[130:131], v[130:131], v[0:1] op_sel_hi:[1,0]
	v_pk_mul_f32 v[128:129], v[128:129], v[0:1] op_sel_hi:[1,0]
	v_pk_mul_f32 v[126:127], v[126:127], v[0:1] op_sel_hi:[1,0]
	v_pk_mul_f32 v[124:125], v[124:125], v[0:1] op_sel_hi:[1,0]
	v_pk_mul_f32 v[122:123], v[122:123], v[0:1] op_sel_hi:[1,0]
	v_pk_mul_f32 v[120:121], v[120:121], v[0:1] op_sel_hi:[1,0]
	v_pk_mul_f32 v[118:119], v[118:119], v[0:1] op_sel_hi:[1,0]
	v_pk_mul_f32 v[116:117], v[116:117], v[0:1] op_sel_hi:[1,0]
	v_fma_f32 v0, -v2, v138, 1.0
	v_fmac_f32_e32 v138, v0, v138
	v_div_scale_f32 v0, vcc, v3, v139, v3
	v_mul_f32_e32 v141, v0, v138
	v_fma_f32 v142, -v2, v141, v0
	v_fmac_f32_e32 v141, v142, v138
	v_fma_f32 v0, -v2, v141, v0
	v_div_fmas_f32 v0, v0, v138, v141
	v_div_fixup_f32 v0, v0, v139, v3
	ds_read2_b32 v[2:3], v137 offset0:32 offset1:48
	ds_read2_b32 v[138:139], v140 offset0:32 offset1:48
	v_pk_mul_f32 v[114:115], v[114:115], v[0:1] op_sel_hi:[1,0]
	v_pk_mul_f32 v[112:113], v[112:113], v[0:1] op_sel_hi:[1,0]
	v_pk_mul_f32 v[110:111], v[110:111], v[0:1] op_sel_hi:[1,0]
	v_pk_mul_f32 v[108:109], v[108:109], v[0:1] op_sel_hi:[1,0]
	s_waitcnt lgkmcnt(0)
	v_div_scale_f32 v141, s[2:3], v138, v138, v2
	v_rcp_f32_e32 v142, v141
	v_pk_mul_f32 v[106:107], v[106:107], v[0:1] op_sel_hi:[1,0]
	v_pk_mul_f32 v[104:105], v[104:105], v[0:1] op_sel_hi:[1,0]
	v_pk_mul_f32 v[102:103], v[102:103], v[0:1] op_sel_hi:[1,0]
	v_pk_mul_f32 v[100:101], v[100:101], v[0:1] op_sel_hi:[1,0]
	v_fma_f32 v0, -v141, v142, 1.0
	v_fmac_f32_e32 v142, v0, v142
	v_div_scale_f32 v0, vcc, v2, v138, v2
	v_mul_f32_e32 v143, v0, v142
	v_fma_f32 v144, -v141, v143, v0
	v_fmac_f32_e32 v143, v144, v142
	v_fma_f32 v0, -v141, v143, v0
	v_div_fmas_f32 v0, v0, v142, v143
	v_div_fixup_f32 v0, v0, v138, v2
	v_div_scale_f32 v2, s[2:3], v139, v139, v3
	v_rcp_f32_e32 v138, v2
	v_pk_mul_f32 v[98:99], v[98:99], v[0:1] op_sel_hi:[1,0]
	v_pk_mul_f32 v[96:97], v[96:97], v[0:1] op_sel_hi:[1,0]
	v_pk_mul_f32 v[94:95], v[94:95], v[0:1] op_sel_hi:[1,0]
	v_pk_mul_f32 v[92:93], v[92:93], v[0:1] op_sel_hi:[1,0]
	v_pk_mul_f32 v[90:91], v[90:91], v[0:1] op_sel_hi:[1,0]
	v_pk_mul_f32 v[88:89], v[88:89], v[0:1] op_sel_hi:[1,0]
	v_pk_mul_f32 v[86:87], v[86:87], v[0:1] op_sel_hi:[1,0]
	v_pk_mul_f32 v[84:85], v[84:85], v[0:1] op_sel_hi:[1,0]
	v_fma_f32 v0, -v2, v138, 1.0
	v_fmac_f32_e32 v138, v0, v138
	v_div_scale_f32 v0, vcc, v3, v139, v3
	v_mul_f32_e32 v141, v0, v138
	v_fma_f32 v142, -v2, v141, v0
	v_fmac_f32_e32 v141, v142, v138
	v_fma_f32 v0, -v2, v141, v0
	v_div_fmas_f32 v0, v0, v138, v141
	v_div_fixup_f32 v0, v0, v139, v3
	ds_read2_b32 v[2:3], v137 offset0:128 offset1:144
	ds_read2_b32 v[138:139], v140 offset0:128 offset1:144
	v_pk_mul_f32 v[82:83], v[82:83], v[0:1] op_sel_hi:[1,0]
	v_pk_mul_f32 v[80:81], v[80:81], v[0:1] op_sel_hi:[1,0]
	v_pk_mul_f32 v[78:79], v[78:79], v[0:1] op_sel_hi:[1,0]
	v_pk_mul_f32 v[76:77], v[76:77], v[0:1] op_sel_hi:[1,0]
	s_waitcnt lgkmcnt(0)
	v_div_scale_f32 v141, s[2:3], v138, v138, v2
	v_rcp_f32_e32 v142, v141
	v_pk_mul_f32 v[74:75], v[74:75], v[0:1] op_sel_hi:[1,0]
	v_pk_mul_f32 v[72:73], v[72:73], v[0:1] op_sel_hi:[1,0]
	v_pk_mul_f32 v[70:71], v[70:71], v[0:1] op_sel_hi:[1,0]
	v_pk_mul_f32 v[68:69], v[68:69], v[0:1] op_sel_hi:[1,0]
	v_fma_f32 v0, -v141, v142, 1.0
	v_fmac_f32_e32 v142, v0, v142
	v_div_scale_f32 v0, vcc, v2, v138, v2
	v_mul_f32_e32 v143, v0, v142
	v_fma_f32 v144, -v141, v143, v0
	v_fmac_f32_e32 v143, v144, v142
	v_fma_f32 v0, -v141, v143, v0
	v_div_fmas_f32 v0, v0, v142, v143
	v_div_fixup_f32 v0, v0, v138, v2
	v_div_scale_f32 v2, s[2:3], v139, v139, v3
	v_rcp_f32_e32 v138, v2
	v_pk_mul_f32 v[66:67], v[66:67], v[0:1] op_sel_hi:[1,0]
	v_pk_mul_f32 v[64:65], v[64:65], v[0:1] op_sel_hi:[1,0]
	v_pk_mul_f32 v[62:63], v[62:63], v[0:1] op_sel_hi:[1,0]
	v_pk_mul_f32 v[60:61], v[60:61], v[0:1] op_sel_hi:[1,0]
	v_pk_mul_f32 v[58:59], v[58:59], v[0:1] op_sel_hi:[1,0]
	v_pk_mul_f32 v[56:57], v[56:57], v[0:1] op_sel_hi:[1,0]
	v_pk_mul_f32 v[54:55], v[54:55], v[0:1] op_sel_hi:[1,0]
	v_pk_mul_f32 v[52:53], v[52:53], v[0:1] op_sel_hi:[1,0]
	v_fma_f32 v0, -v2, v138, 1.0
	v_fmac_f32_e32 v138, v0, v138
	v_div_scale_f32 v0, vcc, v3, v139, v3
	v_mul_f32_e32 v141, v0, v138
	v_fma_f32 v142, -v2, v141, v0
	v_fmac_f32_e32 v141, v142, v138
	v_fma_f32 v0, -v2, v141, v0
	v_div_fmas_f32 v0, v0, v138, v141
	v_div_fixup_f32 v0, v0, v139, v3
	ds_read2_b32 v[2:3], v137 offset0:160 offset1:176
	ds_read2_b32 v[138:139], v140 offset0:160 offset1:176
	v_pk_mul_f32 v[50:51], v[50:51], v[0:1] op_sel_hi:[1,0]
	v_pk_mul_f32 v[48:49], v[48:49], v[0:1] op_sel_hi:[1,0]
	v_pk_mul_f32 v[46:47], v[46:47], v[0:1] op_sel_hi:[1,0]
	v_pk_mul_f32 v[44:45], v[44:45], v[0:1] op_sel_hi:[1,0]
	s_waitcnt lgkmcnt(0)
	v_div_scale_f32 v137, s[2:3], v138, v138, v2
	v_rcp_f32_e32 v140, v137
	v_pk_mul_f32 v[42:43], v[42:43], v[0:1] op_sel_hi:[1,0]
	v_pk_mul_f32 v[40:41], v[40:41], v[0:1] op_sel_hi:[1,0]
	v_pk_mul_f32 v[38:39], v[38:39], v[0:1] op_sel_hi:[1,0]
	v_pk_mul_f32 v[36:37], v[36:37], v[0:1] op_sel_hi:[1,0]
	v_fma_f32 v0, -v137, v140, 1.0
	v_fmac_f32_e32 v140, v0, v140
	v_div_scale_f32 v0, vcc, v2, v138, v2
	v_mul_f32_e32 v141, v0, v140
	v_fma_f32 v142, -v137, v141, v0
	v_fmac_f32_e32 v141, v142, v140
	v_fma_f32 v0, -v137, v141, v0
	v_div_fmas_f32 v0, v0, v140, v141
	v_div_fixup_f32 v0, v0, v138, v2
	v_div_scale_f32 v2, s[2:3], v139, v139, v3
	v_rcp_f32_e32 v137, v2
	v_pk_mul_f32 v[34:35], v[34:35], v[0:1] op_sel_hi:[1,0]
	v_pk_mul_f32 v[32:33], v[32:33], v[0:1] op_sel_hi:[1,0]
	v_pk_mul_f32 v[30:31], v[30:31], v[0:1] op_sel_hi:[1,0]
	v_pk_mul_f32 v[28:29], v[28:29], v[0:1] op_sel_hi:[1,0]
	v_pk_mul_f32 v[26:27], v[26:27], v[0:1] op_sel_hi:[1,0]
	v_pk_mul_f32 v[24:25], v[24:25], v[0:1] op_sel_hi:[1,0]
	v_pk_mul_f32 v[22:23], v[22:23], v[0:1] op_sel_hi:[1,0]
	v_pk_mul_f32 v[20:21], v[20:21], v[0:1] op_sel_hi:[1,0]
	v_fma_f32 v0, -v2, v137, 1.0
	v_fmac_f32_e32 v137, v0, v137
	v_div_scale_f32 v0, vcc, v3, v139, v3
	v_mul_f32_e32 v138, v0, v137
	v_fma_f32 v140, -v2, v138, v0
	v_fmac_f32_e32 v138, v140, v137
	v_fma_f32 v0, -v2, v138, v0
	v_div_fmas_f32 v0, v0, v137, v138
	v_div_fixup_f32 v0, v0, v139, v3
	v_pk_mul_f32 v[18:19], v[18:19], v[0:1] op_sel_hi:[1,0]
	v_pk_mul_f32 v[16:17], v[16:17], v[0:1] op_sel_hi:[1,0]
	v_pk_mul_f32 v[14:15], v[14:15], v[0:1] op_sel_hi:[1,0]
	v_pk_mul_f32 v[12:13], v[12:13], v[0:1] op_sel_hi:[1,0]
	v_pk_mul_f32 v[10:11], v[10:11], v[0:1] op_sel_hi:[1,0]
	v_pk_mul_f32 v[8:9], v[8:9], v[0:1] op_sel_hi:[1,0]
	v_pk_mul_f32 v[6:7], v[6:7], v[0:1] op_sel_hi:[1,0]
	v_pk_mul_f32 v[4:5], v[4:5], v[0:1] op_sel_hi:[1,0]
	s_branch .LBB0_1035

;     __device__ __forceinline__ size_t a_extra(const Unit& u) const { return (size_t)(u.pn >> 1) * ((size_t)T * 512 * 2); }
;     __device__ __forceinline__ size_t a_extra(const Unit& u) const { return (size_t)(u.pn >> 1) * 512 * 2; }
;     __device__ __forceinline__ size_t b_extra(const Unit& u) const { return (size_t)(u.pn >> 1) * 512 * 2 - (size_t)(u.pn & ~1) * ((size_t)256 * D * 2); }
; #define PG8_STAGE(bufoff, gbase, voff) do { _Pragma("unroll") for (int _i = 0; _i < 2; ++_i) \
;         __builtin_amdgcn_global_load_lds((const unsigned*)((const char*)(gbase) + (voff)[_i]), (PG8_LAS unsigned*)(lds + (bufoff) + ldsw + _i * 8192), 16, 0, 0); } while (0)
; #define PG8_LDA(dst, b, h) do { _Pragma("unroll") for (int m = 0; m < 4; ++m) _Pragma("unroll") for (int k = 0; k < 2; ++k) dst[m][k] = *(const PG8_LAS bf16x8*)(lds + PG8_SA(b, h) + aoff + m * 2048 + k * 1024); } while (0)
; #define PG8_WAIT_V(n) asm volatile("s_waitcnt vmcnt(" #n ")" ::: "memory")
; #define PG8_WAIT_L(n) asm volatile("s_waitcnt lgkmcnt(" #n ")" ::: "memory")
; template <class Epi, class Sched, bool ALIGN_EPI = true, bool SP2 = true, bool GS = false>
; __device__ __forceinline__ void gemm_phase(PG8_LAS unsigned char* lds, const Gemm g, const Sched& S, const Epi& E, const float* gs_ss = nullptr) {
;     ...
;         const char* nA = has_next ? (const char*)g.A + S.a_extra(nxt) + (size_t)nxt.pm * tstep : cA; const char* nB = has_next ? (const char*)g.Bt + S.b_extra(nxt) + (size_t)nxt.pn * tstep : cB;
;         for (int t = 0; t < nt; t += 2) {
;             const bool last = (t == nt - 2);
;             const char* a1 = cA + (size_t)(t + 1) * kstep;
;             const char* a2 = last ? nA : cA + (size_t)(t + 2) * kstep; const char* b2 = last ? nB : cB + (size_t)(t + 2) * kstep;
;             const char* a3 = a2 + kstep; const char* b3 = b2 + kstep;
;             if constexpr (SP2) {
;             PG8_LDB(B0, 0, 0); PG8_LDB(B1, 0, 1); PG8_SCHED; PG8_LDA(At, 0, 0); PG8_STAGE(PG8_SA(1, 1), a1 + hstep, voffA);
;             PG8_WAIT_V(8); PG8_WAIT_L(0); PG8_BAR; PG8_MMA(0, 0, At, B0); PG8_MMA(0, 1, At, B1); PG8_BAR; PG8_SCHED;
;             PG8_LDA(At, 0, 1); PG8_STAGE(PG8_SB(0, 0), b2, voffB); PG8_STAGE(PG8_SB(0, 1), b2 + hstep, voffB); PG8_STAGE(PG8_SA(0, 0), a2, voffA);
;             PG8_WAIT_V(8); PG8_WAIT_L(0); PG8_BAR; PG8_MMA(1, 0, At, B0); PG8_MMA(1, 1, At, B1); PG8_BAR; PG8_SCHED;
.LBB0_1119:
	s_add_u32 s2, s44, 0xfff80080
	s_addc_u32 s3, s45, -1
	s_add_i32 s59, 0, 0x10000
	s_cmp_eq_u32 s58, 4
	s_cselect_b32 s21, s52, s3
	s_cselect_b32 s20, s53, s2
	v_add_u32_e32 v0, s59, v145
	s_cselect_b32 s3, s54, s57
	s_cselect_b32 s2, s55, s56
	s_add_i32 s62, 0, 0x14000
	ds_read_b128 v[148:151], v0
	ds_read_b128 v[152:155], v0 offset:1024
	ds_read_b128 v[156:159], v0 offset:2048
	ds_read_b128 v[160:163], v0 offset:3072
	v_add_u32_e32 v0, s62, v145
	ds_read_b128 v[164:167], v0
	ds_read_b128 v[168:171], v0 offset:1024
	ds_read_b128 v[172:175], v0 offset:2048
	ds_read_b128 v[180:183], v0 offset:3072
	v_lshl_add_u64 v[142:143], s[44:45], 0, v[138:139]
	s_add_i32 m0, s9, 0xc000
	ds_read_b128 v[184:187], v147
	ds_read_b128 v[188:191], v147 offset:1024
	ds_read_b128 v[192:195], v147 offset:2048
	ds_read_b128 v[196:199], v147 offset:3072
	ds_read_b128 v[200:203], v147 offset:4096
	ds_read_b128 v[204:207], v147 offset:5120
	ds_read_b128 v[208:211], v147 offset:6144
	ds_read_b128 v[212:215], v147 offset:7168
	global_load_lds_dwordx4 v[142:143], off
	v_lshl_add_u64 v[142:143], s[44:45], 0, v[140:141]
	s_add_i32 m0, s9, 0xe000
	s_nop 0
	global_load_lds_dwordx4 v[142:143], off
	s_waitcnt vmcnt(8)
	s_waitcnt lgkmcnt(0)
	s_setprio 1
	s_barrier
	v_mfma_f32_16x16x32_bf16 v[126:129], v[148:151], v[184:187], v[126:129]
	v_mfma_f32_16x16x32_bf16 v[122:125], v[156:159], v[184:187], v[122:125]
	v_mfma_f32_16x16x32_bf16 v[118:121], v[148:151], v[192:195], v[118:121]
	v_mfma_f32_16x16x32_bf16 v[110:113], v[156:159], v[192:195], v[110:113]
	v_mfma_f32_16x16x32_bf16 v[102:105], v[148:151], v[200:203], v[102:105]
	v_mfma_f32_16x16x32_bf16 v[94:97], v[156:159], v[200:203], v[94:97]
	v_mfma_f32_16x16x32_bf16 v[86:89], v[148:151], v[208:211], v[86:89]
	v_mfma_f32_16x16x32_bf16 v[78:81], v[156:159], v[208:211], v[78:81]
	v_mfma_f32_16x16x32_bf16 v[126:129], v[152:155], v[188:191], v[126:129]
	v_mfma_f32_16x16x32_bf16 v[122:125], v[160:163], v[188:191], v[122:125]
	v_mfma_f32_16x16x32_bf16 v[118:121], v[152:155], v[196:199], v[118:121]
	v_mfma_f32_16x16x32_bf16 v[110:113], v[160:163], v[196:199], v[110:113]
	v_mfma_f32_16x16x32_bf16 v[102:105], v[152:155], v[204:207], v[102:105]
	v_mfma_f32_16x16x32_bf16 v[94:97], v[160:163], v[204:207], v[94:97]
	v_mfma_f32_16x16x32_bf16 v[86:89], v[152:155], v[212:215], v[86:89]
	v_mfma_f32_16x16x32_bf16 v[78:81], v[160:163], v[212:215], v[78:81]
	s_setprio 0
	s_setprio 1
	v_mfma_f32_16x16x32_bf16 v[114:117], v[164:167], v[184:187], v[114:117]
	v_mfma_f32_16x16x32_bf16 v[106:109], v[172:175], v[184:187], v[106:109]
	v_mfma_f32_16x16x32_bf16 v[98:101], v[164:167], v[192:195], v[98:101]
	v_mfma_f32_16x16x32_bf16 v[90:93], v[172:175], v[192:195], v[90:93]
	v_mfma_f32_16x16x32_bf16 v[82:85], v[164:167], v[200:203], v[82:85]
	v_mfma_f32_16x16x32_bf16 v[74:77], v[172:175], v[200:203], v[74:77]
	v_mfma_f32_16x16x32_bf16 v[70:73], v[164:167], v[208:211], v[70:73]
	v_mfma_f32_16x16x32_bf16 v[66:69], v[172:175], v[208:211], v[66:69]
	v_mfma_f32_16x16x32_bf16 v[114:117], v[168:171], v[188:191], v[114:117]
	v_mfma_f32_16x16x32_bf16 v[106:109], v[180:183], v[188:191], v[106:109]
	v_mfma_f32_16x16x32_bf16 v[98:101], v[168:171], v[196:199], v[98:101]
	v_mfma_f32_16x16x32_bf16 v[90:93], v[180:183], v[196:199], v[90:93]
	v_mfma_f32_16x16x32_bf16 v[82:85], v[168:171], v[204:207], v[82:85]
	v_mfma_f32_16x16x32_bf16 v[74:77], v[180:183], v[204:207], v[74:77]
	v_mfma_f32_16x16x32_bf16 v[70:73], v[168:171], v[212:215], v[70:73]
	v_mfma_f32_16x16x32_bf16 v[66:69], v[180:183], v[212:215], v[66:69]
	s_barrier
	s_setprio 0
	s_add_i32 s59, s59, s23
	v_lshl_add_u64 v[142:143], s[2:3], 0, v[134:135]
	s_mov_b32 m0, s59
	ds_read_b128 v[184:187], v147 offset:16384
	ds_read_b128 v[188:191], v147 offset:17408
	ds_read_b128 v[192:195], v147 offset:18432
	ds_read_b128 v[196:199], v147 offset:19456
	ds_read_b128 v[200:203], v147 offset:20480
	ds_read_b128 v[204:207], v147 offset:21504
	ds_read_b128 v[208:211], v147 offset:22528
	ds_read_b128 v[212:215], v147 offset:23552
	global_load_lds_dwordx4 v[142:143], off
	s_add_i32 m0, s59, 0x2000
	s_add_u32 s60, s2, 0x80000
	v_lshl_add_u64 v[176:177], s[2:3], 0, v[130:131]
	s_addc_u32 s61, s3, 0
	s_add_i32 s59, s62, s23
	global_load_lds_dwordx4 v[176:177], off
	v_lshl_add_u64 v[216:217], s[60:61], 0, v[134:135]
	s_mov_b32 m0, s59
	v_lshl_add_u64 v[218:219], s[20:21], 0, v[132:133]
	global_load_lds_dwordx4 v[216:217], off
	v_lshl_add_u64 v[216:217], s[60:61], 0, v[130:131]
	s_add_i32 m0, s59, 0x2000
	s_nop 0
	global_load_lds_dwordx4 v[216:217], off
	v_lshl_add_u64 v[216:217], s[20:21], 0, v[136:137]
	s_mov_b32 m0, s9
	s_nop 0
	global_load_lds_dwordx4 v[216:217], off
	s_mov_b32 m0, s25
	s_nop 0
	global_load_lds_dwordx4 v[218:219], off
	s_waitcnt vmcnt(8)
	s_waitcnt lgkmcnt(0)
	s_setprio 1
	s_barrier
; #define PG8_STAGE(bufoff, gbase, voff) do { _Pragma("unroll") for (int _i = 0; _i < 2; ++_i) \
;         __builtin_amdgcn_global_load_lds((const unsigned*)((const char*)(gbase) + (voff)[_i]), (PG8_LAS unsigned*)(lds + (bufoff) + ldsw + _i * 8192), 16, 0, 0); } while (0)
; #define PG8_LDA(dst, b, h) do { _Pragma("unroll") for (int m = 0; m < 4; ++m) _Pragma("unroll") for (int k = 0; k < 2; ++k) dst[m][k] = *(const PG8_LAS bf16x8*)(lds + PG8_SA(b, h) + aoff + m * 2048 + k * 1024); } while (0)
; #define PG8_LDB(dst, b, h) do { _Pragma("unroll") for (int n = 0; n < 2; ++n) _Pragma("unroll") for (int k = 0; k < 2; ++k) dst[n][k] = *(const PG8_LAS bf16x8*)(lds + PG8_SB(b, h) + boff + n * 2048 + k * 1024); } while (0)
; #define PG8_MMA(ai, bj, At, Bt) do { __builtin_amdgcn_s_setprio(1); _Pragma("unroll") for (int m = 0; m < 4; ++m) _Pragma("unroll") for (int n = 0; n < 2; ++n) _Pragma("unroll") for (int k = 0; k < 2; ++k) \
;         acc[ai][bj][m][n] = __builtin_amdgcn_mfma_f32_16x16x32_bf16(Bt[n][k], At[m][k], acc[ai][bj][m][n], 0, 0, 0); __builtin_amdgcn_s_setprio(0); } while (0)
; #define PG8_WAIT_V(n) asm volatile("s_waitcnt vmcnt(" #n ")" ::: "memory")
; #define PG8_WAIT_L(n) asm volatile("s_waitcnt lgkmcnt(" #n ")" ::: "memory")
; #define PG8_BAR __builtin_amdgcn_s_barrier()
; #define PG8_SCHED __builtin_amdgcn_sched_barrier(0)
; template <class Epi, class Sched, bool ALIGN_EPI = true, bool SP2 = true, bool GS = false>
; __device__ __forceinline__ void gemm_phase(PG8_LAS unsigned char* lds, const Gemm g, const Sched& S, const Epi& E, const float* gs_ss = nullptr) {
;     ...
;             PG8_WAIT_V(8); PG8_WAIT_L(0); PG8_BAR; PG8_MMA(1, 0, At, B0); PG8_MMA(1, 1, At, B1); PG8_BAR; PG8_SCHED;
;             PG8_LDB(B0, 1, 0); PG8_LDB(B1, 1, 1); PG8_SCHED; PG8_LDA(At, 1, 0); PG8_STAGE(PG8_SA(0, 1), a2 + hstep, voffA);
;             PG8_WAIT_V(8); PG8_WAIT_L(0); PG8_BAR; PG8_MMA(0, 0, At, B0); PG8_MMA(0, 1, At, B1); PG8_BAR; PG8_SCHED;
	v_mfma_f32_16x16x32_bf16 v[62:65], v[148:151], v[184:187], v[62:65]
	v_mfma_f32_16x16x32_bf16 v[58:61], v[156:159], v[184:187], v[58:61]
	v_mfma_f32_16x16x32_bf16 v[54:57], v[148:151], v[192:195], v[54:57]
	v_mfma_f32_16x16x32_bf16 v[46:49], v[156:159], v[192:195], v[46:49]
	v_mfma_f32_16x16x32_bf16 v[38:41], v[148:151], v[200:203], v[38:41]
	v_mfma_f32_16x16x32_bf16 v[30:33], v[156:159], v[200:203], v[30:33]
	v_mfma_f32_16x16x32_bf16 v[22:25], v[148:151], v[208:211], v[22:25]
	v_mfma_f32_16x16x32_bf16 v[14:17], v[156:159], v[208:211], v[14:17]
	v_mfma_f32_16x16x32_bf16 v[62:65], v[152:155], v[188:191], v[62:65]
	v_mfma_f32_16x16x32_bf16 v[58:61], v[160:163], v[188:191], v[58:61]
	v_mfma_f32_16x16x32_bf16 v[54:57], v[152:155], v[196:199], v[54:57]
	v_mfma_f32_16x16x32_bf16 v[46:49], v[160:163], v[196:199], v[46:49]
	v_mfma_f32_16x16x32_bf16 v[38:41], v[152:155], v[204:207], v[38:41]
	v_mfma_f32_16x16x32_bf16 v[30:33], v[160:163], v[204:207], v[30:33]
	v_mfma_f32_16x16x32_bf16 v[22:25], v[152:155], v[212:215], v[22:25]
	v_mfma_f32_16x16x32_bf16 v[14:17], v[160:163], v[212:215], v[14:17]
	s_setprio 0
	s_setprio 1
	v_mfma_f32_16x16x32_bf16 v[50:53], v[164:167], v[184:187], v[50:53]
	v_mfma_f32_16x16x32_bf16 v[42:45], v[172:175], v[184:187], v[42:45]
	v_mfma_f32_16x16x32_bf16 v[34:37], v[164:167], v[192:195], v[34:37]
	v_mfma_f32_16x16x32_bf16 v[26:29], v[172:175], v[192:195], v[26:29]
	v_mfma_f32_16x16x32_bf16 v[18:21], v[164:167], v[200:203], v[18:21]
	v_mfma_f32_16x16x32_bf16 v[10:13], v[172:175], v[200:203], v[10:13]
	v_mfma_f32_16x16x32_bf16 v[6:9], v[164:167], v[208:211], v[6:9]
	v_mfma_f32_16x16x32_bf16 v[2:5], v[172:175], v[208:211], v[2:5]
	v_mfma_f32_16x16x32_bf16 v[50:53], v[168:171], v[188:191], v[50:53]
	v_mfma_f32_16x16x32_bf16 v[42:45], v[180:183], v[188:191], v[42:45]
	v_mfma_f32_16x16x32_bf16 v[34:37], v[168:171], v[196:199], v[34:37]
	v_mfma_f32_16x16x32_bf16 v[26:29], v[180:183], v[196:199], v[26:29]
	v_mfma_f32_16x16x32_bf16 v[18:21], v[168:171], v[204:207], v[18:21]
	v_mfma_f32_16x16x32_bf16 v[10:13], v[180:183], v[204:207], v[10:13]
	v_mfma_f32_16x16x32_bf16 v[6:9], v[168:171], v[212:215], v[6:9]
	v_mfma_f32_16x16x32_bf16 v[2:5], v[180:183], v[212:215], v[2:5]
	s_barrier
	s_setprio 0
	s_add_i32 s59, 0, 0x18000
	v_add_u32_e32 v0, s59, v145
	s_add_i32 s60, 0, 0x1c000
	ds_read_b128 v[148:151], v0
	ds_read_b128 v[152:155], v0 offset:1024
	ds_read_b128 v[156:159], v0 offset:2048
	ds_read_b128 v[160:163], v0 offset:3072
	v_add_u32_e32 v0, s60, v145
	ds_read_b128 v[164:167], v0
	ds_read_b128 v[168:171], v0 offset:1024
	ds_read_b128 v[172:175], v0 offset:2048
	ds_read_b128 v[180:183], v0 offset:3072
	s_add_u32 s20, s20, 0x80000
	s_addc_u32 s21, s21, 0
	s_mov_b32 m0, s30
	v_lshl_add_u64 v[220:221], s[20:21], 0, v[136:137]
	ds_read_b128 v[184:187], v147 offset:32768
	ds_read_b128 v[188:191], v147 offset:33792
	ds_read_b128 v[192:195], v147 offset:34816
	ds_read_b128 v[196:199], v147 offset:35840
	ds_read_b128 v[200:203], v147 offset:36864
	ds_read_b128 v[204:207], v147 offset:37888
	ds_read_b128 v[208:211], v147 offset:38912
	ds_read_b128 v[212:215], v147 offset:39936
	global_load_lds_dwordx4 v[220:221], off
	v_lshl_add_u64 v[220:221], s[20:21], 0, v[132:133]
	s_mov_b32 m0, s36
	s_nop 0
	global_load_lds_dwordx4 v[220:221], off
	s_waitcnt vmcnt(8)
	s_waitcnt lgkmcnt(0)
	s_setprio 1
	s_barrier
	v_mfma_f32_16x16x32_bf16 v[126:129], v[148:151], v[184:187], v[126:129]
	v_mfma_f32_16x16x32_bf16 v[122:125], v[156:159], v[184:187], v[122:125]
	v_mfma_f32_16x16x32_bf16 v[118:121], v[148:151], v[192:195], v[118:121]
	v_mfma_f32_16x16x32_bf16 v[110:113], v[156:159], v[192:195], v[110:113]
	v_mfma_f32_16x16x32_bf16 v[102:105], v[148:151], v[200:203], v[102:105]
	v_mfma_f32_16x16x32_bf16 v[94:97], v[156:159], v[200:203], v[94:97]
	v_mfma_f32_16x16x32_bf16 v[86:89], v[148:151], v[208:211], v[86:89]
	v_mfma_f32_16x16x32_bf16 v[78:81], v[156:159], v[208:211], v[78:81]
	v_mfma_f32_16x16x32_bf16 v[126:129], v[152:155], v[188:191], v[126:129]
	v_mfma_f32_16x16x32_bf16 v[122:125], v[160:163], v[188:191], v[122:125]
	v_mfma_f32_16x16x32_bf16 v[118:121], v[152:155], v[196:199], v[118:121]
	v_mfma_f32_16x16x32_bf16 v[110:113], v[160:163], v[196:199], v[110:113]
	v_mfma_f32_16x16x32_bf16 v[102:105], v[152:155], v[204:207], v[102:105]
	v_mfma_f32_16x16x32_bf16 v[94:97], v[160:163], v[204:207], v[94:97]
	v_mfma_f32_16x16x32_bf16 v[86:89], v[152:155], v[212:215], v[86:89]
	v_mfma_f32_16x16x32_bf16 v[78:81], v[160:163], v[212:215], v[78:81]
	s_setprio 0
	s_setprio 1
	v_mfma_f32_16x16x32_bf16 v[114:117], v[164:167], v[184:187], v[114:117]
	v_mfma_f32_16x16x32_bf16 v[106:109], v[172:175], v[184:187], v[106:109]
	v_mfma_f32_16x16x32_bf16 v[98:101], v[164:167], v[192:195], v[98:101]
	v_mfma_f32_16x16x32_bf16 v[90:93], v[172:175], v[192:195], v[90:93]
	v_mfma_f32_16x16x32_bf16 v[82:85], v[164:167], v[200:203], v[82:85]
	v_mfma_f32_16x16x32_bf16 v[74:77], v[172:175], v[200:203], v[74:77]
	v_mfma_f32_16x16x32_bf16 v[70:73], v[164:167], v[208:211], v[70:73]
	v_mfma_f32_16x16x32_bf16 v[66:69], v[172:175], v[208:211], v[66:69]
	v_mfma_f32_16x16x32_bf16 v[114:117], v[168:171], v[188:191], v[114:117]
	v_mfma_f32_16x16x32_bf16 v[106:109], v[180:183], v[188:191], v[106:109]
	v_mfma_f32_16x16x32_bf16 v[98:101], v[168:171], v[196:199], v[98:101]
	v_mfma_f32_16x16x32_bf16 v[90:93], v[180:183], v[196:199], v[90:93]
	v_mfma_f32_16x16x32_bf16 v[82:85], v[168:171], v[204:207], v[82:85]
	v_mfma_f32_16x16x32_bf16 v[74:77], v[180:183], v[204:207], v[74:77]
	v_mfma_f32_16x16x32_bf16 v[70:73], v[168:171], v[212:215], v[70:73]
	v_mfma_f32_16x16x32_bf16 v[66:69], v[180:183], v[212:215], v[66:69]
	s_barrier
; #define PG8_STAGE(bufoff, gbase, voff) do { _Pragma("unroll") for (int _i = 0; _i < 2; ++_i) \
;         __builtin_amdgcn_global_load_lds((const unsigned*)((const char*)(gbase) + (voff)[_i]), (PG8_LAS unsigned*)(lds + (bufoff) + ldsw + _i * 8192), 16, 0, 0); } while (0)
; #define PG8_LDA(dst, b, h) do { _Pragma("unroll") for (int m = 0; m < 4; ++m) _Pragma("unroll") for (int k = 0; k < 2; ++k) dst[m][k] = *(const PG8_LAS bf16x8*)(lds + PG8_SA(b, h) + aoff + m * 2048 + k * 1024); } while (0)
; #define PG8_MMA(ai, bj, At, Bt) do { __builtin_amdgcn_s_setprio(1); _Pragma("unroll") for (int m = 0; m < 4; ++m) _Pragma("unroll") for (int n = 0; n < 2; ++n) _Pragma("unroll") for (int k = 0; k < 2; ++k) \
;         acc[ai][bj][m][n] = __builtin_amdgcn_mfma_f32_16x16x32_bf16(Bt[n][k], At[m][k], acc[ai][bj][m][n], 0, 0, 0); __builtin_amdgcn_s_setprio(0); } while (0)
; #define PG8_WAIT_V(n) asm volatile("s_waitcnt vmcnt(" #n ")" ::: "memory")
; #define PG8_WAIT_L(n) asm volatile("s_waitcnt lgkmcnt(" #n ")" ::: "memory")
; #define PG8_BAR __builtin_amdgcn_s_barrier()
; #define PG8_SCHED __builtin_amdgcn_sched_barrier(0)
; template <class Epi, class Sched, bool ALIGN_EPI = true, bool SP2 = true, bool GS = false>
; __device__ __forceinline__ void gemm_phase(PG8_LAS unsigned char* lds, const Gemm g, const Sched& S, const Epi& E, const float* gs_ss = nullptr) {
;     ...
;         for (int t = 0; t < nt; t += 2) {
;             const bool last = (t == nt - 2);
;             const char* a1 = cA + (size_t)(t + 1) * kstep;
;     ...
;             PG8_LDA(At, 1, 1); PG8_STAGE(PG8_SB(1, 0), b3, voffB); PG8_STAGE(PG8_SB(1, 1), b3 + hstep, voffB); PG8_STAGE(PG8_SA(1, 0), a3, voffA);
;             PG8_WAIT_V(8); PG8_WAIT_L(0); PG8_BAR; PG8_MMA(1, 0, At, B0); PG8_MMA(1, 1, At, B1); PG8_BAR; PG8_SCHED;
	s_setprio 0
	s_add_i32 s20, s59, s23
	v_lshl_add_u64 v[142:143], v[142:143], 0, s[26:27]
	s_mov_b32 m0, s20
	ds_read_b128 v[184:187], v147 offset:49152
	ds_read_b128 v[188:191], v147 offset:50176
	ds_read_b128 v[192:195], v147 offset:51200
	ds_read_b128 v[196:199], v147 offset:52224
	ds_read_b128 v[200:203], v147 offset:53248
	ds_read_b128 v[204:207], v147 offset:54272
	ds_read_b128 v[208:211], v147 offset:55296
	ds_read_b128 v[212:215], v147 offset:56320
	global_load_lds_dwordx4 v[142:143], off
	s_add_i32 m0, s20, 0x2000
	s_add_u32 s2, s2, 0x80080
	v_lshl_add_u64 v[142:143], v[176:177], 0, s[26:27]
	s_addc_u32 s3, s3, 0
	s_add_i32 s20, s60, s23
	global_load_lds_dwordx4 v[142:143], off
	v_lshl_add_u64 v[142:143], s[2:3], 0, v[134:135]
	s_mov_b32 m0, s20
	s_nop 0
	global_load_lds_dwordx4 v[142:143], off
	v_lshl_add_u64 v[142:143], s[2:3], 0, v[130:131]
	s_add_i32 m0, s20, 0x2000
	s_nop 0
	global_load_lds_dwordx4 v[142:143], off
	v_lshl_add_u64 v[142:143], v[216:217], 0, s[26:27]
	s_mov_b32 m0, s47
	s_nop 0
	global_load_lds_dwordx4 v[142:143], off
	v_lshl_add_u64 v[142:143], v[218:219], 0, s[26:27]
	s_mov_b32 m0, s48
	s_nop 0
	global_load_lds_dwordx4 v[142:143], off
	s_waitcnt vmcnt(8)
	s_waitcnt lgkmcnt(0)
	s_setprio 1
	s_barrier
	v_mfma_f32_16x16x32_bf16 v[62:65], v[148:151], v[184:187], v[62:65]
	v_mfma_f32_16x16x32_bf16 v[58:61], v[156:159], v[184:187], v[58:61]
	v_mfma_f32_16x16x32_bf16 v[54:57], v[148:151], v[192:195], v[54:57]
	v_mfma_f32_16x16x32_bf16 v[46:49], v[156:159], v[192:195], v[46:49]
	v_mfma_f32_16x16x32_bf16 v[38:41], v[148:151], v[200:203], v[38:41]
	v_mfma_f32_16x16x32_bf16 v[30:33], v[156:159], v[200:203], v[30:33]
	v_mfma_f32_16x16x32_bf16 v[22:25], v[148:151], v[208:211], v[22:25]
	v_mfma_f32_16x16x32_bf16 v[14:17], v[156:159], v[208:211], v[14:17]
	v_mfma_f32_16x16x32_bf16 v[62:65], v[152:155], v[188:191], v[62:65]
	v_mfma_f32_16x16x32_bf16 v[58:61], v[160:163], v[188:191], v[58:61]
	v_mfma_f32_16x16x32_bf16 v[54:57], v[152:155], v[196:199], v[54:57]
	v_mfma_f32_16x16x32_bf16 v[46:49], v[160:163], v[196:199], v[46:49]
	v_mfma_f32_16x16x32_bf16 v[38:41], v[152:155], v[204:207], v[38:41]
	v_mfma_f32_16x16x32_bf16 v[30:33], v[160:163], v[204:207], v[30:33]
	v_mfma_f32_16x16x32_bf16 v[22:25], v[152:155], v[212:215], v[22:25]
	v_mfma_f32_16x16x32_bf16 v[14:17], v[160:163], v[212:215], v[14:17]
	s_setprio 0
	s_setprio 1
	v_mfma_f32_16x16x32_bf16 v[50:53], v[164:167], v[184:187], v[50:53]
	v_mfma_f32_16x16x32_bf16 v[42:45], v[172:175], v[184:187], v[42:45]
	v_mfma_f32_16x16x32_bf16 v[34:37], v[164:167], v[192:195], v[34:37]
	v_mfma_f32_16x16x32_bf16 v[26:29], v[172:175], v[192:195], v[26:29]
	v_mfma_f32_16x16x32_bf16 v[18:21], v[164:167], v[200:203], v[18:21]
	v_mfma_f32_16x16x32_bf16 v[10:13], v[172:175], v[200:203], v[10:13]
	v_mfma_f32_16x16x32_bf16 v[6:9], v[164:167], v[208:211], v[6:9]
	v_mfma_f32_16x16x32_bf16 v[2:5], v[172:175], v[208:211], v[2:5]
	v_mfma_f32_16x16x32_bf16 v[50:53], v[168:171], v[188:191], v[50:53]
	v_mfma_f32_16x16x32_bf16 v[42:45], v[180:183], v[188:191], v[42:45]
	v_mfma_f32_16x16x32_bf16 v[34:37], v[168:171], v[196:199], v[34:37]
	v_mfma_f32_16x16x32_bf16 v[26:29], v[180:183], v[196:199], v[26:29]
	v_mfma_f32_16x16x32_bf16 v[18:21], v[168:171], v[204:207], v[18:21]
	v_mfma_f32_16x16x32_bf16 v[10:13], v[180:183], v[204:207], v[10:13]
	v_mfma_f32_16x16x32_bf16 v[6:9], v[168:171], v[212:215], v[6:9]
	v_mfma_f32_16x16x32_bf16 v[2:5], v[180:183], v[212:215], v[2:5]
	s_barrier
	s_setprio 0
	s_add_i32 s58, s58, 2
	s_add_u32 s44, s44, 0x100
	s_addc_u32 s45, s45, 0
	s_add_u32 s56, s56, 0x100
	s_addc_u32 s57, s57, 0
	s_cmp_gt_u32 s58, 5
	s_cbranch_scc0 .LBB0_1119
	s_and_b64 vcc, exec, s[38:39]
	s_cbranch_vccz .LBB0_1122
	s_barrier

;     __device__ __forceinline__ size_t a_extra(const Unit& u) const { return (size_t)(u.pn >> 1) * ((size_t)T * 512 * 2); }
;     __device__ __forceinline__ size_t a_extra(const Unit& u) const { return (size_t)(u.pn >> 1) * 512 * 2; }
;     __device__ __forceinline__ size_t b_extra(const Unit& u) const { return (size_t)(u.pn >> 1) * 512 * 2 - (size_t)(u.pn & ~1) * ((size_t)256 * D * 2); }
; #define PG8_STAGE(bufoff, gbase, voff) do { _Pragma("unroll") for (int _i = 0; _i < 2; ++_i) \
;         __builtin_amdgcn_global_load_lds((const unsigned*)((const char*)(gbase) + (voff)[_i]), (PG8_LAS unsigned*)(lds + (bufoff) + ldsw + _i * 8192), 16, 0, 0); } while (0)
; #define PG8_LDA(dst, b, h) do { _Pragma("unroll") for (int m = 0; m < 4; ++m) _Pragma("unroll") for (int k = 0; k < 2; ++k) dst[m][k] = *(const PG8_LAS bf16x8*)(lds + PG8_SA(b, h) + aoff + m * 2048 + k * 1024); } while (0)
; #define PG8_WAIT_V(n) asm volatile("s_waitcnt vmcnt(" #n ")" ::: "memory")
; #define PG8_WAIT_L(n) asm volatile("s_waitcnt lgkmcnt(" #n ")" ::: "memory")
; template <class Epi, class Sched, bool ALIGN_EPI = true, bool SP2 = true, bool GS = false>
; __device__ __forceinline__ void gemm_phase(PG8_LAS unsigned char* lds, const Gemm g, const Sched& S, const Epi& E, const float* gs_ss = nullptr) {
;     ...
;         const char* nA = has_next ? (const char*)g.A + S.a_extra(nxt) + (size_t)nxt.pm * tstep : cA; const char* nB = has_next ? (const char*)g.Bt + S.b_extra(nxt) + (size_t)nxt.pn * tstep : cB;
;         for (int t = 0; t < nt; t += 2) {
;             const bool last = (t == nt - 2);
;             const char* a1 = cA + (size_t)(t + 1) * kstep;
;             const char* a2 = last ? nA : cA + (size_t)(t + 2) * kstep; const char* b2 = last ? nB : cB + (size_t)(t + 2) * kstep;
;             const char* a3 = a2 + kstep; const char* b3 = b2 + kstep;
;             if constexpr (SP2) {
;             PG8_LDB(B0, 0, 0); PG8_LDB(B1, 0, 1); PG8_SCHED; PG8_LDA(At, 0, 0); PG8_STAGE(PG8_SA(1, 1), a1 + hstep, voffA);
;             PG8_WAIT_V(8); PG8_WAIT_L(0); PG8_BAR; PG8_MMA(0, 0, At, B0); PG8_MMA(0, 1, At, B1); PG8_BAR; PG8_SCHED;
;             PG8_LDA(At, 0, 1); PG8_STAGE(PG8_SB(0, 0), b2, voffB); PG8_STAGE(PG8_SB(0, 1), b2 + hstep, voffB); PG8_STAGE(PG8_SA(0, 0), a2, voffA);
;             PG8_WAIT_V(8); PG8_WAIT_L(0); PG8_BAR; PG8_MMA(1, 0, At, B0); PG8_MMA(1, 1, At, B1); PG8_BAR; PG8_SCHED;
.LBB0_1252:
	s_add_u32 s2, s56, 0xfffe0080
	s_addc_u32 s3, s57, -1
	s_add_i32 s65, 0, 0x10000
	s_cmp_eq_u32 s64, 4
	s_cselect_b32 s21, s18, s3
	s_cselect_b32 s20, s51, s2
	s_cselect_b32 s3, s49, s59
	s_cselect_b32 s2, s63, s58
	s_add_i32 s67, 0, 0x14000
	v_add_u32_e32 v142, s65, v183
	v_add_u32_e32 v168, s67, v183
	ds_read_b128 v[122:125], v142
	ds_read_b128 v[130:133], v142 offset:1024
	ds_read_b128 v[138:141], v142 offset:2048
	ds_read_b128 v[142:145], v142 offset:3072
	ds_read_b128 v[156:159], v168
	ds_read_b128 v[160:163], v168 offset:1024
	ds_read_b128 v[164:167], v168 offset:2048
	ds_read_b128 v[168:171], v168 offset:3072
	v_lshl_add_u64 v[176:177], s[56:57], 0, v[152:153]
	s_add_i32 m0, s9, 0xc000
	ds_read_b128 v[172:175], v197
	ds_read_b128 v[184:187], v197 offset:1024
	ds_read_b128 v[188:191], v197 offset:2048
	ds_read_b128 v[192:195], v197 offset:3072
	ds_read_b128 v[198:201], v197 offset:4096
	ds_read_b128 v[202:205], v197 offset:5120
	ds_read_b128 v[206:209], v197 offset:6144
	ds_read_b128 v[210:213], v197 offset:7168
	global_load_lds_dwordx4 v[176:177], off
	v_lshl_add_u64 v[176:177], s[56:57], 0, v[154:155]
	s_add_i32 m0, s9, 0xe000
	s_nop 0
	global_load_lds_dwordx4 v[176:177], off
	s_waitcnt vmcnt(8)
	s_waitcnt lgkmcnt(0)
	s_setprio 1
	s_barrier
	v_mfma_f32_16x16x32_bf16 v[134:137], v[122:125], v[172:175], v[134:137]
	v_mfma_f32_16x16x32_bf16 v[126:129], v[138:141], v[172:175], v[126:129]
	v_mfma_f32_16x16x32_bf16 v[110:113], v[122:125], v[188:191], v[110:113]
	v_mfma_f32_16x16x32_bf16 v[106:109], v[138:141], v[188:191], v[106:109]
	v_mfma_f32_16x16x32_bf16 v[94:97], v[122:125], v[198:201], v[94:97]
	v_mfma_f32_16x16x32_bf16 v[90:93], v[138:141], v[198:201], v[90:93]
	v_mfma_f32_16x16x32_bf16 v[78:81], v[122:125], v[206:209], v[78:81]
	v_mfma_f32_16x16x32_bf16 v[74:77], v[138:141], v[206:209], v[74:77]
	v_mfma_f32_16x16x32_bf16 v[134:137], v[130:133], v[184:187], v[134:137]
	v_mfma_f32_16x16x32_bf16 v[126:129], v[142:145], v[184:187], v[126:129]
	v_mfma_f32_16x16x32_bf16 v[110:113], v[130:133], v[192:195], v[110:113]
	v_mfma_f32_16x16x32_bf16 v[106:109], v[142:145], v[192:195], v[106:109]
	v_mfma_f32_16x16x32_bf16 v[94:97], v[130:133], v[202:205], v[94:97]
	v_mfma_f32_16x16x32_bf16 v[90:93], v[142:145], v[202:205], v[90:93]
	v_mfma_f32_16x16x32_bf16 v[78:81], v[130:133], v[210:213], v[78:81]
	v_mfma_f32_16x16x32_bf16 v[74:77], v[142:145], v[210:213], v[74:77]
	s_setprio 0
	s_setprio 1
	v_mfma_f32_16x16x32_bf16 v[118:121], v[156:159], v[172:175], v[118:121]
	v_mfma_f32_16x16x32_bf16 v[114:117], v[164:167], v[172:175], v[114:117]
	v_mfma_f32_16x16x32_bf16 v[102:105], v[156:159], v[188:191], v[102:105]
	v_mfma_f32_16x16x32_bf16 v[98:101], v[164:167], v[188:191], v[98:101]
	v_mfma_f32_16x16x32_bf16 v[86:89], v[156:159], v[198:201], v[86:89]
	v_mfma_f32_16x16x32_bf16 v[82:85], v[164:167], v[198:201], v[82:85]
	v_mfma_f32_16x16x32_bf16 v[70:73], v[156:159], v[206:209], v[70:73]
	v_mfma_f32_16x16x32_bf16 v[66:69], v[164:167], v[206:209], v[66:69]
	v_mfma_f32_16x16x32_bf16 v[118:121], v[160:163], v[184:187], v[118:121]
	v_mfma_f32_16x16x32_bf16 v[114:117], v[168:171], v[184:187], v[114:117]
	v_mfma_f32_16x16x32_bf16 v[102:105], v[160:163], v[192:195], v[102:105]
	v_mfma_f32_16x16x32_bf16 v[98:101], v[168:171], v[192:195], v[98:101]
	v_mfma_f32_16x16x32_bf16 v[86:89], v[160:163], v[202:205], v[86:89]
	v_mfma_f32_16x16x32_bf16 v[82:85], v[168:171], v[202:205], v[82:85]
	v_mfma_f32_16x16x32_bf16 v[70:73], v[160:163], v[210:213], v[70:73]
	v_mfma_f32_16x16x32_bf16 v[66:69], v[168:171], v[210:213], v[66:69]
	s_barrier
	s_setprio 0
	s_add_i32 s65, s65, s24
	v_lshl_add_u64 v[176:177], s[2:3], 0, v[0:1]
	s_mov_b32 m0, s65
	ds_read_b128 v[172:175], v197 offset:16384
	ds_read_b128 v[184:187], v197 offset:17408
	ds_read_b128 v[188:191], v197 offset:18432
	ds_read_b128 v[192:195], v197 offset:19456
	ds_read_b128 v[198:201], v197 offset:20480
	ds_read_b128 v[202:205], v197 offset:21504
	ds_read_b128 v[206:209], v197 offset:22528
	ds_read_b128 v[210:213], v197 offset:23552
	global_load_lds_dwordx4 v[176:177], off
	s_add_i32 m0, s65, 0x2000
	s_add_u32 s70, s2, 0x20000
	v_lshl_add_u64 v[180:181], s[2:3], 0, v[150:151]
	s_addc_u32 s71, s3, 0
	s_add_i32 s65, s67, s24
	global_load_lds_dwordx4 v[180:181], off
	v_lshl_add_u64 v[214:215], s[70:71], 0, v[0:1]
	s_mov_b32 m0, s65
	v_lshl_add_u64 v[216:217], s[20:21], 0, v[148:149]
	global_load_lds_dwordx4 v[214:215], off
	v_lshl_add_u64 v[214:215], s[70:71], 0, v[150:151]
	s_add_i32 m0, s65, 0x2000
	s_nop 0
	global_load_lds_dwordx4 v[214:215], off
	v_lshl_add_u64 v[214:215], s[20:21], 0, v[146:147]
	s_mov_b32 m0, s9
	s_nop 0
	global_load_lds_dwordx4 v[214:215], off
	s_mov_b32 m0, s13
	s_nop 0
	global_load_lds_dwordx4 v[216:217], off
	s_waitcnt vmcnt(8)
	s_waitcnt lgkmcnt(0)
	s_setprio 1
	s_barrier
; #define PG8_STAGE(bufoff, gbase, voff) do { _Pragma("unroll") for (int _i = 0; _i < 2; ++_i) \
;         __builtin_amdgcn_global_load_lds((const unsigned*)((const char*)(gbase) + (voff)[_i]), (PG8_LAS unsigned*)(lds + (bufoff) + ldsw + _i * 8192), 16, 0, 0); } while (0)
; #define PG8_LDA(dst, b, h) do { _Pragma("unroll") for (int m = 0; m < 4; ++m) _Pragma("unroll") for (int k = 0; k < 2; ++k) dst[m][k] = *(const PG8_LAS bf16x8*)(lds + PG8_SA(b, h) + aoff + m * 2048 + k * 1024); } while (0)
; #define PG8_LDB(dst, b, h) do { _Pragma("unroll") for (int n = 0; n < 2; ++n) _Pragma("unroll") for (int k = 0; k < 2; ++k) dst[n][k] = *(const PG8_LAS bf16x8*)(lds + PG8_SB(b, h) + boff + n * 2048 + k * 1024); } while (0)
; #define PG8_MMA(ai, bj, At, Bt) do { __builtin_amdgcn_s_setprio(1); _Pragma("unroll") for (int m = 0; m < 4; ++m) _Pragma("unroll") for (int n = 0; n < 2; ++n) _Pragma("unroll") for (int k = 0; k < 2; ++k) \
;         acc[ai][bj][m][n] = __builtin_amdgcn_mfma_f32_16x16x32_bf16(Bt[n][k], At[m][k], acc[ai][bj][m][n], 0, 0, 0); __builtin_amdgcn_s_setprio(0); } while (0)
; #define PG8_WAIT_V(n) asm volatile("s_waitcnt vmcnt(" #n ")" ::: "memory")
; #define PG8_WAIT_L(n) asm volatile("s_waitcnt lgkmcnt(" #n ")" ::: "memory")
; #define PG8_BAR __builtin_amdgcn_s_barrier()
; #define PG8_SCHED __builtin_amdgcn_sched_barrier(0)
; template <class Epi, class Sched, bool ALIGN_EPI = true, bool SP2 = true, bool GS = false>
; __device__ __forceinline__ void gemm_phase(PG8_LAS unsigned char* lds, const Gemm g, const Sched& S, const Epi& E, const float* gs_ss = nullptr) {
;     ...
;             PG8_WAIT_V(8); PG8_WAIT_L(0); PG8_BAR; PG8_MMA(1, 0, At, B0); PG8_MMA(1, 1, At, B1); PG8_BAR; PG8_SCHED;
;             PG8_LDB(B0, 1, 0); PG8_LDB(B1, 1, 1); PG8_SCHED; PG8_LDA(At, 1, 0); PG8_STAGE(PG8_SA(0, 1), a2 + hstep, voffA);
;             PG8_WAIT_V(8); PG8_WAIT_L(0); PG8_BAR; PG8_MMA(0, 0, At, B0); PG8_MMA(0, 1, At, B1); PG8_BAR; PG8_SCHED;
	v_mfma_f32_16x16x32_bf16 v[62:65], v[122:125], v[172:175], v[62:65]
	v_mfma_f32_16x16x32_bf16 v[58:61], v[138:141], v[172:175], v[58:61]
	v_mfma_f32_16x16x32_bf16 v[46:49], v[122:125], v[188:191], v[46:49]
	v_mfma_f32_16x16x32_bf16 v[42:45], v[138:141], v[188:191], v[42:45]
	v_mfma_f32_16x16x32_bf16 v[30:33], v[122:125], v[198:201], v[30:33]
	v_mfma_f32_16x16x32_bf16 v[26:29], v[138:141], v[198:201], v[26:29]
	v_mfma_f32_16x16x32_bf16 v[14:17], v[122:125], v[206:209], v[14:17]
	v_mfma_f32_16x16x32_bf16 v[10:13], v[138:141], v[206:209], v[10:13]
	v_mfma_f32_16x16x32_bf16 v[62:65], v[130:133], v[184:187], v[62:65]
	v_mfma_f32_16x16x32_bf16 v[58:61], v[142:145], v[184:187], v[58:61]
	v_mfma_f32_16x16x32_bf16 v[46:49], v[130:133], v[192:195], v[46:49]
	v_mfma_f32_16x16x32_bf16 v[42:45], v[142:145], v[192:195], v[42:45]
	v_mfma_f32_16x16x32_bf16 v[30:33], v[130:133], v[202:205], v[30:33]
	v_mfma_f32_16x16x32_bf16 v[26:29], v[142:145], v[202:205], v[26:29]
	v_mfma_f32_16x16x32_bf16 v[14:17], v[130:133], v[210:213], v[14:17]
	v_mfma_f32_16x16x32_bf16 v[10:13], v[142:145], v[210:213], v[10:13]
	s_setprio 0
	s_setprio 1
	v_mfma_f32_16x16x32_bf16 v[54:57], v[156:159], v[172:175], v[54:57]
	v_mfma_f32_16x16x32_bf16 v[50:53], v[164:167], v[172:175], v[50:53]
	v_mfma_f32_16x16x32_bf16 v[38:41], v[156:159], v[188:191], v[38:41]
	v_mfma_f32_16x16x32_bf16 v[34:37], v[164:167], v[188:191], v[34:37]
	v_mfma_f32_16x16x32_bf16 v[22:25], v[156:159], v[198:201], v[22:25]
	v_mfma_f32_16x16x32_bf16 v[18:21], v[164:167], v[198:201], v[18:21]
	v_mfma_f32_16x16x32_bf16 v[6:9], v[156:159], v[206:209], v[6:9]
	v_mfma_f32_16x16x32_bf16 v[2:5], v[164:167], v[206:209], v[2:5]
	v_mfma_f32_16x16x32_bf16 v[54:57], v[160:163], v[184:187], v[54:57]
	v_mfma_f32_16x16x32_bf16 v[50:53], v[168:171], v[184:187], v[50:53]
	v_mfma_f32_16x16x32_bf16 v[38:41], v[160:163], v[192:195], v[38:41]
	v_mfma_f32_16x16x32_bf16 v[34:37], v[168:171], v[192:195], v[34:37]
	v_mfma_f32_16x16x32_bf16 v[22:25], v[160:163], v[202:205], v[22:25]
	v_mfma_f32_16x16x32_bf16 v[18:21], v[168:171], v[202:205], v[18:21]
	v_mfma_f32_16x16x32_bf16 v[6:9], v[160:163], v[210:213], v[6:9]
	v_mfma_f32_16x16x32_bf16 v[2:5], v[168:171], v[210:213], v[2:5]
	s_barrier
	s_setprio 0
	s_add_i32 s65, 0, 0x18000
	s_add_i32 s67, 0, 0x1c000
	v_add_u32_e32 v142, s65, v183
	v_add_u32_e32 v168, s67, v183
	ds_read_b128 v[122:125], v142
	ds_read_b128 v[130:133], v142 offset:1024
	ds_read_b128 v[138:141], v142 offset:2048
	ds_read_b128 v[142:145], v142 offset:3072
	ds_read_b128 v[156:159], v168
	ds_read_b128 v[160:163], v168 offset:1024
	ds_read_b128 v[164:167], v168 offset:2048
	ds_read_b128 v[168:171], v168 offset:3072
	s_add_u32 s20, s20, 0x20000
	s_addc_u32 s21, s21, 0
	s_mov_b32 m0, s25
	v_lshl_add_u64 v[218:219], s[20:21], 0, v[146:147]
	ds_read_b128 v[172:175], v197 offset:32768
	ds_read_b128 v[184:187], v197 offset:33792
	ds_read_b128 v[188:191], v197 offset:34816
	ds_read_b128 v[192:195], v197 offset:35840
	ds_read_b128 v[198:201], v197 offset:36864
	ds_read_b128 v[202:205], v197 offset:37888
	ds_read_b128 v[206:209], v197 offset:38912
	ds_read_b128 v[210:213], v197 offset:39936
	global_load_lds_dwordx4 v[218:219], off
	v_lshl_add_u64 v[218:219], s[20:21], 0, v[148:149]
	s_mov_b32 m0, s30
	s_nop 0
	global_load_lds_dwordx4 v[218:219], off
	s_waitcnt vmcnt(8)
	s_waitcnt lgkmcnt(0)
	s_setprio 1
	s_barrier
	v_mfma_f32_16x16x32_bf16 v[134:137], v[122:125], v[172:175], v[134:137]
	v_mfma_f32_16x16x32_bf16 v[126:129], v[138:141], v[172:175], v[126:129]
	v_mfma_f32_16x16x32_bf16 v[110:113], v[122:125], v[188:191], v[110:113]
	v_mfma_f32_16x16x32_bf16 v[106:109], v[138:141], v[188:191], v[106:109]
	v_mfma_f32_16x16x32_bf16 v[94:97], v[122:125], v[198:201], v[94:97]
	v_mfma_f32_16x16x32_bf16 v[90:93], v[138:141], v[198:201], v[90:93]
	v_mfma_f32_16x16x32_bf16 v[78:81], v[122:125], v[206:209], v[78:81]
	v_mfma_f32_16x16x32_bf16 v[74:77], v[138:141], v[206:209], v[74:77]
	v_mfma_f32_16x16x32_bf16 v[134:137], v[130:133], v[184:187], v[134:137]
	v_mfma_f32_16x16x32_bf16 v[126:129], v[142:145], v[184:187], v[126:129]
	v_mfma_f32_16x16x32_bf16 v[110:113], v[130:133], v[192:195], v[110:113]
	v_mfma_f32_16x16x32_bf16 v[106:109], v[142:145], v[192:195], v[106:109]
	v_mfma_f32_16x16x32_bf16 v[94:97], v[130:133], v[202:205], v[94:97]
	v_mfma_f32_16x16x32_bf16 v[90:93], v[142:145], v[202:205], v[90:93]
	v_mfma_f32_16x16x32_bf16 v[78:81], v[130:133], v[210:213], v[78:81]
	v_mfma_f32_16x16x32_bf16 v[74:77], v[142:145], v[210:213], v[74:77]
	s_setprio 0
	s_setprio 1
	v_mfma_f32_16x16x32_bf16 v[118:121], v[156:159], v[172:175], v[118:121]
	v_mfma_f32_16x16x32_bf16 v[114:117], v[164:167], v[172:175], v[114:117]
	v_mfma_f32_16x16x32_bf16 v[102:105], v[156:159], v[188:191], v[102:105]
	v_mfma_f32_16x16x32_bf16 v[98:101], v[164:167], v[188:191], v[98:101]
	v_mfma_f32_16x16x32_bf16 v[86:89], v[156:159], v[198:201], v[86:89]
	v_mfma_f32_16x16x32_bf16 v[82:85], v[164:167], v[198:201], v[82:85]
	v_mfma_f32_16x16x32_bf16 v[70:73], v[156:159], v[206:209], v[70:73]
	v_mfma_f32_16x16x32_bf16 v[66:69], v[164:167], v[206:209], v[66:69]
	v_mfma_f32_16x16x32_bf16 v[118:121], v[160:163], v[184:187], v[118:121]
	v_mfma_f32_16x16x32_bf16 v[114:117], v[168:171], v[184:187], v[114:117]
	v_mfma_f32_16x16x32_bf16 v[102:105], v[160:163], v[192:195], v[102:105]
	v_mfma_f32_16x16x32_bf16 v[98:101], v[168:171], v[192:195], v[98:101]
	v_mfma_f32_16x16x32_bf16 v[86:89], v[160:163], v[202:205], v[86:89]
	v_mfma_f32_16x16x32_bf16 v[82:85], v[168:171], v[202:205], v[82:85]
	v_mfma_f32_16x16x32_bf16 v[70:73], v[160:163], v[210:213], v[70:73]
	v_mfma_f32_16x16x32_bf16 v[66:69], v[168:171], v[210:213], v[66:69]
	s_barrier
; #define PG8_LAS __attribute__((address_space(3)))
; #define PG8_STAGE(bufoff, gbase, voff) do { _Pragma("unroll") for (int _i = 0; _i < 2; ++_i) \
;         __builtin_amdgcn_global_load_lds((const unsigned*)((const char*)(gbase) + (voff)[_i]), (PG8_LAS unsigned*)(lds + (bufoff) + ldsw + _i * 8192), 16, 0, 0); } while (0)
; #define PG8_LDA(dst, b, h) do { _Pragma("unroll") for (int m = 0; m < 4; ++m) _Pragma("unroll") for (int k = 0; k < 2; ++k) dst[m][k] = *(const PG8_LAS bf16x8*)(lds + PG8_SA(b, h) + aoff + m * 2048 + k * 1024); } while (0)
; #define PG8_MMA(ai, bj, At, Bt) do { __builtin_amdgcn_s_setprio(1); _Pragma("unroll") for (int m = 0; m < 4; ++m) _Pragma("unroll") for (int n = 0; n < 2; ++n) _Pragma("unroll") for (int k = 0; k < 2; ++k) \
;         acc[ai][bj][m][n] = __builtin_amdgcn_mfma_f32_16x16x32_bf16(Bt[n][k], At[m][k], acc[ai][bj][m][n], 0, 0, 0); __builtin_amdgcn_s_setprio(0); } while (0)
; #define PG8_WAIT_V(n) asm volatile("s_waitcnt vmcnt(" #n ")" ::: "memory")
; #define PG8_WAIT_L(n) asm volatile("s_waitcnt lgkmcnt(" #n ")" ::: "memory")
; #define PG8_BAR __builtin_amdgcn_s_barrier()
; #define PG8_SCHED __builtin_amdgcn_sched_barrier(0)
; template <class Epi, class Sched, bool ALIGN_EPI = true, bool SP2 = true, bool GS = false>
; __device__ __forceinline__ void gemm_phase(PG8_LAS unsigned char* lds, const Gemm g, const Sched& S, const Epi& E, const float* gs_ss = nullptr) {
;     ...
;             PG8_LDA(At, 1, 1); PG8_STAGE(PG8_SB(1, 0), b3, voffB); PG8_STAGE(PG8_SB(1, 1), b3 + hstep, voffB); PG8_STAGE(PG8_SA(1, 0), a3, voffA);
;             PG8_WAIT_V(8); PG8_WAIT_L(0); PG8_BAR; PG8_MMA(1, 0, At, B0); PG8_MMA(1, 1, At, B1); PG8_BAR; PG8_SCHED;
;     ...
;         if constexpr (ALIGN_EPI) { if (wr == 0) PG8_BAR; }
;         if constexpr (GS) E.gs(acc, cur, wr, wc, fr, fq, (const PG8_LAS float*)(lds + STAGE_BYTES + gpar * 4096)); else E(acc, cur, wr, wc, fr, fq);
;         if (!has_next) break;
	s_setprio 0
	s_add_i32 s20, s65, s24
	v_lshl_add_u64 v[176:177], v[176:177], 0, s[26:27]
	s_mov_b32 m0, s20
	ds_read_b128 v[172:175], v197 offset:49152
	ds_read_b128 v[184:187], v197 offset:50176
	ds_read_b128 v[188:191], v197 offset:51200
	ds_read_b128 v[192:195], v197 offset:52224
	ds_read_b128 v[198:201], v197 offset:53248
	ds_read_b128 v[202:205], v197 offset:54272
	ds_read_b128 v[206:209], v197 offset:55296
	ds_read_b128 v[210:213], v197 offset:56320
	global_load_lds_dwordx4 v[176:177], off
	s_add_i32 m0, s20, 0x2000
	s_add_u32 s2, s2, 0x20080
	v_lshl_add_u64 v[176:177], v[180:181], 0, s[26:27]
	s_addc_u32 s3, s3, 0
	s_add_i32 s20, s67, s24
	global_load_lds_dwordx4 v[176:177], off
	v_lshl_add_u64 v[176:177], s[2:3], 0, v[0:1]
	s_mov_b32 m0, s20
	s_nop 0
	global_load_lds_dwordx4 v[176:177], off
	v_lshl_add_u64 v[176:177], s[2:3], 0, v[150:151]
	s_add_i32 m0, s20, 0x2000
	s_nop 0
	global_load_lds_dwordx4 v[176:177], off
	v_lshl_add_u64 v[176:177], v[214:215], 0, s[26:27]
	s_mov_b32 m0, s37
	s_nop 0
	global_load_lds_dwordx4 v[176:177], off
	v_lshl_add_u64 v[176:177], v[216:217], 0, s[26:27]
	s_mov_b32 m0, s60
	s_nop 0
	global_load_lds_dwordx4 v[176:177], off
	s_waitcnt vmcnt(8)
	s_waitcnt lgkmcnt(0)
	s_setprio 1
	s_barrier
	v_mfma_f32_16x16x32_bf16 v[62:65], v[122:125], v[172:175], v[62:65]
	v_mfma_f32_16x16x32_bf16 v[58:61], v[138:141], v[172:175], v[58:61]
	v_mfma_f32_16x16x32_bf16 v[46:49], v[122:125], v[188:191], v[46:49]
	v_mfma_f32_16x16x32_bf16 v[42:45], v[138:141], v[188:191], v[42:45]
	v_mfma_f32_16x16x32_bf16 v[30:33], v[122:125], v[198:201], v[30:33]
	v_mfma_f32_16x16x32_bf16 v[26:29], v[138:141], v[198:201], v[26:29]
	v_mfma_f32_16x16x32_bf16 v[14:17], v[122:125], v[206:209], v[14:17]
	v_mfma_f32_16x16x32_bf16 v[10:13], v[138:141], v[206:209], v[10:13]
	v_mfma_f32_16x16x32_bf16 v[62:65], v[130:133], v[184:187], v[62:65]
	v_mfma_f32_16x16x32_bf16 v[58:61], v[142:145], v[184:187], v[58:61]
	v_mfma_f32_16x16x32_bf16 v[46:49], v[130:133], v[192:195], v[46:49]
	v_mfma_f32_16x16x32_bf16 v[42:45], v[142:145], v[192:195], v[42:45]
	v_mfma_f32_16x16x32_bf16 v[30:33], v[130:133], v[202:205], v[30:33]
	v_mfma_f32_16x16x32_bf16 v[26:29], v[142:145], v[202:205], v[26:29]
	v_mfma_f32_16x16x32_bf16 v[14:17], v[130:133], v[210:213], v[14:17]
	v_mfma_f32_16x16x32_bf16 v[10:13], v[142:145], v[210:213], v[10:13]
	s_setprio 0
	s_setprio 1
	v_mfma_f32_16x16x32_bf16 v[54:57], v[156:159], v[172:175], v[54:57]
	v_mfma_f32_16x16x32_bf16 v[50:53], v[164:167], v[172:175], v[50:53]
	v_mfma_f32_16x16x32_bf16 v[38:41], v[156:159], v[188:191], v[38:41]
	v_mfma_f32_16x16x32_bf16 v[34:37], v[164:167], v[188:191], v[34:37]
	v_mfma_f32_16x16x32_bf16 v[22:25], v[156:159], v[198:201], v[22:25]
	v_mfma_f32_16x16x32_bf16 v[18:21], v[164:167], v[198:201], v[18:21]
	v_mfma_f32_16x16x32_bf16 v[6:9], v[156:159], v[206:209], v[6:9]
	v_mfma_f32_16x16x32_bf16 v[2:5], v[164:167], v[206:209], v[2:5]
	v_mfma_f32_16x16x32_bf16 v[54:57], v[160:163], v[184:187], v[54:57]
	v_mfma_f32_16x16x32_bf16 v[50:53], v[168:171], v[184:187], v[50:53]
	v_mfma_f32_16x16x32_bf16 v[38:41], v[160:163], v[192:195], v[38:41]
	v_mfma_f32_16x16x32_bf16 v[34:37], v[168:171], v[192:195], v[34:37]
	v_mfma_f32_16x16x32_bf16 v[22:25], v[160:163], v[202:205], v[22:25]
	v_mfma_f32_16x16x32_bf16 v[18:21], v[168:171], v[202:205], v[18:21]
	v_mfma_f32_16x16x32_bf16 v[6:9], v[160:163], v[210:213], v[6:9]
	v_mfma_f32_16x16x32_bf16 v[2:5], v[168:171], v[210:213], v[2:5]
	s_barrier
	s_setprio 0
	s_add_i32 s64, s64, 2
	s_add_u32 s56, s56, 0x100
	s_addc_u32 s57, s57, 0
	s_add_u32 s58, s58, 0x100
	s_addc_u32 s59, s59, 0
	s_cmp_gt_u32 s64, 5
	s_cbranch_scc0 .LBB0_1252
	s_and_b64 vcc, exec, s[46:47]
	s_cbranch_vccz .LBB0_1255
	s_barrier

; #define PG8_STAGE(bufoff, gbase, voff) do { _Pragma("unroll") for (int _i = 0; _i < 2; ++_i) \
;         __builtin_amdgcn_global_load_lds((const unsigned*)((const char*)(gbase) + (voff)[_i]), (PG8_LAS unsigned*)(lds + (bufoff) + ldsw + _i * 8192), 16, 0, 0); } while (0)
; #define PG8_LDA(dst, b, h) do { _Pragma("unroll") for (int m = 0; m < 4; ++m) _Pragma("unroll") for (int k = 0; k < 2; ++k) dst[m][k] = *(const PG8_LAS bf16x8*)(lds + PG8_SA(b, h) + aoff + m * 2048 + k * 1024); } while (0)
; #define PG8_LDB(dst, b, h) do { _Pragma("unroll") for (int n = 0; n < 2; ++n) _Pragma("unroll") for (int k = 0; k < 2; ++k) dst[n][k] = *(const PG8_LAS bf16x8*)(lds + PG8_SB(b, h) + boff + n * 2048 + k * 1024); } while (0)
; #define PG8_MMA(ai, bj, At, Bt) do { __builtin_amdgcn_s_setprio(1); _Pragma("unroll") for (int m = 0; m < 4; ++m) _Pragma("unroll") for (int n = 0; n < 2; ++n) _Pragma("unroll") for (int k = 0; k < 2; ++k) \
;         acc[ai][bj][m][n] = __builtin_amdgcn_mfma_f32_16x16x32_bf16(Bt[n][k], At[m][k], acc[ai][bj][m][n], 0, 0, 0); __builtin_amdgcn_s_setprio(0); } while (0)
; #define PG8_WAIT_V(n) asm volatile("s_waitcnt vmcnt(" #n ")" ::: "memory")
; #define PG8_WAIT_L(n) asm volatile("s_waitcnt lgkmcnt(" #n ")" ::: "memory")
; #define PG8_BAR __builtin_amdgcn_s_barrier()
; #define PG8_SCHED __builtin_amdgcn_sched_barrier(0)
; template <class Epi, class Sched, bool ALIGN_EPI = true, bool SP2 = true, bool GS = false>
; __device__ __forceinline__ void gemm_phase(PG8_LAS unsigned char* lds, const Gemm g, const Sched& S, const Epi& E, const float* gs_ss = nullptr) {
;     ...
;             PG8_LDB(B0, 0, 0); PG8_LDB(B1, 0, 1); PG8_SCHED; PG8_LDA(At, 0, 0); PG8_STAGE(PG8_SA(1, 1), a1 + hstep, voffA);
;             PG8_WAIT_V(8); PG8_WAIT_L(0); PG8_BAR; PG8_MMA(0, 0, At, B0); PG8_MMA(0, 1, At, B1); PG8_BAR; PG8_SCHED;
;             PG8_LDA(At, 0, 1); PG8_STAGE(PG8_SB(0, 0), b2, voffB); PG8_STAGE(PG8_SB(0, 1), b2 + hstep, voffB); PG8_STAGE(PG8_SA(0, 0), a2, voffA);
;             PG8_WAIT_V(8); PG8_WAIT_L(0); PG8_BAR; PG8_MMA(1, 0, At, B0); PG8_MMA(1, 1, At, B1); PG8_BAR; PG8_SCHED;
.LBB0_1344:
	s_add_u32 s2, s50, 0xfff80080
	s_addc_u32 s3, s51, -1
	s_add_i32 s60, 0, 0x10000
	s_cmp_eq_u32 s59, 28
	s_cselect_b32 s21, s43, s3
	s_cselect_b32 s20, s57, s2
	v_add_u32_e32 v140, s60, v143
	s_cselect_b32 s3, s41, s53
	s_cselect_b32 s2, s58, s52
	s_add_i32 s62, 0, 0x14000
	ds_read_b128 v[146:149], v140
	ds_read_b128 v[150:153], v140 offset:1024
	ds_read_b128 v[154:157], v140 offset:2048
	ds_read_b128 v[158:161], v140 offset:3072
	v_add_u32_e32 v140, s62, v143
	ds_read_b128 v[162:165], v140
	ds_read_b128 v[166:169], v140 offset:1024
	ds_read_b128 v[170:173], v140 offset:2048
	ds_read_b128 v[174:177], v140 offset:3072
	v_lshl_add_u64 v[140:141], s[50:51], 0, v[136:137]
	s_add_i32 m0, s30, 0xc000
	ds_read_b128 v[180:183], v145
	ds_read_b128 v[184:187], v145 offset:1024
	ds_read_b128 v[188:191], v145 offset:2048
	ds_read_b128 v[192:195], v145 offset:3072
	ds_read_b128 v[196:199], v145 offset:4096
	ds_read_b128 v[200:203], v145 offset:5120
	ds_read_b128 v[204:207], v145 offset:6144
	ds_read_b128 v[208:211], v145 offset:7168
	global_load_lds_dwordx4 v[140:141], off
	v_lshl_add_u64 v[140:141], s[50:51], 0, v[138:139]
	s_add_i32 m0, s30, 0xe000
	s_nop 0
	global_load_lds_dwordx4 v[140:141], off
	s_waitcnt vmcnt(8)
	s_waitcnt lgkmcnt(0)
	s_setprio 1
	s_barrier
	v_mfma_f32_16x16x32_bf16 v[126:129], v[146:149], v[180:183], v[126:129]
	v_mfma_f32_16x16x32_bf16 v[122:125], v[154:157], v[180:183], v[122:125]
	v_mfma_f32_16x16x32_bf16 v[110:113], v[146:149], v[188:191], v[110:113]
	v_mfma_f32_16x16x32_bf16 v[106:109], v[154:157], v[188:191], v[106:109]
	v_mfma_f32_16x16x32_bf16 v[94:97], v[146:149], v[196:199], v[94:97]
	v_mfma_f32_16x16x32_bf16 v[90:93], v[154:157], v[196:199], v[90:93]
	v_mfma_f32_16x16x32_bf16 v[78:81], v[146:149], v[204:207], v[78:81]
	v_mfma_f32_16x16x32_bf16 v[74:77], v[154:157], v[204:207], v[74:77]
	v_mfma_f32_16x16x32_bf16 v[126:129], v[150:153], v[184:187], v[126:129]
	v_mfma_f32_16x16x32_bf16 v[122:125], v[158:161], v[184:187], v[122:125]
	v_mfma_f32_16x16x32_bf16 v[110:113], v[150:153], v[192:195], v[110:113]
	v_mfma_f32_16x16x32_bf16 v[106:109], v[158:161], v[192:195], v[106:109]
	v_mfma_f32_16x16x32_bf16 v[94:97], v[150:153], v[200:203], v[94:97]
	v_mfma_f32_16x16x32_bf16 v[90:93], v[158:161], v[200:203], v[90:93]
	v_mfma_f32_16x16x32_bf16 v[78:81], v[150:153], v[208:211], v[78:81]
	v_mfma_f32_16x16x32_bf16 v[74:77], v[158:161], v[208:211], v[74:77]
	s_setprio 0
	s_setprio 1
	v_mfma_f32_16x16x32_bf16 v[118:121], v[162:165], v[180:183], v[118:121]
	v_mfma_f32_16x16x32_bf16 v[114:117], v[170:173], v[180:183], v[114:117]
	v_mfma_f32_16x16x32_bf16 v[102:105], v[162:165], v[188:191], v[102:105]
	v_mfma_f32_16x16x32_bf16 v[98:101], v[170:173], v[188:191], v[98:101]
	v_mfma_f32_16x16x32_bf16 v[86:89], v[162:165], v[196:199], v[86:89]
	v_mfma_f32_16x16x32_bf16 v[82:85], v[170:173], v[196:199], v[82:85]
	v_mfma_f32_16x16x32_bf16 v[70:73], v[162:165], v[204:207], v[70:73]
	v_mfma_f32_16x16x32_bf16 v[66:69], v[170:173], v[204:207], v[66:69]
	v_mfma_f32_16x16x32_bf16 v[118:121], v[166:169], v[184:187], v[118:121]
	v_mfma_f32_16x16x32_bf16 v[114:117], v[174:177], v[184:187], v[114:117]
	v_mfma_f32_16x16x32_bf16 v[102:105], v[166:169], v[192:195], v[102:105]
	v_mfma_f32_16x16x32_bf16 v[98:101], v[174:177], v[192:195], v[98:101]
	v_mfma_f32_16x16x32_bf16 v[86:89], v[166:169], v[200:203], v[86:89]
	v_mfma_f32_16x16x32_bf16 v[82:85], v[174:177], v[200:203], v[82:85]
	v_mfma_f32_16x16x32_bf16 v[70:73], v[166:169], v[208:211], v[70:73]
	v_mfma_f32_16x16x32_bf16 v[66:69], v[174:177], v[208:211], v[66:69]
	s_barrier
	s_setprio 0
	s_add_i32 s60, s60, s25
	v_lshl_add_u64 v[140:141], s[2:3], 0, v[0:1]
	s_mov_b32 m0, s60
	ds_read_b128 v[180:183], v145 offset:16384
	ds_read_b128 v[184:187], v145 offset:17408
	ds_read_b128 v[188:191], v145 offset:18432
	ds_read_b128 v[192:195], v145 offset:19456
	ds_read_b128 v[196:199], v145 offset:20480
	ds_read_b128 v[200:203], v145 offset:21504
	ds_read_b128 v[204:207], v145 offset:22528
	ds_read_b128 v[208:211], v145 offset:23552
	global_load_lds_dwordx4 v[140:141], off
	s_add_i32 m0, s60, 0x2000
	s_add_u32 s60, s2, 0x80000
	v_lshl_add_u64 v[212:213], s[2:3], 0, v[134:135]
	s_addc_u32 s61, s3, 0
	s_add_i32 s62, s62, s25
	global_load_lds_dwordx4 v[212:213], off
	v_lshl_add_u64 v[214:215], s[60:61], 0, v[0:1]
	s_mov_b32 m0, s62
	v_lshl_add_u64 v[216:217], s[20:21], 0, v[132:133]
	global_load_lds_dwordx4 v[214:215], off
	v_lshl_add_u64 v[214:215], s[60:61], 0, v[134:135]
	s_add_i32 m0, s62, 0x2000
	s_nop 0
	global_load_lds_dwordx4 v[214:215], off
	v_lshl_add_u64 v[214:215], s[20:21], 0, v[130:131]
	s_mov_b32 m0, s30
	s_nop 0
	global_load_lds_dwordx4 v[214:215], off
	s_mov_b32 m0, s36
	s_nop 0
	global_load_lds_dwordx4 v[216:217], off
	s_waitcnt vmcnt(8)
	s_waitcnt lgkmcnt(0)
	s_setprio 1
	s_barrier
; #define PG8_STAGE(bufoff, gbase, voff) do { _Pragma("unroll") for (int _i = 0; _i < 2; ++_i) \
;         __builtin_amdgcn_global_load_lds((const unsigned*)((const char*)(gbase) + (voff)[_i]), (PG8_LAS unsigned*)(lds + (bufoff) + ldsw + _i * 8192), 16, 0, 0); } while (0)
; #define PG8_LDA(dst, b, h) do { _Pragma("unroll") for (int m = 0; m < 4; ++m) _Pragma("unroll") for (int k = 0; k < 2; ++k) dst[m][k] = *(const PG8_LAS bf16x8*)(lds + PG8_SA(b, h) + aoff + m * 2048 + k * 1024); } while (0)
; #define PG8_LDB(dst, b, h) do { _Pragma("unroll") for (int n = 0; n < 2; ++n) _Pragma("unroll") for (int k = 0; k < 2; ++k) dst[n][k] = *(const PG8_LAS bf16x8*)(lds + PG8_SB(b, h) + boff + n * 2048 + k * 1024); } while (0)
; #define PG8_MMA(ai, bj, At, Bt) do { __builtin_amdgcn_s_setprio(1); _Pragma("unroll") for (int m = 0; m < 4; ++m) _Pragma("unroll") for (int n = 0; n < 2; ++n) _Pragma("unroll") for (int k = 0; k < 2; ++k) \
;         acc[ai][bj][m][n] = __builtin_amdgcn_mfma_f32_16x16x32_bf16(Bt[n][k], At[m][k], acc[ai][bj][m][n], 0, 0, 0); __builtin_amdgcn_s_setprio(0); } while (0)
; #define PG8_WAIT_V(n) asm volatile("s_waitcnt vmcnt(" #n ")" ::: "memory")
; #define PG8_WAIT_L(n) asm volatile("s_waitcnt lgkmcnt(" #n ")" ::: "memory")
; #define PG8_BAR __builtin_amdgcn_s_barrier()
; #define PG8_SCHED __builtin_amdgcn_sched_barrier(0)
; template <class Epi, class Sched, bool ALIGN_EPI = true, bool SP2 = true, bool GS = false>
; __device__ __forceinline__ void gemm_phase(PG8_LAS unsigned char* lds, const Gemm g, const Sched& S, const Epi& E, const float* gs_ss = nullptr) {
;     ...
;             PG8_WAIT_V(8); PG8_WAIT_L(0); PG8_BAR; PG8_MMA(1, 0, At, B0); PG8_MMA(1, 1, At, B1); PG8_BAR; PG8_SCHED;
;             PG8_LDB(B0, 1, 0); PG8_LDB(B1, 1, 1); PG8_SCHED; PG8_LDA(At, 1, 0); PG8_STAGE(PG8_SA(0, 1), a2 + hstep, voffA);
;             PG8_WAIT_V(8); PG8_WAIT_L(0); PG8_BAR; PG8_MMA(0, 0, At, B0); PG8_MMA(0, 1, At, B1); PG8_BAR; PG8_SCHED;
	v_mfma_f32_16x16x32_bf16 v[62:65], v[146:149], v[180:183], v[62:65]
	v_mfma_f32_16x16x32_bf16 v[58:61], v[154:157], v[180:183], v[58:61]
	v_mfma_f32_16x16x32_bf16 v[46:49], v[146:149], v[188:191], v[46:49]
	v_mfma_f32_16x16x32_bf16 v[42:45], v[154:157], v[188:191], v[42:45]
	v_mfma_f32_16x16x32_bf16 v[30:33], v[146:149], v[196:199], v[30:33]
	v_mfma_f32_16x16x32_bf16 v[26:29], v[154:157], v[196:199], v[26:29]
	v_mfma_f32_16x16x32_bf16 v[14:17], v[146:149], v[204:207], v[14:17]
	v_mfma_f32_16x16x32_bf16 v[10:13], v[154:157], v[204:207], v[10:13]
	v_mfma_f32_16x16x32_bf16 v[62:65], v[150:153], v[184:187], v[62:65]
	v_mfma_f32_16x16x32_bf16 v[58:61], v[158:161], v[184:187], v[58:61]
	v_mfma_f32_16x16x32_bf16 v[46:49], v[150:153], v[192:195], v[46:49]
	v_mfma_f32_16x16x32_bf16 v[42:45], v[158:161], v[192:195], v[42:45]
	v_mfma_f32_16x16x32_bf16 v[30:33], v[150:153], v[200:203], v[30:33]
	v_mfma_f32_16x16x32_bf16 v[26:29], v[158:161], v[200:203], v[26:29]
	v_mfma_f32_16x16x32_bf16 v[14:17], v[150:153], v[208:211], v[14:17]
	v_mfma_f32_16x16x32_bf16 v[10:13], v[158:161], v[208:211], v[10:13]
	s_setprio 0
	s_setprio 1
	v_mfma_f32_16x16x32_bf16 v[54:57], v[162:165], v[180:183], v[54:57]
	v_mfma_f32_16x16x32_bf16 v[50:53], v[170:173], v[180:183], v[50:53]
	v_mfma_f32_16x16x32_bf16 v[38:41], v[162:165], v[188:191], v[38:41]
	v_mfma_f32_16x16x32_bf16 v[34:37], v[170:173], v[188:191], v[34:37]
	v_mfma_f32_16x16x32_bf16 v[22:25], v[162:165], v[196:199], v[22:25]
	v_mfma_f32_16x16x32_bf16 v[18:21], v[170:173], v[196:199], v[18:21]
	v_mfma_f32_16x16x32_bf16 v[6:9], v[162:165], v[204:207], v[6:9]
	v_mfma_f32_16x16x32_bf16 v[2:5], v[170:173], v[204:207], v[2:5]
	v_mfma_f32_16x16x32_bf16 v[54:57], v[166:169], v[184:187], v[54:57]
	v_mfma_f32_16x16x32_bf16 v[50:53], v[174:177], v[184:187], v[50:53]
	v_mfma_f32_16x16x32_bf16 v[38:41], v[166:169], v[192:195], v[38:41]
	v_mfma_f32_16x16x32_bf16 v[34:37], v[174:177], v[192:195], v[34:37]
	v_mfma_f32_16x16x32_bf16 v[22:25], v[166:169], v[200:203], v[22:25]
	v_mfma_f32_16x16x32_bf16 v[18:21], v[174:177], v[200:203], v[18:21]
	v_mfma_f32_16x16x32_bf16 v[6:9], v[166:169], v[208:211], v[6:9]
	v_mfma_f32_16x16x32_bf16 v[2:5], v[174:177], v[208:211], v[2:5]
	s_barrier
	s_setprio 0
	s_add_i32 s60, 0, 0x18000
	s_add_i32 s61, 0, 0x1c000
	v_add_u32_e32 v158, s60, v143
	v_add_u32_e32 v174, s61, v143
	ds_read_b128 v[146:149], v158
	ds_read_b128 v[150:153], v158 offset:1024
	ds_read_b128 v[154:157], v158 offset:2048
	ds_read_b128 v[158:161], v158 offset:3072
	ds_read_b128 v[162:165], v174
	ds_read_b128 v[166:169], v174 offset:1024
	ds_read_b128 v[170:173], v174 offset:2048
	ds_read_b128 v[174:177], v174 offset:3072
	s_add_u32 s20, s20, 0x80000
	s_addc_u32 s21, s21, 0
	s_mov_b32 m0, s37
	v_lshl_add_u64 v[218:219], s[20:21], 0, v[130:131]
	ds_read_b128 v[180:183], v145 offset:32768
	ds_read_b128 v[184:187], v145 offset:33792
	ds_read_b128 v[188:191], v145 offset:34816
	ds_read_b128 v[192:195], v145 offset:35840
	ds_read_b128 v[196:199], v145 offset:36864
	ds_read_b128 v[200:203], v145 offset:37888
	ds_read_b128 v[204:207], v145 offset:38912
	ds_read_b128 v[208:211], v145 offset:39936
	global_load_lds_dwordx4 v[218:219], off
	v_lshl_add_u64 v[218:219], s[20:21], 0, v[132:133]
	s_mov_b32 m0, s49
	s_nop 0
	global_load_lds_dwordx4 v[218:219], off
	s_waitcnt vmcnt(8)
	s_waitcnt lgkmcnt(0)
	s_setprio 1
	s_barrier
	v_mfma_f32_16x16x32_bf16 v[126:129], v[146:149], v[180:183], v[126:129]
	v_mfma_f32_16x16x32_bf16 v[122:125], v[154:157], v[180:183], v[122:125]
	v_mfma_f32_16x16x32_bf16 v[110:113], v[146:149], v[188:191], v[110:113]
	v_mfma_f32_16x16x32_bf16 v[106:109], v[154:157], v[188:191], v[106:109]
	v_mfma_f32_16x16x32_bf16 v[94:97], v[146:149], v[196:199], v[94:97]
	v_mfma_f32_16x16x32_bf16 v[90:93], v[154:157], v[196:199], v[90:93]
	v_mfma_f32_16x16x32_bf16 v[78:81], v[146:149], v[204:207], v[78:81]
	v_mfma_f32_16x16x32_bf16 v[74:77], v[154:157], v[204:207], v[74:77]
	v_mfma_f32_16x16x32_bf16 v[126:129], v[150:153], v[184:187], v[126:129]
	v_mfma_f32_16x16x32_bf16 v[122:125], v[158:161], v[184:187], v[122:125]
	v_mfma_f32_16x16x32_bf16 v[110:113], v[150:153], v[192:195], v[110:113]
	v_mfma_f32_16x16x32_bf16 v[106:109], v[158:161], v[192:195], v[106:109]
	v_mfma_f32_16x16x32_bf16 v[94:97], v[150:153], v[200:203], v[94:97]
	v_mfma_f32_16x16x32_bf16 v[90:93], v[158:161], v[200:203], v[90:93]
	v_mfma_f32_16x16x32_bf16 v[78:81], v[150:153], v[208:211], v[78:81]
	v_mfma_f32_16x16x32_bf16 v[74:77], v[158:161], v[208:211], v[74:77]
	s_setprio 0
	s_setprio 1
	v_mfma_f32_16x16x32_bf16 v[118:121], v[162:165], v[180:183], v[118:121]
	v_mfma_f32_16x16x32_bf16 v[114:117], v[170:173], v[180:183], v[114:117]
	v_mfma_f32_16x16x32_bf16 v[102:105], v[162:165], v[188:191], v[102:105]
	v_mfma_f32_16x16x32_bf16 v[98:101], v[170:173], v[188:191], v[98:101]
	v_mfma_f32_16x16x32_bf16 v[86:89], v[162:165], v[196:199], v[86:89]
	v_mfma_f32_16x16x32_bf16 v[82:85], v[170:173], v[196:199], v[82:85]
	v_mfma_f32_16x16x32_bf16 v[70:73], v[162:165], v[204:207], v[70:73]
	v_mfma_f32_16x16x32_bf16 v[66:69], v[170:173], v[204:207], v[66:69]
	v_mfma_f32_16x16x32_bf16 v[118:121], v[166:169], v[184:187], v[118:121]
	v_mfma_f32_16x16x32_bf16 v[114:117], v[174:177], v[184:187], v[114:117]
	v_mfma_f32_16x16x32_bf16 v[102:105], v[166:169], v[192:195], v[102:105]
	v_mfma_f32_16x16x32_bf16 v[98:101], v[174:177], v[192:195], v[98:101]
	v_mfma_f32_16x16x32_bf16 v[86:89], v[166:169], v[200:203], v[86:89]
	v_mfma_f32_16x16x32_bf16 v[82:85], v[174:177], v[200:203], v[82:85]
	v_mfma_f32_16x16x32_bf16 v[70:73], v[166:169], v[208:211], v[70:73]
	v_mfma_f32_16x16x32_bf16 v[66:69], v[174:177], v[208:211], v[66:69]
	s_barrier
; #define PG8_LAS __attribute__((address_space(3)))
; #define PG8_STAGE(bufoff, gbase, voff) do { _Pragma("unroll") for (int _i = 0; _i < 2; ++_i) \
;         __builtin_amdgcn_global_load_lds((const unsigned*)((const char*)(gbase) + (voff)[_i]), (PG8_LAS unsigned*)(lds + (bufoff) + ldsw + _i * 8192), 16, 0, 0); } while (0)
; #define PG8_LDA(dst, b, h) do { _Pragma("unroll") for (int m = 0; m < 4; ++m) _Pragma("unroll") for (int k = 0; k < 2; ++k) dst[m][k] = *(const PG8_LAS bf16x8*)(lds + PG8_SA(b, h) + aoff + m * 2048 + k * 1024); } while (0)
; #define PG8_MMA(ai, bj, At, Bt) do { __builtin_amdgcn_s_setprio(1); _Pragma("unroll") for (int m = 0; m < 4; ++m) _Pragma("unroll") for (int n = 0; n < 2; ++n) _Pragma("unroll") for (int k = 0; k < 2; ++k) \
;         acc[ai][bj][m][n] = __builtin_amdgcn_mfma_f32_16x16x32_bf16(Bt[n][k], At[m][k], acc[ai][bj][m][n], 0, 0, 0); __builtin_amdgcn_s_setprio(0); } while (0)
; #define PG8_WAIT_V(n) asm volatile("s_waitcnt vmcnt(" #n ")" ::: "memory")
; #define PG8_WAIT_L(n) asm volatile("s_waitcnt lgkmcnt(" #n ")" ::: "memory")
; #define PG8_BAR __builtin_amdgcn_s_barrier()
; #define PG8_SCHED __builtin_amdgcn_sched_barrier(0)
; template <class Epi, class Sched, bool ALIGN_EPI = true, bool SP2 = true, bool GS = false>
; __device__ __forceinline__ void gemm_phase(PG8_LAS unsigned char* lds, const Gemm g, const Sched& S, const Epi& E, const float* gs_ss = nullptr) {
;     ...
;             PG8_LDA(At, 1, 1); PG8_STAGE(PG8_SB(1, 0), b3, voffB); PG8_STAGE(PG8_SB(1, 1), b3 + hstep, voffB); PG8_STAGE(PG8_SA(1, 0), a3, voffA);
;             PG8_WAIT_V(8); PG8_WAIT_L(0); PG8_BAR; PG8_MMA(1, 0, At, B0); PG8_MMA(1, 1, At, B1); PG8_BAR; PG8_SCHED;
;     ...
;         if constexpr (ALIGN_EPI) { if (wr == 0) PG8_BAR; }
;         if constexpr (GS) E.gs(acc, cur, wr, wc, fr, fq, (const PG8_LAS float*)(lds + STAGE_BYTES + gpar * 4096)); else E(acc, cur, wr, wc, fr, fq);
;         if (!has_next) break;
	s_setprio 0
	s_add_i32 s20, s60, s25
	v_lshl_add_u64 v[140:141], v[140:141], 0, s[26:27]
	s_mov_b32 m0, s20
	ds_read_b128 v[180:183], v145 offset:49152
	ds_read_b128 v[184:187], v145 offset:50176
	ds_read_b128 v[188:191], v145 offset:51200
	ds_read_b128 v[192:195], v145 offset:52224
	ds_read_b128 v[196:199], v145 offset:53248
	ds_read_b128 v[200:203], v145 offset:54272
	ds_read_b128 v[204:207], v145 offset:55296
	ds_read_b128 v[208:211], v145 offset:56320
	global_load_lds_dwordx4 v[140:141], off
	s_add_i32 m0, s20, 0x2000
	s_add_u32 s2, s2, 0x80080
	v_lshl_add_u64 v[140:141], v[212:213], 0, s[26:27]
	s_addc_u32 s3, s3, 0
	s_add_i32 s20, s61, s25
	global_load_lds_dwordx4 v[140:141], off
	v_lshl_add_u64 v[140:141], s[2:3], 0, v[0:1]
	s_mov_b32 m0, s20
	s_nop 0
	global_load_lds_dwordx4 v[140:141], off
	v_lshl_add_u64 v[140:141], s[2:3], 0, v[134:135]
	s_add_i32 m0, s20, 0x2000
	s_nop 0
	global_load_lds_dwordx4 v[140:141], off
	v_lshl_add_u64 v[140:141], v[214:215], 0, s[26:27]
	s_mov_b32 m0, s18
	s_nop 0
	global_load_lds_dwordx4 v[140:141], off
	v_lshl_add_u64 v[140:141], v[216:217], 0, s[26:27]
	s_mov_b32 m0, s54
	s_nop 0
	global_load_lds_dwordx4 v[140:141], off
	s_waitcnt vmcnt(8)
	s_waitcnt lgkmcnt(0)
	s_setprio 1
	s_barrier
	v_mfma_f32_16x16x32_bf16 v[62:65], v[146:149], v[180:183], v[62:65]
	v_mfma_f32_16x16x32_bf16 v[58:61], v[154:157], v[180:183], v[58:61]
	v_mfma_f32_16x16x32_bf16 v[46:49], v[146:149], v[188:191], v[46:49]
	v_mfma_f32_16x16x32_bf16 v[42:45], v[154:157], v[188:191], v[42:45]
	v_mfma_f32_16x16x32_bf16 v[30:33], v[146:149], v[196:199], v[30:33]
	v_mfma_f32_16x16x32_bf16 v[26:29], v[154:157], v[196:199], v[26:29]
	v_mfma_f32_16x16x32_bf16 v[14:17], v[146:149], v[204:207], v[14:17]
	v_mfma_f32_16x16x32_bf16 v[10:13], v[154:157], v[204:207], v[10:13]
	v_mfma_f32_16x16x32_bf16 v[62:65], v[150:153], v[184:187], v[62:65]
	v_mfma_f32_16x16x32_bf16 v[58:61], v[158:161], v[184:187], v[58:61]
	v_mfma_f32_16x16x32_bf16 v[46:49], v[150:153], v[192:195], v[46:49]
	v_mfma_f32_16x16x32_bf16 v[42:45], v[158:161], v[192:195], v[42:45]
	v_mfma_f32_16x16x32_bf16 v[30:33], v[150:153], v[200:203], v[30:33]
	v_mfma_f32_16x16x32_bf16 v[26:29], v[158:161], v[200:203], v[26:29]
	v_mfma_f32_16x16x32_bf16 v[14:17], v[150:153], v[208:211], v[14:17]
	v_mfma_f32_16x16x32_bf16 v[10:13], v[158:161], v[208:211], v[10:13]
	s_setprio 0
	s_setprio 1
	v_mfma_f32_16x16x32_bf16 v[54:57], v[162:165], v[180:183], v[54:57]
	v_mfma_f32_16x16x32_bf16 v[50:53], v[170:173], v[180:183], v[50:53]
	v_mfma_f32_16x16x32_bf16 v[38:41], v[162:165], v[188:191], v[38:41]
	v_mfma_f32_16x16x32_bf16 v[34:37], v[170:173], v[188:191], v[34:37]
	v_mfma_f32_16x16x32_bf16 v[22:25], v[162:165], v[196:199], v[22:25]
	v_mfma_f32_16x16x32_bf16 v[18:21], v[170:173], v[196:199], v[18:21]
	v_mfma_f32_16x16x32_bf16 v[6:9], v[162:165], v[204:207], v[6:9]
	v_mfma_f32_16x16x32_bf16 v[2:5], v[170:173], v[204:207], v[2:5]
	v_mfma_f32_16x16x32_bf16 v[54:57], v[166:169], v[184:187], v[54:57]
	v_mfma_f32_16x16x32_bf16 v[50:53], v[174:177], v[184:187], v[50:53]
	v_mfma_f32_16x16x32_bf16 v[38:41], v[166:169], v[192:195], v[38:41]
	v_mfma_f32_16x16x32_bf16 v[34:37], v[174:177], v[192:195], v[34:37]
	v_mfma_f32_16x16x32_bf16 v[22:25], v[166:169], v[200:203], v[22:25]
	v_mfma_f32_16x16x32_bf16 v[18:21], v[174:177], v[200:203], v[18:21]
	v_mfma_f32_16x16x32_bf16 v[6:9], v[166:169], v[208:211], v[6:9]
	v_mfma_f32_16x16x32_bf16 v[2:5], v[174:177], v[208:211], v[2:5]
	s_barrier
	s_setprio 0
	s_add_i32 s59, s59, 2
	s_add_u32 s50, s50, 0x100
	s_addc_u32 s51, s51, 0
	s_add_u32 s52, s52, 0x100
	s_addc_u32 s53, s53, 0
	s_cmp_gt_u32 s59, 29
	s_cbranch_scc0 .LBB0_1344
	s_and_b64 vcc, exec, s[34:35]
	s_cbranch_vccz .LBB0_1347
	s_barrier

; #define PG8_STAGE(bufoff, gbase, voff) do { _Pragma("unroll") for (int _i = 0; _i < 2; ++_i) \
;         __builtin_amdgcn_global_load_lds((const unsigned*)((const char*)(gbase) + (voff)[_i]), (PG8_LAS unsigned*)(lds + (bufoff) + ldsw + _i * 8192), 16, 0, 0); } while (0)
; #define PG8_LDA(dst, b, h) do { _Pragma("unroll") for (int m = 0; m < 4; ++m) _Pragma("unroll") for (int k = 0; k < 2; ++k) dst[m][k] = *(const PG8_LAS bf16x8*)(lds + PG8_SA(b, h) + aoff + m * 2048 + k * 1024); } while (0)
; #define PG8_LDB(dst, b, h) do { _Pragma("unroll") for (int n = 0; n < 2; ++n) _Pragma("unroll") for (int k = 0; k < 2; ++k) dst[n][k] = *(const PG8_LAS bf16x8*)(lds + PG8_SB(b, h) + boff + n * 2048 + k * 1024); } while (0)
; #define PG8_MMA(ai, bj, At, Bt) do { __builtin_amdgcn_s_setprio(1); _Pragma("unroll") for (int m = 0; m < 4; ++m) _Pragma("unroll") for (int n = 0; n < 2; ++n) _Pragma("unroll") for (int k = 0; k < 2; ++k) \
;         acc[ai][bj][m][n] = __builtin_amdgcn_mfma_f32_16x16x32_bf16(Bt[n][k], At[m][k], acc[ai][bj][m][n], 0, 0, 0); __builtin_amdgcn_s_setprio(0); } while (0)
; #define PG8_WAIT_V(n) asm volatile("s_waitcnt vmcnt(" #n ")" ::: "memory")
; #define PG8_WAIT_L(n) asm volatile("s_waitcnt lgkmcnt(" #n ")" ::: "memory")
; #define PG8_BAR __builtin_amdgcn_s_barrier()
; #define PG8_SCHED __builtin_amdgcn_sched_barrier(0)
; template <class Epi, class Sched, bool ALIGN_EPI = true, bool SP2 = true, bool GS = false>
; __device__ __forceinline__ void gemm_phase(PG8_LAS unsigned char* lds, const Gemm g, const Sched& S, const Epi& E, const float* gs_ss = nullptr) {
;     ...
;             PG8_LDB(B0, 0, 0); PG8_LDB(B1, 0, 1); PG8_SCHED; PG8_LDA(At, 0, 0); PG8_STAGE(PG8_SA(1, 1), a1 + hstep, voffA);
;             PG8_WAIT_V(8); PG8_WAIT_L(0); PG8_BAR; PG8_MMA(0, 0, At, B0); PG8_MMA(0, 1, At, B1); PG8_BAR; PG8_SCHED;
;             PG8_LDA(At, 0, 1); PG8_STAGE(PG8_SB(0, 0), b2, voffB); PG8_STAGE(PG8_SB(0, 1), b2 + hstep, voffB); PG8_STAGE(PG8_SA(0, 0), a2, voffA);
;             PG8_WAIT_V(8); PG8_WAIT_L(0); PG8_BAR; PG8_MMA(1, 0, At, B0); PG8_MMA(1, 1, At, B1); PG8_BAR; PG8_SCHED;
.LBB0_1422:
	s_add_u32 s2, s56, 0xffe00080
	s_addc_u32 s3, s57, -1
	s_add_i32 s65, 0, 0x10000
	s_cmpk_eq_i32 s64, 0x7c
	s_cselect_b32 s21, s18, s3
	s_cselect_b32 s20, s51, s2
	s_cselect_b32 s3, s49, s59
	s_cselect_b32 s2, s63, s58
	s_add_i32 s67, 0, 0x14000
	v_add_u32_e32 v142, s65, v236
	v_add_u32_e32 v170, s67, v236
	ds_read_b128 v[130:133], v142
	ds_read_b128 v[134:137], v142 offset:1024
	ds_read_b128 v[138:141], v142 offset:2048
	ds_read_b128 v[142:145], v142 offset:3072
	ds_read_b128 v[158:161], v170
	ds_read_b128 v[162:165], v170 offset:1024
	ds_read_b128 v[166:169], v170 offset:2048
	ds_read_b128 v[170:173], v170 offset:3072
	v_lshl_add_u64 v[180:181], s[56:57], 0, v[154:155]
	s_add_i32 m0, s9, 0xc000
	ds_read_b128 v[174:177], v238
	ds_read_b128 v[184:187], v238 offset:1024
	ds_read_b128 v[188:191], v238 offset:2048
	ds_read_b128 v[192:195], v238 offset:3072
	ds_read_b128 v[196:199], v238 offset:4096
	ds_read_b128 v[200:203], v238 offset:5120
	ds_read_b128 v[204:207], v238 offset:6144
	ds_read_b128 v[208:211], v238 offset:7168
	global_load_lds_dwordx4 v[180:181], off
	v_lshl_add_u64 v[180:181], s[56:57], 0, v[156:157]
	s_add_i32 m0, s9, 0xe000
	s_nop 0
	global_load_lds_dwordx4 v[180:181], off
	s_waitcnt vmcnt(8)
	s_waitcnt lgkmcnt(0)
	s_setprio 1
	s_barrier
	v_mfma_f32_16x16x32_bf16 v[126:129], v[130:133], v[174:177], v[126:129]
	v_mfma_f32_16x16x32_bf16 v[122:125], v[138:141], v[174:177], v[122:125]
	v_mfma_f32_16x16x32_bf16 v[110:113], v[130:133], v[188:191], v[110:113]
	v_mfma_f32_16x16x32_bf16 v[106:109], v[138:141], v[188:191], v[106:109]
	v_mfma_f32_16x16x32_bf16 v[94:97], v[130:133], v[196:199], v[94:97]
	v_mfma_f32_16x16x32_bf16 v[90:93], v[138:141], v[196:199], v[90:93]
	v_mfma_f32_16x16x32_bf16 v[78:81], v[130:133], v[204:207], v[78:81]
	v_mfma_f32_16x16x32_bf16 v[74:77], v[138:141], v[204:207], v[74:77]
	v_mfma_f32_16x16x32_bf16 v[126:129], v[134:137], v[184:187], v[126:129]
	v_mfma_f32_16x16x32_bf16 v[122:125], v[142:145], v[184:187], v[122:125]
	v_mfma_f32_16x16x32_bf16 v[110:113], v[134:137], v[192:195], v[110:113]
	v_mfma_f32_16x16x32_bf16 v[106:109], v[142:145], v[192:195], v[106:109]
	v_mfma_f32_16x16x32_bf16 v[94:97], v[134:137], v[200:203], v[94:97]
	v_mfma_f32_16x16x32_bf16 v[90:93], v[142:145], v[200:203], v[90:93]
	v_mfma_f32_16x16x32_bf16 v[78:81], v[134:137], v[208:211], v[78:81]
	v_mfma_f32_16x16x32_bf16 v[74:77], v[142:145], v[208:211], v[74:77]
	s_setprio 0
	s_setprio 1
	v_mfma_f32_16x16x32_bf16 v[118:121], v[158:161], v[174:177], v[118:121]
	v_mfma_f32_16x16x32_bf16 v[114:117], v[166:169], v[174:177], v[114:117]
	v_mfma_f32_16x16x32_bf16 v[102:105], v[158:161], v[188:191], v[102:105]
	v_mfma_f32_16x16x32_bf16 v[98:101], v[166:169], v[188:191], v[98:101]
	v_mfma_f32_16x16x32_bf16 v[86:89], v[158:161], v[196:199], v[86:89]
	v_mfma_f32_16x16x32_bf16 v[82:85], v[166:169], v[196:199], v[82:85]
	v_mfma_f32_16x16x32_bf16 v[70:73], v[158:161], v[204:207], v[70:73]
	v_mfma_f32_16x16x32_bf16 v[66:69], v[166:169], v[204:207], v[66:69]
	v_mfma_f32_16x16x32_bf16 v[118:121], v[162:165], v[184:187], v[118:121]
	v_mfma_f32_16x16x32_bf16 v[114:117], v[170:173], v[184:187], v[114:117]
	v_mfma_f32_16x16x32_bf16 v[102:105], v[162:165], v[192:195], v[102:105]
	v_mfma_f32_16x16x32_bf16 v[98:101], v[170:173], v[192:195], v[98:101]
	v_mfma_f32_16x16x32_bf16 v[86:89], v[162:165], v[200:203], v[86:89]
	v_mfma_f32_16x16x32_bf16 v[82:85], v[170:173], v[200:203], v[82:85]
	v_mfma_f32_16x16x32_bf16 v[70:73], v[162:165], v[208:211], v[70:73]
	v_mfma_f32_16x16x32_bf16 v[66:69], v[170:173], v[208:211], v[66:69]
	s_barrier
	s_setprio 0
	s_add_i32 s65, s65, s24
	v_lshl_add_u64 v[180:181], s[2:3], 0, v[0:1]
	s_mov_b32 m0, s65
	ds_read_b128 v[174:177], v238 offset:16384
	ds_read_b128 v[184:187], v238 offset:17408
	ds_read_b128 v[188:191], v238 offset:18432
	ds_read_b128 v[192:195], v238 offset:19456
	ds_read_b128 v[196:199], v238 offset:20480
	ds_read_b128 v[200:203], v238 offset:21504
	ds_read_b128 v[204:207], v238 offset:22528
	ds_read_b128 v[208:211], v238 offset:23552
	global_load_lds_dwordx4 v[180:181], off
	s_add_i32 m0, s65, 0x2000
	s_add_u32 s70, s2, 0x200000
	v_lshl_add_u64 v[212:213], s[2:3], 0, v[150:151]
	s_addc_u32 s71, s3, 0
	s_add_i32 s65, s67, s24
	global_load_lds_dwordx4 v[212:213], off
	v_lshl_add_u64 v[214:215], s[70:71], 0, v[0:1]
	s_mov_b32 m0, s65
	v_lshl_add_u64 v[216:217], s[20:21], 0, v[148:149]
	global_load_lds_dwordx4 v[214:215], off
	v_lshl_add_u64 v[214:215], s[70:71], 0, v[150:151]
	s_add_i32 m0, s65, 0x2000
	s_nop 0
	global_load_lds_dwordx4 v[214:215], off
	v_lshl_add_u64 v[214:215], s[20:21], 0, v[146:147]
	s_mov_b32 m0, s9
	s_nop 0
	global_load_lds_dwordx4 v[214:215], off
	s_mov_b32 m0, s13
	s_nop 0
	global_load_lds_dwordx4 v[216:217], off
	s_waitcnt vmcnt(8)
	s_waitcnt lgkmcnt(0)
	s_setprio 1
	s_barrier
; #define PG8_STAGE(bufoff, gbase, voff) do { _Pragma("unroll") for (int _i = 0; _i < 2; ++_i) \
;         __builtin_amdgcn_global_load_lds((const unsigned*)((const char*)(gbase) + (voff)[_i]), (PG8_LAS unsigned*)(lds + (bufoff) + ldsw + _i * 8192), 16, 0, 0); } while (0)
; #define PG8_LDA(dst, b, h) do { _Pragma("unroll") for (int m = 0; m < 4; ++m) _Pragma("unroll") for (int k = 0; k < 2; ++k) dst[m][k] = *(const PG8_LAS bf16x8*)(lds + PG8_SA(b, h) + aoff + m * 2048 + k * 1024); } while (0)
; #define PG8_LDB(dst, b, h) do { _Pragma("unroll") for (int n = 0; n < 2; ++n) _Pragma("unroll") for (int k = 0; k < 2; ++k) dst[n][k] = *(const PG8_LAS bf16x8*)(lds + PG8_SB(b, h) + boff + n * 2048 + k * 1024); } while (0)
; #define PG8_MMA(ai, bj, At, Bt) do { __builtin_amdgcn_s_setprio(1); _Pragma("unroll") for (int m = 0; m < 4; ++m) _Pragma("unroll") for (int n = 0; n < 2; ++n) _Pragma("unroll") for (int k = 0; k < 2; ++k) \
;         acc[ai][bj][m][n] = __builtin_amdgcn_mfma_f32_16x16x32_bf16(Bt[n][k], At[m][k], acc[ai][bj][m][n], 0, 0, 0); __builtin_amdgcn_s_setprio(0); } while (0)
; #define PG8_WAIT_V(n) asm volatile("s_waitcnt vmcnt(" #n ")" ::: "memory")
; #define PG8_WAIT_L(n) asm volatile("s_waitcnt lgkmcnt(" #n ")" ::: "memory")
; #define PG8_BAR __builtin_amdgcn_s_barrier()
; #define PG8_SCHED __builtin_amdgcn_sched_barrier(0)
; template <class Epi, class Sched, bool ALIGN_EPI = true, bool SP2 = true, bool GS = false>
; __device__ __forceinline__ void gemm_phase(PG8_LAS unsigned char* lds, const Gemm g, const Sched& S, const Epi& E, const float* gs_ss = nullptr) {
;     ...
;             PG8_WAIT_V(8); PG8_WAIT_L(0); PG8_BAR; PG8_MMA(1, 0, At, B0); PG8_MMA(1, 1, At, B1); PG8_BAR; PG8_SCHED;
;             PG8_LDB(B0, 1, 0); PG8_LDB(B1, 1, 1); PG8_SCHED; PG8_LDA(At, 1, 0); PG8_STAGE(PG8_SA(0, 1), a2 + hstep, voffA);
;             PG8_WAIT_V(8); PG8_WAIT_L(0); PG8_BAR; PG8_MMA(0, 0, At, B0); PG8_MMA(0, 1, At, B1); PG8_BAR; PG8_SCHED;
	v_mfma_f32_16x16x32_bf16 v[62:65], v[130:133], v[174:177], v[62:65]
	v_mfma_f32_16x16x32_bf16 v[58:61], v[138:141], v[174:177], v[58:61]
	v_mfma_f32_16x16x32_bf16 v[46:49], v[130:133], v[188:191], v[46:49]
	v_mfma_f32_16x16x32_bf16 v[42:45], v[138:141], v[188:191], v[42:45]
	v_mfma_f32_16x16x32_bf16 v[30:33], v[130:133], v[196:199], v[30:33]
	v_mfma_f32_16x16x32_bf16 v[26:29], v[138:141], v[196:199], v[26:29]
	v_mfma_f32_16x16x32_bf16 v[14:17], v[130:133], v[204:207], v[14:17]
	v_mfma_f32_16x16x32_bf16 v[10:13], v[138:141], v[204:207], v[10:13]
	v_mfma_f32_16x16x32_bf16 v[62:65], v[134:137], v[184:187], v[62:65]
	v_mfma_f32_16x16x32_bf16 v[58:61], v[142:145], v[184:187], v[58:61]
	v_mfma_f32_16x16x32_bf16 v[46:49], v[134:137], v[192:195], v[46:49]
	v_mfma_f32_16x16x32_bf16 v[42:45], v[142:145], v[192:195], v[42:45]
	v_mfma_f32_16x16x32_bf16 v[30:33], v[134:137], v[200:203], v[30:33]
	v_mfma_f32_16x16x32_bf16 v[26:29], v[142:145], v[200:203], v[26:29]
	v_mfma_f32_16x16x32_bf16 v[14:17], v[134:137], v[208:211], v[14:17]
	v_mfma_f32_16x16x32_bf16 v[10:13], v[142:145], v[208:211], v[10:13]
	s_setprio 0
	s_setprio 1
	v_mfma_f32_16x16x32_bf16 v[54:57], v[158:161], v[174:177], v[54:57]
	v_mfma_f32_16x16x32_bf16 v[50:53], v[166:169], v[174:177], v[50:53]
	v_mfma_f32_16x16x32_bf16 v[38:41], v[158:161], v[188:191], v[38:41]
	v_mfma_f32_16x16x32_bf16 v[34:37], v[166:169], v[188:191], v[34:37]
	v_mfma_f32_16x16x32_bf16 v[22:25], v[158:161], v[196:199], v[22:25]
	v_mfma_f32_16x16x32_bf16 v[18:21], v[166:169], v[196:199], v[18:21]
	v_mfma_f32_16x16x32_bf16 v[6:9], v[158:161], v[204:207], v[6:9]
	v_mfma_f32_16x16x32_bf16 v[2:5], v[166:169], v[204:207], v[2:5]
	v_mfma_f32_16x16x32_bf16 v[54:57], v[162:165], v[184:187], v[54:57]
	v_mfma_f32_16x16x32_bf16 v[50:53], v[170:173], v[184:187], v[50:53]
	v_mfma_f32_16x16x32_bf16 v[38:41], v[162:165], v[192:195], v[38:41]
	v_mfma_f32_16x16x32_bf16 v[34:37], v[170:173], v[192:195], v[34:37]
	v_mfma_f32_16x16x32_bf16 v[22:25], v[162:165], v[200:203], v[22:25]
	v_mfma_f32_16x16x32_bf16 v[18:21], v[170:173], v[200:203], v[18:21]
	v_mfma_f32_16x16x32_bf16 v[6:9], v[162:165], v[208:211], v[6:9]
	v_mfma_f32_16x16x32_bf16 v[2:5], v[170:173], v[208:211], v[2:5]
	s_barrier
	s_setprio 0
	s_add_i32 s65, 0, 0x18000
	s_add_i32 s67, 0, 0x1c000
	v_add_u32_e32 v142, s65, v236
	v_add_u32_e32 v170, s67, v236
	ds_read_b128 v[130:133], v142
	ds_read_b128 v[134:137], v142 offset:1024
	ds_read_b128 v[138:141], v142 offset:2048
	ds_read_b128 v[142:145], v142 offset:3072
	ds_read_b128 v[158:161], v170
	ds_read_b128 v[162:165], v170 offset:1024
	ds_read_b128 v[166:169], v170 offset:2048
	ds_read_b128 v[170:173], v170 offset:3072
	s_add_u32 s20, s20, 0x200000
	s_addc_u32 s21, s21, 0
	s_mov_b32 m0, s25
	v_lshl_add_u64 v[218:219], s[20:21], 0, v[146:147]
	ds_read_b128 v[174:177], v238 offset:32768
	ds_read_b128 v[184:187], v238 offset:33792
	ds_read_b128 v[188:191], v238 offset:34816
	ds_read_b128 v[192:195], v238 offset:35840
	ds_read_b128 v[196:199], v238 offset:36864
	ds_read_b128 v[200:203], v238 offset:37888
	ds_read_b128 v[204:207], v238 offset:38912
	ds_read_b128 v[208:211], v238 offset:39936
	global_load_lds_dwordx4 v[218:219], off
	v_lshl_add_u64 v[218:219], s[20:21], 0, v[148:149]
	s_mov_b32 m0, s30
	s_nop 0
	global_load_lds_dwordx4 v[218:219], off
	s_waitcnt vmcnt(8)
	s_waitcnt lgkmcnt(0)
	s_setprio 1
	s_barrier
	v_mfma_f32_16x16x32_bf16 v[126:129], v[130:133], v[174:177], v[126:129]
	v_mfma_f32_16x16x32_bf16 v[122:125], v[138:141], v[174:177], v[122:125]
	v_mfma_f32_16x16x32_bf16 v[110:113], v[130:133], v[188:191], v[110:113]
	v_mfma_f32_16x16x32_bf16 v[106:109], v[138:141], v[188:191], v[106:109]
	v_mfma_f32_16x16x32_bf16 v[94:97], v[130:133], v[196:199], v[94:97]
	v_mfma_f32_16x16x32_bf16 v[90:93], v[138:141], v[196:199], v[90:93]
	v_mfma_f32_16x16x32_bf16 v[78:81], v[130:133], v[204:207], v[78:81]
	v_mfma_f32_16x16x32_bf16 v[74:77], v[138:141], v[204:207], v[74:77]
	v_mfma_f32_16x16x32_bf16 v[126:129], v[134:137], v[184:187], v[126:129]
	v_mfma_f32_16x16x32_bf16 v[122:125], v[142:145], v[184:187], v[122:125]
	v_mfma_f32_16x16x32_bf16 v[110:113], v[134:137], v[192:195], v[110:113]
	v_mfma_f32_16x16x32_bf16 v[106:109], v[142:145], v[192:195], v[106:109]
	v_mfma_f32_16x16x32_bf16 v[94:97], v[134:137], v[200:203], v[94:97]
	v_mfma_f32_16x16x32_bf16 v[90:93], v[142:145], v[200:203], v[90:93]
	v_mfma_f32_16x16x32_bf16 v[78:81], v[134:137], v[208:211], v[78:81]
	v_mfma_f32_16x16x32_bf16 v[74:77], v[142:145], v[208:211], v[74:77]
	s_setprio 0
	s_setprio 1
	v_mfma_f32_16x16x32_bf16 v[118:121], v[158:161], v[174:177], v[118:121]
	v_mfma_f32_16x16x32_bf16 v[114:117], v[166:169], v[174:177], v[114:117]
	v_mfma_f32_16x16x32_bf16 v[102:105], v[158:161], v[188:191], v[102:105]
	v_mfma_f32_16x16x32_bf16 v[98:101], v[166:169], v[188:191], v[98:101]
	v_mfma_f32_16x16x32_bf16 v[86:89], v[158:161], v[196:199], v[86:89]
	v_mfma_f32_16x16x32_bf16 v[82:85], v[166:169], v[196:199], v[82:85]
	v_mfma_f32_16x16x32_bf16 v[70:73], v[158:161], v[204:207], v[70:73]
	v_mfma_f32_16x16x32_bf16 v[66:69], v[166:169], v[204:207], v[66:69]
	v_mfma_f32_16x16x32_bf16 v[118:121], v[162:165], v[184:187], v[118:121]
	v_mfma_f32_16x16x32_bf16 v[114:117], v[170:173], v[184:187], v[114:117]
	v_mfma_f32_16x16x32_bf16 v[102:105], v[162:165], v[192:195], v[102:105]
	v_mfma_f32_16x16x32_bf16 v[98:101], v[170:173], v[192:195], v[98:101]
	v_mfma_f32_16x16x32_bf16 v[86:89], v[162:165], v[200:203], v[86:89]
	v_mfma_f32_16x16x32_bf16 v[82:85], v[170:173], v[200:203], v[82:85]
	v_mfma_f32_16x16x32_bf16 v[70:73], v[162:165], v[208:211], v[70:73]
	v_mfma_f32_16x16x32_bf16 v[66:69], v[170:173], v[208:211], v[66:69]
	s_barrier
; #define PG8_LAS __attribute__((address_space(3)))
; #define PG8_STAGE(bufoff, gbase, voff) do { _Pragma("unroll") for (int _i = 0; _i < 2; ++_i) \
;         __builtin_amdgcn_global_load_lds((const unsigned*)((const char*)(gbase) + (voff)[_i]), (PG8_LAS unsigned*)(lds + (bufoff) + ldsw + _i * 8192), 16, 0, 0); } while (0)
; #define PG8_LDA(dst, b, h) do { _Pragma("unroll") for (int m = 0; m < 4; ++m) _Pragma("unroll") for (int k = 0; k < 2; ++k) dst[m][k] = *(const PG8_LAS bf16x8*)(lds + PG8_SA(b, h) + aoff + m * 2048 + k * 1024); } while (0)
; #define PG8_MMA(ai, bj, At, Bt) do { __builtin_amdgcn_s_setprio(1); _Pragma("unroll") for (int m = 0; m < 4; ++m) _Pragma("unroll") for (int n = 0; n < 2; ++n) _Pragma("unroll") for (int k = 0; k < 2; ++k) \
;         acc[ai][bj][m][n] = __builtin_amdgcn_mfma_f32_16x16x32_bf16(Bt[n][k], At[m][k], acc[ai][bj][m][n], 0, 0, 0); __builtin_amdgcn_s_setprio(0); } while (0)
; #define PG8_WAIT_V(n) asm volatile("s_waitcnt vmcnt(" #n ")" ::: "memory")
; #define PG8_WAIT_L(n) asm volatile("s_waitcnt lgkmcnt(" #n ")" ::: "memory")
; #define PG8_BAR __builtin_amdgcn_s_barrier()
; #define PG8_SCHED __builtin_amdgcn_sched_barrier(0)
; template <class Epi, class Sched, bool ALIGN_EPI = true, bool SP2 = true, bool GS = false>
; __device__ __forceinline__ void gemm_phase(PG8_LAS unsigned char* lds, const Gemm g, const Sched& S, const Epi& E, const float* gs_ss = nullptr) {
;     ...
;             PG8_LDA(At, 1, 1); PG8_STAGE(PG8_SB(1, 0), b3, voffB); PG8_STAGE(PG8_SB(1, 1), b3 + hstep, voffB); PG8_STAGE(PG8_SA(1, 0), a3, voffA);
;             PG8_WAIT_V(8); PG8_WAIT_L(0); PG8_BAR; PG8_MMA(1, 0, At, B0); PG8_MMA(1, 1, At, B1); PG8_BAR; PG8_SCHED;
;     ...
;         if constexpr (ALIGN_EPI) { if (wr == 0) PG8_BAR; }
;         if constexpr (GS) E.gs(acc, cur, wr, wc, fr, fq, (const PG8_LAS float*)(lds + STAGE_BYTES + gpar * 4096)); else E(acc, cur, wr, wc, fr, fq);
;         if (!has_next) break;
	s_setprio 0
	s_add_i32 s20, s65, s24
	v_lshl_add_u64 v[180:181], v[180:181], 0, s[26:27]
	s_mov_b32 m0, s20
	ds_read_b128 v[174:177], v238 offset:49152
	ds_read_b128 v[184:187], v238 offset:50176
	ds_read_b128 v[188:191], v238 offset:51200
	ds_read_b128 v[192:195], v238 offset:52224
	ds_read_b128 v[196:199], v238 offset:53248
	ds_read_b128 v[200:203], v238 offset:54272
	ds_read_b128 v[204:207], v238 offset:55296
	ds_read_b128 v[208:211], v238 offset:56320
	global_load_lds_dwordx4 v[180:181], off
	s_add_i32 m0, s20, 0x2000
	s_add_u32 s2, s2, 0x200080
	v_lshl_add_u64 v[180:181], v[212:213], 0, s[26:27]
	s_addc_u32 s3, s3, 0
	s_add_i32 s20, s67, s24
	global_load_lds_dwordx4 v[180:181], off
	v_lshl_add_u64 v[180:181], s[2:3], 0, v[0:1]
	s_mov_b32 m0, s20
	s_nop 0
	global_load_lds_dwordx4 v[180:181], off
	v_lshl_add_u64 v[180:181], s[2:3], 0, v[150:151]
	s_add_i32 m0, s20, 0x2000
	s_nop 0
	global_load_lds_dwordx4 v[180:181], off
	v_lshl_add_u64 v[180:181], v[214:215], 0, s[26:27]
	s_mov_b32 m0, s37
	s_nop 0
	global_load_lds_dwordx4 v[180:181], off
	v_lshl_add_u64 v[180:181], v[216:217], 0, s[26:27]
	s_mov_b32 m0, s60
	s_nop 0
	global_load_lds_dwordx4 v[180:181], off
	s_waitcnt vmcnt(8)
	s_waitcnt lgkmcnt(0)
	s_setprio 1
	s_barrier
	v_mfma_f32_16x16x32_bf16 v[62:65], v[130:133], v[174:177], v[62:65]
	v_mfma_f32_16x16x32_bf16 v[58:61], v[138:141], v[174:177], v[58:61]
	v_mfma_f32_16x16x32_bf16 v[46:49], v[130:133], v[188:191], v[46:49]
	v_mfma_f32_16x16x32_bf16 v[42:45], v[138:141], v[188:191], v[42:45]
	v_mfma_f32_16x16x32_bf16 v[30:33], v[130:133], v[196:199], v[30:33]
	v_mfma_f32_16x16x32_bf16 v[26:29], v[138:141], v[196:199], v[26:29]
	v_mfma_f32_16x16x32_bf16 v[14:17], v[130:133], v[204:207], v[14:17]
	v_mfma_f32_16x16x32_bf16 v[10:13], v[138:141], v[204:207], v[10:13]
	v_mfma_f32_16x16x32_bf16 v[62:65], v[134:137], v[184:187], v[62:65]
	v_mfma_f32_16x16x32_bf16 v[58:61], v[142:145], v[184:187], v[58:61]
	v_mfma_f32_16x16x32_bf16 v[46:49], v[134:137], v[192:195], v[46:49]
	v_mfma_f32_16x16x32_bf16 v[42:45], v[142:145], v[192:195], v[42:45]
	v_mfma_f32_16x16x32_bf16 v[30:33], v[134:137], v[200:203], v[30:33]
	v_mfma_f32_16x16x32_bf16 v[26:29], v[142:145], v[200:203], v[26:29]
	v_mfma_f32_16x16x32_bf16 v[14:17], v[134:137], v[208:211], v[14:17]
	v_mfma_f32_16x16x32_bf16 v[10:13], v[142:145], v[208:211], v[10:13]
	s_setprio 0
	s_setprio 1
	v_mfma_f32_16x16x32_bf16 v[54:57], v[158:161], v[174:177], v[54:57]
	v_mfma_f32_16x16x32_bf16 v[50:53], v[166:169], v[174:177], v[50:53]
	v_mfma_f32_16x16x32_bf16 v[38:41], v[158:161], v[188:191], v[38:41]
	v_mfma_f32_16x16x32_bf16 v[34:37], v[166:169], v[188:191], v[34:37]
	v_mfma_f32_16x16x32_bf16 v[22:25], v[158:161], v[196:199], v[22:25]
	v_mfma_f32_16x16x32_bf16 v[18:21], v[166:169], v[196:199], v[18:21]
	v_mfma_f32_16x16x32_bf16 v[6:9], v[158:161], v[204:207], v[6:9]
	v_mfma_f32_16x16x32_bf16 v[2:5], v[166:169], v[204:207], v[2:5]
	v_mfma_f32_16x16x32_bf16 v[54:57], v[162:165], v[184:187], v[54:57]
	v_mfma_f32_16x16x32_bf16 v[50:53], v[170:173], v[184:187], v[50:53]
	v_mfma_f32_16x16x32_bf16 v[38:41], v[162:165], v[192:195], v[38:41]
	v_mfma_f32_16x16x32_bf16 v[34:37], v[170:173], v[192:195], v[34:37]
	v_mfma_f32_16x16x32_bf16 v[22:25], v[162:165], v[200:203], v[22:25]
	v_mfma_f32_16x16x32_bf16 v[18:21], v[170:173], v[200:203], v[18:21]
	v_mfma_f32_16x16x32_bf16 v[6:9], v[162:165], v[208:211], v[6:9]
	v_mfma_f32_16x16x32_bf16 v[2:5], v[170:173], v[208:211], v[2:5]
	s_barrier
	s_setprio 0
	s_add_i32 s64, s64, 2
	s_add_u32 s56, s56, 0x100
	s_addc_u32 s57, s57, 0
	s_add_u32 s58, s58, 0x100
	s_addc_u32 s59, s59, 0
	s_cmpk_gt_u32 s64, 0x7d
	s_cbranch_scc0 .LBB0_1422
	s_and_b64 vcc, exec, s[46:47]
	s_cbranch_vccz .LBB0_1425
	s_barrier
